# P0 rmsnorm wave sum: the six butterfly steps use DPP / v_permlane swaps instead of six LDS round trips; leftover lane-index arithmetic removed
# speedup vs baseline: 1.0003x; 1.0003x over previous
.LBB0_218:
	s_add_i32 s3, s0, s33
	s_cmpk_lt_i32 s3, 0x4000
	s_cselect_b32 s4, s3, s0
	s_ashr_i32 s1, s0, 31
	s_lshl_b64 s[6:7], s[0:1], 12
	s_ashr_i32 s5, s4, 31
	v_lshl_add_u64 v[20:21], v[8:9], 0, s[6:7]
	global_load_dwordx4 v[4:7], v[10:11], off
	s_lshl_b64 s[6:7], s[4:5], 12
	global_load_dwordx4 v[32:35], v[20:21], off nt
	global_load_dwordx4 v[36:39], v[20:21], off offset:1024 nt
	global_load_dwordx4 v[0:3], v[20:21], off offset:3072 nt
	global_load_dwordx4 v[40:43], v[20:21], off offset:2048 nt
	v_lshl_add_u64 v[60:61], v[8:9], 0, s[6:7]
	global_load_dwordx4 v[44:47], v[60:61], off nt
	global_load_dwordx4 v[48:51], v[60:61], off offset:1024 nt
	global_load_dwordx4 v[52:55], v[60:61], off offset:3072 nt
	global_load_dwordx4 v[56:59], v[60:61], off offset:2048 nt
	s_lshl_b64 s[18:19], s[0:1], 11
	v_lshl_add_u64 v[16:17], v[12:13], 0, s[18:19]
	s_lshl_b64 s[0:1], s[4:5], 11
	v_lshl_add_u64 v[20:21], v[12:13], 0, s[0:1]
	v_lshl_add_u64 v[18:19], v[14:15], 0, s[18:19]
	v_lshl_add_u64 v[22:23], v[14:15], 0, s[0:1]
	s_add_i32 s0, s3, s33
	s_cmpk_lt_i32 s0, 0x4000
	s_waitcnt vmcnt(7)
	v_pk_mul_f32 v[60:61], v[34:35], v[34:35]
	v_pk_mul_f32 v[62:63], v[32:33], v[32:33]
	s_waitcnt vmcnt(6)
	v_pk_mul_f32 v[64:65], v[38:39], v[38:39]
	v_pk_mul_f32 v[66:67], v[36:37], v[36:37]
	s_waitcnt vmcnt(4)
	v_mul_f32_e32 v68, v41, v41
	v_mul_f32_e32 v70, v43, v43
	v_pk_mov_b32 v[72:73], v[62:63], v[60:61] op_sel:[1,0]
	v_mov_b32_e32 v63, v61
	s_waitcnt vmcnt(3)
	v_pk_mul_f32 v[60:61], v[46:47], v[46:47]
	v_pk_mul_f32 v[74:75], v[44:45], v[44:45]
	v_pk_mov_b32 v[76:77], v[66:67], v[64:65] op_sel:[1,0]
	v_mov_b32_e32 v67, v65
	s_waitcnt vmcnt(2)
	v_pk_mul_f32 v[64:65], v[50:51], v[50:51]
	v_pk_mul_f32 v[78:79], v[48:49], v[48:49]
	v_mul_f32_e32 v31, v2, v2
	v_mul_f32_e32 v81, v3, v3
	v_pk_fma_f32 v[68:69], v[40:41], v[40:41], v[68:69] op_sel_hi:[1,1,0]
	v_pk_fma_f32 v[70:71], v[42:43], v[42:43], v[70:71] op_sel_hi:[1,1,0]
	v_pk_add_f32 v[62:63], v[72:73], v[62:63]
	v_pk_mov_b32 v[72:73], v[74:75], v[60:61] op_sel:[1,0]
	v_mov_b32_e32 v75, v61
	v_pk_add_f32 v[60:61], v[76:77], v[66:67]
	v_pk_mov_b32 v[66:67], v[78:79], v[64:65] op_sel:[1,0]
	v_mov_b32_e32 v79, v65
	v_mul_f32_e32 v83, v0, v0
	v_mul_f32_e32 v84, v1, v1
	s_waitcnt vmcnt(0)
	v_mul_f32_e32 v80, v57, v57
	v_mul_f32_e32 v82, v59, v59
	v_mov_b32_e32 v69, v31
	v_mov_b32_e32 v71, v81
	v_pk_add_f32 v[72:73], v[72:73], v[74:75]
	v_pk_add_f32 v[66:67], v[66:67], v[78:79]
	v_pk_add_f32 v[62:63], v[62:63], v[62:63] op_sel:[0,1] op_sel_hi:[1,0]
	v_pk_add_f32 v[60:61], v[60:61], v[60:61] op_sel:[0,1] op_sel_hi:[1,0]
	v_mul_f32_e32 v85, v54, v54
	v_mul_f32_e32 v86, v55, v55
	v_mul_f32_e32 v87, v52, v52
	v_mul_f32_e32 v88, v53, v53
	v_pk_fma_f32 v[64:65], v[56:57], v[56:57], v[80:81] op_sel_hi:[1,1,0]
	v_pk_fma_f32 v[76:77], v[58:59], v[58:59], v[82:83] op_sel_hi:[1,1,0]
	v_pk_add_f32 v[68:69], v[68:69], v[70:71]
	v_mov_b32_e32 v63, v83
	v_mov_b32_e32 v61, v84
	v_pk_add_f32 v[70:71], v[72:73], v[72:73] op_sel:[0,1] op_sel_hi:[1,0]
	v_pk_add_f32 v[66:67], v[66:67], v[66:67] op_sel:[0,1] op_sel_hi:[1,0]
	v_mov_b32_e32 v65, v85
	v_mov_b32_e32 v77, v86
	v_pk_add_f32 v[60:61], v[62:63], v[60:61]
	v_mov_b32_e32 v71, v87
	v_mov_b32_e32 v67, v88
	v_pk_add_f32 v[64:65], v[64:65], v[76:77]
	v_pk_add_f32 v[60:61], v[60:61], v[68:69]
	v_pk_add_f32 v[62:63], v[70:71], v[66:67]
	v_add_f32_e32 v31, v60, v61
	v_pk_add_f32 v[60:61], v[62:63], v[64:65]
	s_nop 1
	v_mov_b32_dpp v62, v31 quad_perm:[1,0,3,2] row_mask:0xf bank_mask:0xf
	v_add_f32_e32 v60, v60, v61
	s_nop 1
	v_mov_b32_dpp v61, v60 quad_perm:[1,0,3,2] row_mask:0xf bank_mask:0xf
	s_waitcnt lgkmcnt(1)
	v_add_f32_e32 v31, v31, v62
	s_nop 1
	v_mov_b32_dpp v62, v31 quad_perm:[2,3,0,1] row_mask:0xf bank_mask:0xf
	s_waitcnt lgkmcnt(1)
	v_add_f32_e32 v60, v60, v61
	s_nop 1
	v_mov_b32_dpp v61, v60 quad_perm:[2,3,0,1] row_mask:0xf bank_mask:0xf
	s_waitcnt lgkmcnt(1)
	v_add_f32_e32 v31, v31, v62
	s_nop 1
	v_mov_b32_dpp v62, v31 row_half_mirror row_mask:0xf bank_mask:0xf
	s_waitcnt lgkmcnt(1)
	v_add_f32_e32 v60, v60, v61
	s_nop 1
	v_mov_b32_dpp v61, v60 row_half_mirror row_mask:0xf bank_mask:0xf
	s_waitcnt lgkmcnt(1)
	v_add_f32_e32 v31, v31, v62
	s_nop 1
	v_mov_b32_dpp v62, v31 row_mirror row_mask:0xf bank_mask:0xf
	s_waitcnt lgkmcnt(1)
	v_add_f32_e32 v60, v60, v61
	s_nop 1
	v_mov_b32_dpp v61, v60 row_mirror row_mask:0xf bank_mask:0xf
	s_waitcnt lgkmcnt(1)
	v_add_f32_e32 v31, v31, v62
	v_mov_b32_e32 v62, v31
	s_nop 1
	v_permlane16_swap_b32_e32 v31, v62
	s_nop 1
	s_waitcnt lgkmcnt(1)
	v_add_f32_e32 v60, v60, v61
	v_mov_b32_e32 v61, v60
	s_nop 1
	v_permlane16_swap_b32_e32 v60, v61
	s_nop 1
	s_waitcnt lgkmcnt(1)
	v_add_f32_e32 v31, v31, v62
	v_mov_b32_e32 v62, v31
	s_nop 1
	v_permlane32_swap_b32_e32 v31, v62
	s_nop 1
	s_waitcnt lgkmcnt(1)
	v_add_f32_e32 v60, v60, v61
	v_mov_b32_e32 v61, v60
	s_nop 1
	v_permlane32_swap_b32_e32 v60, v61
	s_nop 1
	s_waitcnt lgkmcnt(1)
	v_add_f32_e32 v31, v31, v62
	v_fmamk_f32 v31, v31, 0x3a800000, v30
	s_waitcnt lgkmcnt(0)
	v_add_f32_e32 v61, v60, v61
	v_rsq_f32_e32 v60, v31
	v_fmamk_f32 v31, v61, 0x3a800000, v30
	v_rsq_f32_e32 v62, v31
	v_pk_mul_f32 v[64:65], v[32:33], v[60:61] op_sel_hi:[1,0]
	v_pk_mul_f32 v[66:67], v[34:35], v[60:61] op_sel_hi:[1,0]
	v_pk_mul_f32 v[68:69], v[44:45], v[62:63] op_sel_hi:[1,0]
	v_pk_mul_f32 v[64:65], v[4:5], v[64:65]
	v_pk_mul_f32 v[70:71], v[46:47], v[62:63] op_sel_hi:[1,0]
	v_pk_mul_f32 v[4:5], v[4:5], v[68:69]
	v_pk_mul_f32 v[66:67], v[6:7], v[66:67]
	v_pk_mul_f32 v[6:7], v[6:7], v[70:71]
	v_cvt_pk_bf16_f32 v64, v64, v65
	v_cvt_pk_bf16_f32 v65, v66, v67
	global_store_dwordx2 v[16:17], v[64:65], off
	v_cvt_pk_bf16_f32 v4, v4, v5
	v_cvt_pk_bf16_f32 v5, v6, v7
	global_store_dwordx2 v[20:21], v[4:5], off
	v_cvt_pk_bf16_f32 v4, v32, v33
	v_cvt_pk_bf16_f32 v5, v34, v35
	global_store_dwordx2 v[18:19], v[4:5], off
	v_cvt_pk_bf16_f32 v4, v44, v45
	v_cvt_pk_bf16_f32 v5, v46, v47
	global_store_dwordx2 v[22:23], v[4:5], off
	global_load_dwordx4 v[4:7], v[10:11], off offset:1024
	v_pk_mul_f32 v[32:33], v[36:37], v[60:61] op_sel_hi:[1,0]
	v_pk_mul_f32 v[44:45], v[48:49], v[62:63] op_sel_hi:[1,0]
	v_pk_mul_f32 v[34:35], v[38:39], v[60:61] op_sel_hi:[1,0]
	v_pk_mul_f32 v[46:47], v[50:51], v[62:63] op_sel_hi:[1,0]
	s_waitcnt vmcnt(0)
	v_pk_mul_f32 v[32:33], v[32:33], v[4:5]
	v_pk_mul_f32 v[4:5], v[44:45], v[4:5]
	v_pk_mul_f32 v[34:35], v[34:35], v[6:7]
	v_pk_mul_f32 v[6:7], v[46:47], v[6:7]
	v_cvt_pk_bf16_f32 v32, v32, v33
	v_cvt_pk_bf16_f32 v33, v34, v35
	global_store_dwordx2 v[16:17], v[32:33], off offset:512
	v_cvt_pk_bf16_f32 v4, v4, v5
	v_cvt_pk_bf16_f32 v5, v6, v7
	global_store_dwordx2 v[20:21], v[4:5], off offset:512
	v_cvt_pk_bf16_f32 v4, v36, v37
	v_cvt_pk_bf16_f32 v5, v38, v39
	global_store_dwordx2 v[18:19], v[4:5], off offset:512
	v_cvt_pk_bf16_f32 v4, v48, v49
	v_cvt_pk_bf16_f32 v5, v50, v51
	global_store_dwordx2 v[22:23], v[4:5], off offset:512
	global_load_dwordx4 v[4:7], v[10:11], off offset:2048
	v_pk_mul_f32 v[32:33], v[40:41], v[60:61] op_sel_hi:[1,0]
	v_pk_mul_f32 v[36:37], v[56:57], v[62:63] op_sel_hi:[1,0]
	v_pk_mul_f32 v[34:35], v[42:43], v[60:61] op_sel_hi:[1,0]
	v_pk_mul_f32 v[38:39], v[58:59], v[62:63] op_sel_hi:[1,0]
	s_waitcnt vmcnt(0)
	v_pk_mul_f32 v[32:33], v[32:33], v[4:5]
	v_pk_mul_f32 v[4:5], v[36:37], v[4:5]
	v_pk_mul_f32 v[34:35], v[34:35], v[6:7]
	v_pk_mul_f32 v[6:7], v[38:39], v[6:7]
	v_cvt_pk_bf16_f32 v32, v32, v33
	v_cvt_pk_bf16_f32 v33, v34, v35
	global_store_dwordx2 v[16:17], v[32:33], off offset:1024
	v_cvt_pk_bf16_f32 v4, v4, v5
	v_cvt_pk_bf16_f32 v5, v6, v7
	global_store_dwordx2 v[20:21], v[4:5], off offset:1024
	v_cvt_pk_bf16_f32 v4, v40, v41
	v_cvt_pk_bf16_f32 v5, v42, v43
	global_store_dwordx2 v[18:19], v[4:5], off offset:1024
	v_cvt_pk_bf16_f32 v4, v56, v57
	v_cvt_pk_bf16_f32 v5, v58, v59
	global_store_dwordx2 v[22:23], v[4:5], off offset:1024
	global_load_dwordx4 v[4:7], v[10:11], off offset:3072
	v_pk_mul_f32 v[32:33], v[0:1], v[60:61] op_sel_hi:[1,0]
	v_pk_mul_f32 v[36:37], v[52:53], v[62:63] op_sel_hi:[1,0]
	v_pk_mul_f32 v[34:35], v[2:3], v[60:61] op_sel_hi:[1,0]
	v_pk_mul_f32 v[38:39], v[54:55], v[62:63] op_sel_hi:[1,0]
	s_waitcnt vmcnt(0)
	v_pk_mul_f32 v[32:33], v[32:33], v[4:5]
	v_pk_mul_f32 v[4:5], v[36:37], v[4:5]
	v_pk_mul_f32 v[34:35], v[34:35], v[6:7]
	v_pk_mul_f32 v[6:7], v[38:39], v[6:7]
	v_cvt_pk_bf16_f32 v32, v32, v33
	v_cvt_pk_bf16_f32 v33, v34, v35
	global_store_dwordx2 v[16:17], v[32:33], off offset:1536
	v_cvt_pk_bf16_f32 v4, v4, v5
	v_cvt_pk_bf16_f32 v5, v6, v7
	global_store_dwordx2 v[20:21], v[4:5], off offset:1536
	v_cvt_pk_bf16_f32 v0, v0, v1
	v_cvt_pk_bf16_f32 v1, v2, v3
	global_store_dwordx2 v[18:19], v[0:1], off offset:1536
	v_cvt_pk_bf16_f32 v0, v52, v53
	v_cvt_pk_bf16_f32 v1, v54, v55
	global_store_dwordx2 v[22:23], v[0:1], off offset:1536
	s_cbranch_scc1 .LBB0_218

.LBB0_426:
	v_lshl_add_u32 v144, s89, 8, v182
	v_ashrrev_i32_e32 v145, 31, v144
	v_lshl_or_b32 v146, s90, 8, v184
	v_pk_mul_f32 v[148:149], v[112:113], 0.5 op_sel_hi:[1,0]
	v_lshlrev_b64 v[112:113], 11, v[144:145]
	v_ashrrev_i32_e32 v147, 31, v146
	v_lshl_add_u64 v[112:113], s[22:23], 0, v[112:113]
	v_cndmask_b32_e64 v154, 0, 1, s[68:69]
	v_pk_mul_f32 v[114:115], v[114:115], 0.5 op_sel_hi:[1,0]
	v_pk_mul_f32 v[118:119], v[118:119], 0.5 op_sel_hi:[1,0]
	v_pk_mul_f32 v[116:117], v[116:117], 0.5 op_sel_hi:[1,0]
	v_cvt_pk_bf16_f32 v150, v148, v149
	v_cvt_pk_bf16_f32 v151, v114, v115
	v_lshl_add_u64 v[112:113], v[146:147], 1, v[112:113]
	v_cvt_pk_bf16_f32 v152, v116, v117
	v_cvt_pk_bf16_f32 v153, v118, v119
	v_pk_mul_f32 v[122:123], v[122:123], 0.5 op_sel_hi:[1,0]
	v_pk_mul_f32 v[120:121], v[120:121], 0.5 op_sel_hi:[1,0]
	v_pk_mul_f32 v[126:127], v[126:127], 0.5 op_sel_hi:[1,0]
	v_pk_mul_f32 v[124:125], v[124:125], 0.5 op_sel_hi:[1,0]
	v_cmp_ne_u32_e64 s[8:9], 1, v154
	s_andn2_b64 vcc, exec, s[68:69]
	global_store_dwordx4 v[112:113], v[150:153], off
	s_nop 1
	v_cvt_pk_bf16_f32 v150, v120, v121
	v_cvt_pk_bf16_f32 v151, v122, v123
	v_cvt_pk_bf16_f32 v152, v124, v125
	v_cvt_pk_bf16_f32 v153, v126, v127
	global_store_dwordx4 v[112:113], v[150:153], off offset:256
	s_cbranch_vccnz .LBB0_430
	v_mul_f32_e32 v117, v117, v117
	v_fmac_f32_e32 v117, v116, v116
	v_mul_f32_e32 v116, v149, v149
	v_mul_f32_e32 v115, v115, v115
	v_fmac_f32_e32 v116, v148, v148
	v_fmac_f32_e32 v115, v114, v114
	v_mul_f32_e32 v119, v119, v119
	v_add_f32_e32 v114, v116, v115
	v_fmac_f32_e32 v119, v118, v118
	v_add_f32_e32 v114, v114, v117
	v_mul_f32_e32 v117, v121, v121
	v_mul_f32_e32 v118, v123, v123
	v_mul_f32_e32 v116, v125, v125
	v_fmac_f32_e32 v117, v120, v120
	v_fmac_f32_e32 v118, v122, v122
	v_mul_f32_e32 v115, v127, v127
	v_fmac_f32_e32 v116, v124, v124
	v_add_f32_e32 v117, v117, v118
	v_fmac_f32_e32 v115, v126, v126
	v_add_f32_e32 v116, v117, v116
	v_add_f32_e32 v114, v119, v114
	v_add_f32_e32 v115, v115, v116
	v_and_b32_e32 v116, 64, v186
	v_add_f32_e32 v114, v114, v115
	v_add_u32_e32 v116, 64, v116
	s_nop 1
	v_mov_b32_e32 v115, v114
	s_nop 1
	v_permlane16_swap_b32_e32 v114, v115
	s_nop 1
	s_waitcnt lgkmcnt(0)
	v_add_f32_e32 v114, v114, v115
	s_nop 1
	v_mov_b32_e32 v115, v114
	s_nop 1
	v_permlane32_swap_b32_e32 v114, v115
	s_nop 1
	s_and_saveexec_b64 s[64:65], s[4:5]
	s_cbranch_execz .LBB0_429
	v_lshl_add_u64 v[116:117], v[144:145], 2, s[28:29]
	s_waitcnt lgkmcnt(0)
	v_add_f32_e32 v114, v114, v115
	global_atomic_add_f32 v[116:117], v114, off

.LBB0_430:
	v_or_b32_e32 v118, 16, v144
	v_ashrrev_i32_e32 v119, 31, v118
	v_lshlrev_b64 v[118:119], 11, v[118:119]
	v_lshl_add_u64 v[118:119], s[22:23], 0, v[118:119]
	v_pk_mul_f32 v[98:99], v[98:99], 0.5 op_sel_hi:[1,0]
	v_pk_mul_f32 v[96:97], v[96:97], 0.5 op_sel_hi:[1,0]
	v_pk_mul_f32 v[102:103], v[102:103], 0.5 op_sel_hi:[1,0]
	v_pk_mul_f32 v[100:101], v[100:101], 0.5 op_sel_hi:[1,0]
	v_cvt_pk_bf16_f32 v114, v96, v97
	s_waitcnt lgkmcnt(0)
	v_cvt_pk_bf16_f32 v115, v98, v99
	v_lshl_add_u64 v[118:119], v[146:147], 1, v[118:119]
	v_cvt_pk_bf16_f32 v116, v100, v101
	v_cvt_pk_bf16_f32 v117, v102, v103
	v_pk_mul_f32 v[106:107], v[106:107], 0.5 op_sel_hi:[1,0]
	v_pk_mul_f32 v[104:105], v[104:105], 0.5 op_sel_hi:[1,0]
	v_pk_mul_f32 v[110:111], v[110:111], 0.5 op_sel_hi:[1,0]
	v_pk_mul_f32 v[108:109], v[108:109], 0.5 op_sel_hi:[1,0]
	s_and_b64 vcc, exec, s[8:9]
	global_store_dwordx4 v[118:119], v[114:117], off
	s_nop 1
	v_cvt_pk_bf16_f32 v114, v104, v105
	v_cvt_pk_bf16_f32 v115, v106, v107
	v_cvt_pk_bf16_f32 v116, v108, v109
	v_cvt_pk_bf16_f32 v117, v110, v111
	global_store_dwordx4 v[118:119], v[114:117], off offset:256
	s_cbranch_vccnz .LBB0_434
	v_mul_f32_e32 v101, v101, v101
	v_mul_f32_e32 v97, v97, v97
	v_fmac_f32_e32 v101, v100, v100
	v_fmac_f32_e32 v97, v96, v96
	v_mul_f32_e32 v96, v99, v99
	v_mul_f32_e32 v99, v105, v105
	v_mul_f32_e32 v100, v107, v107
	v_fmac_f32_e32 v96, v98, v98
	v_mul_f32_e32 v98, v109, v109
	v_fmac_f32_e32 v99, v104, v104
	v_fmac_f32_e32 v100, v106, v106
	v_mul_f32_e32 v103, v103, v103
	v_add_f32_e32 v96, v97, v96
	v_mul_f32_e32 v97, v111, v111
	v_fmac_f32_e32 v98, v108, v108
	v_add_f32_e32 v99, v99, v100
	v_fmac_f32_e32 v103, v102, v102
	v_add_f32_e32 v96, v96, v101
	v_fmac_f32_e32 v97, v110, v110
	v_add_f32_e32 v98, v99, v98
	v_add_f32_e32 v96, v103, v96
	v_add_f32_e32 v97, v97, v98
	v_and_b32_e32 v98, 64, v186
	v_add_f32_e32 v96, v96, v97
	v_add_u32_e32 v98, 64, v98
	s_nop 1
	v_mov_b32_e32 v97, v96
	s_nop 1
	v_permlane16_swap_b32_e32 v96, v97
	s_nop 1
	s_waitcnt lgkmcnt(0)
	v_add_f32_e32 v96, v96, v97
	s_nop 1
	v_mov_b32_e32 v97, v96
	s_nop 1
	v_permlane32_swap_b32_e32 v96, v97
	s_nop 1
	s_and_saveexec_b64 s[64:65], s[4:5]
	s_cbranch_execz .LBB0_433
	v_lshl_add_u64 v[98:99], v[144:145], 2, s[28:29]
	s_waitcnt lgkmcnt(0)
	v_add_f32_e32 v96, v96, v97
	global_atomic_add_f32 v[98:99], v96, off offset:64

.LBB0_434:
	v_or_b32_e32 v100, 32, v144
	v_ashrrev_i32_e32 v101, 31, v100
	v_lshlrev_b64 v[100:101], 11, v[100:101]
	v_lshl_add_u64 v[100:101], s[22:23], 0, v[100:101]
	v_pk_mul_f32 v[82:83], v[82:83], 0.5 op_sel_hi:[1,0]
	v_pk_mul_f32 v[80:81], v[80:81], 0.5 op_sel_hi:[1,0]
	v_pk_mul_f32 v[86:87], v[86:87], 0.5 op_sel_hi:[1,0]
	v_pk_mul_f32 v[84:85], v[84:85], 0.5 op_sel_hi:[1,0]
	v_cvt_pk_bf16_f32 v96, v80, v81
	s_waitcnt lgkmcnt(0)
	v_cvt_pk_bf16_f32 v97, v82, v83
	v_lshl_add_u64 v[100:101], v[146:147], 1, v[100:101]
	v_cvt_pk_bf16_f32 v98, v84, v85
	v_cvt_pk_bf16_f32 v99, v86, v87
	v_pk_mul_f32 v[90:91], v[90:91], 0.5 op_sel_hi:[1,0]
	v_pk_mul_f32 v[88:89], v[88:89], 0.5 op_sel_hi:[1,0]
	v_pk_mul_f32 v[94:95], v[94:95], 0.5 op_sel_hi:[1,0]
	v_pk_mul_f32 v[92:93], v[92:93], 0.5 op_sel_hi:[1,0]
	s_and_b64 vcc, exec, s[8:9]
	global_store_dwordx4 v[100:101], v[96:99], off
	s_nop 1
	v_cvt_pk_bf16_f32 v96, v88, v89
	v_cvt_pk_bf16_f32 v97, v90, v91
	v_cvt_pk_bf16_f32 v98, v92, v93
	v_cvt_pk_bf16_f32 v99, v94, v95
	global_store_dwordx4 v[100:101], v[96:99], off offset:256
	s_cbranch_vccnz .LBB0_438
	v_mul_f32_e32 v85, v85, v85
	v_mul_f32_e32 v81, v81, v81
	v_fmac_f32_e32 v85, v84, v84
	v_fmac_f32_e32 v81, v80, v80
	v_mul_f32_e32 v80, v83, v83
	v_mul_f32_e32 v83, v89, v89
	v_mul_f32_e32 v84, v91, v91
	v_fmac_f32_e32 v80, v82, v82
	v_mul_f32_e32 v82, v93, v93
	v_fmac_f32_e32 v83, v88, v88
	v_fmac_f32_e32 v84, v90, v90
	v_mul_f32_e32 v87, v87, v87
	v_add_f32_e32 v80, v81, v80
	v_mul_f32_e32 v81, v95, v95
	v_fmac_f32_e32 v82, v92, v92
	v_add_f32_e32 v83, v83, v84
	v_fmac_f32_e32 v87, v86, v86
	v_add_f32_e32 v80, v80, v85
	v_fmac_f32_e32 v81, v94, v94
	v_add_f32_e32 v82, v83, v82
	v_add_f32_e32 v80, v87, v80
	v_add_f32_e32 v81, v81, v82
	v_and_b32_e32 v82, 64, v186
	v_add_f32_e32 v80, v80, v81
	v_add_u32_e32 v82, 64, v82
	s_nop 1
	v_mov_b32_e32 v81, v80
	s_nop 1
	v_permlane16_swap_b32_e32 v80, v81
	s_nop 1
	s_waitcnt lgkmcnt(0)
	v_add_f32_e32 v80, v80, v81
	s_nop 1
	v_mov_b32_e32 v81, v80
	s_nop 1
	v_permlane32_swap_b32_e32 v80, v81
	s_nop 1
	s_and_saveexec_b64 s[64:65], s[4:5]
	s_cbranch_execz .LBB0_437
	v_lshl_add_u64 v[82:83], v[144:145], 2, s[28:29]
	s_waitcnt lgkmcnt(0)
	v_add_f32_e32 v80, v80, v81
	global_atomic_add_f32 v[82:83], v80, off offset:128

.LBB0_438:
	v_or_b32_e32 v84, 48, v144
	v_ashrrev_i32_e32 v85, 31, v84
	v_lshlrev_b64 v[84:85], 11, v[84:85]
	v_lshl_add_u64 v[84:85], s[22:23], 0, v[84:85]
	v_pk_mul_f32 v[50:51], v[50:51], 0.5 op_sel_hi:[1,0]
	v_pk_mul_f32 v[48:49], v[48:49], 0.5 op_sel_hi:[1,0]
	v_pk_mul_f32 v[58:59], v[58:59], 0.5 op_sel_hi:[1,0]
	v_pk_mul_f32 v[56:57], v[56:57], 0.5 op_sel_hi:[1,0]
	v_cvt_pk_bf16_f32 v80, v48, v49
	s_waitcnt lgkmcnt(0)
	v_cvt_pk_bf16_f32 v81, v50, v51
	v_lshl_add_u64 v[84:85], v[146:147], 1, v[84:85]
	v_cvt_pk_bf16_f32 v82, v56, v57
	v_cvt_pk_bf16_f32 v83, v58, v59
	v_pk_mul_f32 v[66:67], v[66:67], 0.5 op_sel_hi:[1,0]
	v_pk_mul_f32 v[64:65], v[64:65], 0.5 op_sel_hi:[1,0]
	v_pk_mul_f32 v[74:75], v[74:75], 0.5 op_sel_hi:[1,0]
	v_pk_mul_f32 v[72:73], v[72:73], 0.5 op_sel_hi:[1,0]
	s_and_b64 vcc, exec, s[8:9]
	global_store_dwordx4 v[84:85], v[80:83], off
	s_nop 1
	v_cvt_pk_bf16_f32 v80, v64, v65
	v_cvt_pk_bf16_f32 v81, v66, v67
	v_cvt_pk_bf16_f32 v82, v72, v73
	v_cvt_pk_bf16_f32 v83, v74, v75
	global_store_dwordx4 v[84:85], v[80:83], off offset:256
	s_cbranch_vccnz .LBB0_442
	v_mul_f32_e32 v57, v57, v57
	v_mul_f32_e32 v49, v49, v49
	v_fmac_f32_e32 v57, v56, v56
	v_fmac_f32_e32 v49, v48, v48
	v_mul_f32_e32 v48, v51, v51
	v_mul_f32_e32 v51, v65, v65
	v_mul_f32_e32 v56, v67, v67
	v_fmac_f32_e32 v48, v50, v50
	v_mul_f32_e32 v50, v73, v73
	v_fmac_f32_e32 v51, v64, v64
	v_fmac_f32_e32 v56, v66, v66
	v_mul_f32_e32 v59, v59, v59
	v_add_f32_e32 v48, v49, v48
	v_mul_f32_e32 v49, v75, v75
	v_fmac_f32_e32 v50, v72, v72
	v_add_f32_e32 v51, v51, v56
	v_fmac_f32_e32 v59, v58, v58
	v_add_f32_e32 v48, v48, v57
	v_fmac_f32_e32 v49, v74, v74
	v_add_f32_e32 v50, v51, v50
	v_add_f32_e32 v48, v59, v48
	v_add_f32_e32 v49, v49, v50
	v_and_b32_e32 v50, 64, v186
	v_add_f32_e32 v48, v48, v49
	v_add_u32_e32 v50, 64, v50
	s_nop 1
	v_mov_b32_e32 v49, v48
	s_nop 1
	v_permlane16_swap_b32_e32 v48, v49
	s_nop 1
	s_waitcnt lgkmcnt(0)
	v_add_f32_e32 v48, v48, v49
	s_nop 1
	v_mov_b32_e32 v49, v48
	s_nop 1
	v_permlane32_swap_b32_e32 v48, v49
	s_nop 1
	s_and_saveexec_b64 s[64:65], s[4:5]
	s_cbranch_execz .LBB0_441
	v_lshl_add_u64 v[50:51], v[144:145], 2, s[28:29]
	s_waitcnt lgkmcnt(0)
	v_add_f32_e32 v48, v48, v49
	global_atomic_add_f32 v[50:51], v48, off offset:192

.LBB0_442:
	v_pk_mul_f32 v[50:51], v[52:53], 0.5 op_sel_hi:[1,0]
	v_pk_mul_f32 v[52:53], v[60:61], 0.5 op_sel_hi:[1,0]
	v_add_co_u32_e32 v60, vcc, s21, v112
	s_waitcnt lgkmcnt(0)
	v_pk_mul_f32 v[48:49], v[54:55], 0.5 op_sel_hi:[1,0]
	v_pk_mul_f32 v[54:55], v[62:63], 0.5 op_sel_hi:[1,0]
	v_cvt_pk_bf16_f32 v56, v50, v51
	v_cvt_pk_bf16_f32 v57, v48, v49
	v_cvt_pk_bf16_f32 v58, v52, v53
	v_addc_co_u32_e32 v61, vcc, 0, v113, vcc
	v_cvt_pk_bf16_f32 v59, v54, v55
	v_lshl_add_u64 v[72:73], v[112:113], 0, s[10:11]
	global_store_dwordx4 v[60:61], v[56:59], off
	v_pk_mul_f32 v[62:63], v[78:79], 0.5 op_sel_hi:[1,0]
	v_pk_mul_f32 v[60:61], v[76:77], 0.5 op_sel_hi:[1,0]
	v_pk_mul_f32 v[56:57], v[70:71], 0.5 op_sel_hi:[1,0]
	v_pk_mul_f32 v[58:59], v[68:69], 0.5 op_sel_hi:[1,0]
	s_and_b64 vcc, exec, s[8:9]
	v_cvt_pk_bf16_f32 v64, v58, v59
	v_cvt_pk_bf16_f32 v65, v56, v57
	v_cvt_pk_bf16_f32 v66, v60, v61
	v_cvt_pk_bf16_f32 v67, v62, v63
	global_store_dwordx4 v[72:73], v[64:67], off offset:256
	s_cbranch_vccnz .LBB0_446
	v_mul_f32_e32 v51, v51, v51
	v_mul_f32_e32 v49, v49, v49
	v_mul_f32_e32 v53, v53, v53
	v_fmac_f32_e32 v51, v50, v50
	v_fmac_f32_e32 v49, v48, v48
	v_fmac_f32_e32 v53, v52, v52
	v_add_f32_e32 v48, v51, v49
	v_mul_f32_e32 v51, v59, v59
	v_mul_f32_e32 v52, v57, v57
	v_mul_f32_e32 v50, v61, v61
	v_fmac_f32_e32 v51, v58, v58
	v_fmac_f32_e32 v52, v56, v56
	v_mul_f32_e32 v55, v55, v55
	v_mul_f32_e32 v49, v63, v63
	v_fmac_f32_e32 v50, v60, v60
	v_add_f32_e32 v51, v51, v52
	v_fmac_f32_e32 v55, v54, v54
	v_add_f32_e32 v48, v48, v53
	v_fmac_f32_e32 v49, v62, v62
	v_add_f32_e32 v50, v51, v50
	v_add_f32_e32 v48, v55, v48
	v_add_f32_e32 v49, v49, v50
	v_and_b32_e32 v50, 64, v186
	v_add_f32_e32 v48, v48, v49
	v_add_u32_e32 v50, 64, v50
	s_nop 1
	v_mov_b32_e32 v49, v48
	s_nop 1
	v_permlane16_swap_b32_e32 v48, v49
	s_nop 1
	s_waitcnt lgkmcnt(0)
	v_add_f32_e32 v48, v48, v49
	s_nop 1
	v_mov_b32_e32 v49, v48
	s_nop 1
	v_permlane32_swap_b32_e32 v48, v49
	s_nop 1
	s_and_saveexec_b64 s[64:65], s[4:5]
	s_cbranch_execz .LBB0_445
	v_lshl_add_u64 v[50:51], v[144:145], 2, s[28:29]
	s_waitcnt lgkmcnt(0)
	v_add_f32_e32 v48, v48, v49
	global_atomic_add_f32 v[50:51], v48, off offset:512

.LBB0_446:
	v_add_co_u32_e32 v54, vcc, s48, v112
	v_pk_mul_f32 v[34:35], v[34:35], 0.5 op_sel_hi:[1,0]
	s_nop 0
	v_addc_co_u32_e32 v55, vcc, 0, v113, vcc
	v_pk_mul_f32 v[32:33], v[32:33], 0.5 op_sel_hi:[1,0]
	v_pk_mul_f32 v[38:39], v[38:39], 0.5 op_sel_hi:[1,0]
	v_pk_mul_f32 v[36:37], v[36:37], 0.5 op_sel_hi:[1,0]
	v_cvt_pk_bf16_f32 v48, v32, v33
	s_waitcnt lgkmcnt(0)
	v_cvt_pk_bf16_f32 v49, v34, v35
	v_lshl_add_u64 v[52:53], v[112:113], 0, s[12:13]
	v_cvt_pk_bf16_f32 v50, v36, v37
	v_cvt_pk_bf16_f32 v51, v38, v39
	v_pk_mul_f32 v[42:43], v[42:43], 0.5 op_sel_hi:[1,0]
	v_pk_mul_f32 v[40:41], v[40:41], 0.5 op_sel_hi:[1,0]
	v_pk_mul_f32 v[46:47], v[46:47], 0.5 op_sel_hi:[1,0]
	v_pk_mul_f32 v[44:45], v[44:45], 0.5 op_sel_hi:[1,0]
	s_and_b64 vcc, exec, s[8:9]
	global_store_dwordx4 v[54:55], v[48:51], off
	s_nop 1
	v_cvt_pk_bf16_f32 v48, v40, v41
	v_cvt_pk_bf16_f32 v49, v42, v43
	v_cvt_pk_bf16_f32 v50, v44, v45
	v_cvt_pk_bf16_f32 v51, v46, v47
	global_store_dwordx4 v[52:53], v[48:51], off offset:256
	s_cbranch_vccnz .LBB0_450
	v_mul_f32_e32 v37, v37, v37
	v_mul_f32_e32 v33, v33, v33
	v_fmac_f32_e32 v37, v36, v36
	v_fmac_f32_e32 v33, v32, v32
	v_mul_f32_e32 v32, v35, v35
	v_mul_f32_e32 v35, v41, v41
	v_mul_f32_e32 v36, v43, v43
	v_fmac_f32_e32 v32, v34, v34
	v_mul_f32_e32 v34, v45, v45
	v_fmac_f32_e32 v35, v40, v40
	v_fmac_f32_e32 v36, v42, v42
	v_mul_f32_e32 v39, v39, v39
	v_add_f32_e32 v32, v33, v32
	v_mul_f32_e32 v33, v47, v47
	v_fmac_f32_e32 v34, v44, v44
	v_add_f32_e32 v35, v35, v36
	v_fmac_f32_e32 v39, v38, v38
	v_add_f32_e32 v32, v32, v37
	v_fmac_f32_e32 v33, v46, v46
	v_add_f32_e32 v34, v35, v34
	v_add_f32_e32 v32, v39, v32
	v_add_f32_e32 v33, v33, v34
	v_and_b32_e32 v34, 64, v186
	v_add_f32_e32 v32, v32, v33
	v_add_u32_e32 v34, 64, v34
	s_nop 1
	v_mov_b32_e32 v33, v32
	s_nop 1
	v_permlane16_swap_b32_e32 v32, v33
	s_nop 1
	s_waitcnt lgkmcnt(0)
	v_add_f32_e32 v32, v32, v33
	s_nop 1
	v_mov_b32_e32 v33, v32
	s_nop 1
	v_permlane32_swap_b32_e32 v32, v33
	s_nop 1
	s_and_saveexec_b64 s[64:65], s[4:5]
	s_cbranch_execz .LBB0_449
	v_lshl_add_u64 v[34:35], v[144:145], 2, s[28:29]
	s_waitcnt lgkmcnt(0)
	v_add_f32_e32 v32, v32, v33
	global_atomic_add_f32 v[34:35], v32, off offset:576

.LBB0_450:
	v_add_co_u32_e32 v38, vcc, s49, v112
	v_pk_mul_f32 v[18:19], v[18:19], 0.5 op_sel_hi:[1,0]
	s_nop 0
	v_addc_co_u32_e32 v39, vcc, 0, v113, vcc
	v_pk_mul_f32 v[16:17], v[16:17], 0.5 op_sel_hi:[1,0]
	v_pk_mul_f32 v[22:23], v[22:23], 0.5 op_sel_hi:[1,0]
	v_pk_mul_f32 v[20:21], v[20:21], 0.5 op_sel_hi:[1,0]
	v_cvt_pk_bf16_f32 v32, v16, v17
	s_waitcnt lgkmcnt(0)
	v_cvt_pk_bf16_f32 v33, v18, v19
	v_lshl_add_u64 v[36:37], v[112:113], 0, s[14:15]
	v_cvt_pk_bf16_f32 v34, v20, v21
	v_cvt_pk_bf16_f32 v35, v22, v23
	v_pk_mul_f32 v[26:27], v[26:27], 0.5 op_sel_hi:[1,0]
	v_pk_mul_f32 v[24:25], v[24:25], 0.5 op_sel_hi:[1,0]
	v_pk_mul_f32 v[30:31], v[30:31], 0.5 op_sel_hi:[1,0]
	v_pk_mul_f32 v[28:29], v[28:29], 0.5 op_sel_hi:[1,0]
	s_and_b64 vcc, exec, s[8:9]
	global_store_dwordx4 v[38:39], v[32:35], off
	s_nop 1
	v_cvt_pk_bf16_f32 v32, v24, v25
	v_cvt_pk_bf16_f32 v33, v26, v27
	v_cvt_pk_bf16_f32 v34, v28, v29
	v_cvt_pk_bf16_f32 v35, v30, v31
	global_store_dwordx4 v[36:37], v[32:35], off offset:256
	s_cbranch_vccnz .LBB0_454
	v_mul_f32_e32 v21, v21, v21
	v_mul_f32_e32 v17, v17, v17
	v_fmac_f32_e32 v21, v20, v20
	v_fmac_f32_e32 v17, v16, v16
	v_mul_f32_e32 v16, v19, v19
	v_mul_f32_e32 v19, v25, v25
	v_mul_f32_e32 v20, v27, v27
	v_fmac_f32_e32 v16, v18, v18
	v_mul_f32_e32 v18, v29, v29
	v_fmac_f32_e32 v19, v24, v24
	v_fmac_f32_e32 v20, v26, v26
	v_mul_f32_e32 v23, v23, v23
	v_add_f32_e32 v16, v17, v16
	v_mul_f32_e32 v17, v31, v31
	v_fmac_f32_e32 v18, v28, v28
	v_add_f32_e32 v19, v19, v20
	v_fmac_f32_e32 v23, v22, v22
	v_add_f32_e32 v16, v16, v21
	v_fmac_f32_e32 v17, v30, v30
	v_add_f32_e32 v18, v19, v18
	v_add_f32_e32 v16, v23, v16
	v_add_f32_e32 v17, v17, v18
	v_and_b32_e32 v18, 64, v186
	v_add_f32_e32 v16, v16, v17
	v_add_u32_e32 v18, 64, v18
	s_nop 1
	v_mov_b32_e32 v17, v16
	s_nop 1
	v_permlane16_swap_b32_e32 v16, v17
	s_nop 1
	s_waitcnt lgkmcnt(0)
	v_add_f32_e32 v16, v16, v17
	s_nop 1
	v_mov_b32_e32 v17, v16
	s_nop 1
	v_permlane32_swap_b32_e32 v16, v17
	s_nop 1
	s_and_saveexec_b64 s[64:65], s[4:5]
	s_cbranch_execz .LBB0_453
	v_lshl_add_u64 v[18:19], v[144:145], 2, s[28:29]
	s_waitcnt lgkmcnt(0)
	v_add_f32_e32 v16, v16, v17
	global_atomic_add_f32 v[18:19], v16, off offset:640

.LBB0_454:
	v_add_co_u32_e32 v22, vcc, s74, v112
	v_pk_mul_f32 v[2:3], v[2:3], 0.5 op_sel_hi:[1,0]
	s_nop 0
	v_addc_co_u32_e32 v23, vcc, 0, v113, vcc
	v_pk_mul_f32 v[0:1], v[0:1], 0.5 op_sel_hi:[1,0]
	v_pk_mul_f32 v[6:7], v[6:7], 0.5 op_sel_hi:[1,0]
	v_pk_mul_f32 v[4:5], v[4:5], 0.5 op_sel_hi:[1,0]
	v_cvt_pk_bf16_f32 v16, v0, v1
	s_waitcnt lgkmcnt(0)
	v_cvt_pk_bf16_f32 v17, v2, v3
	v_lshl_add_u64 v[20:21], v[112:113], 0, s[52:53]
	v_cvt_pk_bf16_f32 v18, v4, v5
	v_cvt_pk_bf16_f32 v19, v6, v7
	v_pk_mul_f32 v[10:11], v[10:11], 0.5 op_sel_hi:[1,0]
	v_pk_mul_f32 v[8:9], v[8:9], 0.5 op_sel_hi:[1,0]
	v_pk_mul_f32 v[14:15], v[14:15], 0.5 op_sel_hi:[1,0]
	v_pk_mul_f32 v[12:13], v[12:13], 0.5 op_sel_hi:[1,0]
	s_and_b64 vcc, exec, s[8:9]
	global_store_dwordx4 v[22:23], v[16:19], off
	s_nop 1
	v_cvt_pk_bf16_f32 v16, v8, v9
	v_cvt_pk_bf16_f32 v17, v10, v11
	v_cvt_pk_bf16_f32 v18, v12, v13
	v_cvt_pk_bf16_f32 v19, v14, v15
	global_store_dwordx4 v[20:21], v[16:19], off offset:256
	s_cbranch_vccnz .LBB0_458
	v_mul_f32_e32 v5, v5, v5
	v_mul_f32_e32 v1, v1, v1
	v_fmac_f32_e32 v5, v4, v4
	v_fmac_f32_e32 v1, v0, v0
	v_mul_f32_e32 v0, v3, v3
	v_mul_f32_e32 v3, v9, v9
	v_mul_f32_e32 v4, v11, v11
	v_fmac_f32_e32 v0, v2, v2
	v_mul_f32_e32 v2, v13, v13
	v_fmac_f32_e32 v3, v8, v8
	v_fmac_f32_e32 v4, v10, v10
	v_mul_f32_e32 v7, v7, v7
	v_add_f32_e32 v0, v1, v0
	v_mul_f32_e32 v1, v15, v15
	v_fmac_f32_e32 v2, v12, v12
	v_add_f32_e32 v3, v3, v4
	v_fmac_f32_e32 v7, v6, v6
	v_add_f32_e32 v0, v0, v5
	v_fmac_f32_e32 v1, v14, v14
	v_add_f32_e32 v2, v3, v2
	v_add_f32_e32 v0, v7, v0
	v_add_f32_e32 v1, v1, v2
	v_and_b32_e32 v2, 64, v186
	v_add_f32_e32 v0, v0, v1
	v_add_u32_e32 v2, 64, v2
	s_nop 1
	v_mov_b32_e32 v1, v0
	s_nop 1
	v_permlane16_swap_b32_e32 v0, v1
	s_nop 1
	s_waitcnt lgkmcnt(0)
	v_add_f32_e32 v0, v0, v1
	s_nop 1
	v_mov_b32_e32 v1, v0
	s_nop 1
	v_permlane32_swap_b32_e32 v0, v1
	s_nop 1
	s_and_saveexec_b64 s[8:9], s[4:5]
	s_cbranch_execz .LBB0_457
	v_lshl_add_u64 v[2:3], v[144:145], 2, s[28:29]
	s_waitcnt lgkmcnt(0)
	v_add_f32_e32 v0, v0, v1
	global_atomic_add_f32 v[2:3], v0, off offset:704

.LBB0_567:
	s_waitcnt vmcnt(0)
	v_fmamk_f32 v184, v200, 0x3a800000, v228
	v_rsq_f32_e32 v184, v184
	s_cmp_eq_u32 s83, 4
	s_cselect_b64 s[10:11], -1, 0
	s_cmp_eq_u32 s83, 1
	s_cselect_b64 s[8:9], -1, 0
	v_pk_fma_f32 v[158:159], v[158:159], v[184:185], v[46:47] op_sel_hi:[1,0,1]
	v_pk_fma_f32 v[156:157], v[156:157], v[184:185], v[44:45] op_sel_hi:[1,0,1]
	v_pk_fma_f32 v[154:155], v[154:155], v[184:185], v[42:43] op_sel_hi:[1,0,1]
	v_pk_fma_f32 v[152:153], v[152:153], v[184:185], v[40:41] op_sel_hi:[1,0,1]
	v_pk_fma_f32 v[150:151], v[150:151], v[184:185], v[38:39] op_sel_hi:[1,0,1]
	v_pk_fma_f32 v[148:149], v[148:149], v[184:185], v[36:37] op_sel_hi:[1,0,1]
	v_pk_fma_f32 v[146:147], v[146:147], v[184:185], v[34:35] op_sel_hi:[1,0,1]
	v_pk_fma_f32 v[144:145], v[144:145], v[184:185], v[32:33] op_sel_hi:[1,0,1]
	v_cndmask_b32_e64 v184, 0, 1, s[8:9]
	s_mov_b64 s[94:95], -1
	s_and_b64 vcc, exec, s[92:93]
	v_cmp_ne_u32_e64 s[8:9], 1, v184
	s_cbranch_vccz .LBB0_573
	s_and_b64 vcc, exec, s[8:9]
	v_mov_b32_e32 v209, v159
	v_mov_b32_e32 v208, v158
	v_mov_b32_e32 v207, v157
	v_mov_b32_e32 v206, v156
	v_mov_b32_e32 v213, v155
	v_mov_b32_e32 v212, v154
	v_mov_b32_e32 v211, v153
	v_mov_b32_e32 v210, v152
	v_mov_b32_e32 v217, v151
	v_mov_b32_e32 v216, v150
	v_mov_b32_e32 v215, v149
	v_mov_b32_e32 v214, v148
	v_mov_b32_e32 v221, v147
	v_mov_b32_e32 v220, v146
	v_mov_b32_e32 v219, v145
	v_mov_b32_e32 v218, v144
	s_cbranch_vccnz .LBB0_572
	v_and_b32_e32 v201, 0x7fffffff, v157
	v_and_b32_e32 v200, 0x7fffffff, v156
	v_pk_fma_f32 v[200:201], v[200:201], s[68:69], 1.0 op_sel_hi:[1,0,0]
	v_pk_mul_f32 v[210:211], v[156:157], v[156:157]
	v_rcp_f32_e32 v206, v200
	v_rcp_f32_e32 v207, v201
	v_mov_b64_e32 v[200:201], s[72:73]
	v_pk_mul_f32 v[210:211], v[210:211], s[80:81] op_sel_hi:[1,0]
	v_cmp_gt_f32_e32 vcc, 0, v156
	v_pk_fma_f32 v[208:209], v[206:207], s[70:71], v[200:201] op_sel_hi:[1,0,0]
	v_exp_f32_e32 v210, v210
	v_pk_fma_f32 v[208:209], v[206:207], v[208:209], s[74:75] op_sel_hi:[1,1,0]
	v_exp_f32_e32 v211, v211
	v_pk_fma_f32 v[208:209], v[206:207], v[208:209], s[76:77] op_sel_hi:[1,1,0]
	v_pk_mul_f32 v[214:215], v[152:153], v[152:153]
	v_pk_fma_f32 v[208:209], v[206:207], v[208:209], s[78:79] op_sel_hi:[1,1,0]
	v_pk_mul_f32 v[214:215], v[214:215], s[80:81] op_sel_hi:[1,0]
	v_pk_mul_f32 v[206:207], v[206:207], v[208:209]
	v_pk_mul_f32 v[208:209], v[158:159], v[158:159]
	v_pk_mul_f32 v[206:207], v[210:211], v[206:207]
	v_pk_mul_f32 v[208:209], v[208:209], s[80:81] op_sel_hi:[1,0]
	v_pk_mul_f32 v[210:211], v[156:157], v[206:207]
	v_pk_fma_f32 v[206:207], v[156:157], v[206:207], v[156:157] neg_lo:[1,0,0] neg_hi:[1,0,0]
	v_exp_f32_e32 v208, v208
	v_cndmask_b32_e32 v206, v206, v210, vcc
	v_cmp_gt_f32_e32 vcc, 0, v157
	v_and_b32_e32 v210, 0x7fffffff, v158
	v_exp_f32_e32 v209, v209
	v_cndmask_b32_e32 v207, v207, v211, vcc
	v_and_b32_e32 v211, 0x7fffffff, v159
	v_pk_fma_f32 v[210:211], v[210:211], s[68:69], 1.0 op_sel_hi:[1,0,0]
	v_cmp_gt_f32_e32 vcc, 0, v158
	v_rcp_f32_e32 v210, v210
	v_rcp_f32_e32 v211, v211
	v_exp_f32_e32 v214, v214
	v_exp_f32_e32 v215, v215
	v_pk_mul_f32 v[218:219], v[148:149], v[148:149]
	v_pk_fma_f32 v[212:213], v[210:211], s[70:71], v[200:201] op_sel_hi:[1,0,0]
	v_pk_mul_f32 v[218:219], v[218:219], s[80:81] op_sel_hi:[1,0]
	v_pk_fma_f32 v[212:213], v[210:211], v[212:213], s[74:75] op_sel_hi:[1,1,0]
	v_exp_f32_e32 v218, v218
	v_pk_fma_f32 v[212:213], v[210:211], v[212:213], s[76:77] op_sel_hi:[1,1,0]
	v_exp_f32_e32 v219, v219
	v_pk_fma_f32 v[212:213], v[210:211], v[212:213], s[78:79] op_sel_hi:[1,1,0]
	v_pk_mul_f32 v[240:241], v[144:145], v[144:145]
	v_pk_mul_f32 v[210:211], v[210:211], v[212:213]
	v_pk_mul_f32 v[240:241], v[240:241], s[80:81] op_sel_hi:[1,0]
	v_pk_mul_f32 v[208:209], v[208:209], v[210:211]
	v_exp_f32_e32 v240, v240
	v_pk_mul_f32 v[210:211], v[158:159], v[208:209]
	v_pk_fma_f32 v[208:209], v[158:159], v[208:209], v[158:159] neg_lo:[1,0,0] neg_hi:[1,0,0]
	v_exp_f32_e32 v241, v241
	v_cndmask_b32_e32 v208, v208, v210, vcc
	v_cmp_gt_f32_e32 vcc, 0, v159
	v_and_b32_e32 v210, 0x7fffffff, v152
	v_add_f32_e32 v184, 0, v206
	v_cndmask_b32_e32 v209, v209, v211, vcc
	v_and_b32_e32 v211, 0x7fffffff, v153
	v_pk_fma_f32 v[210:211], v[210:211], s[68:69], 1.0 op_sel_hi:[1,0,0]
	v_cmp_gt_f32_e32 vcc, 0, v152
	v_rcp_f32_e32 v210, v210
	v_rcp_f32_e32 v211, v211
	v_add_f32_e32 v184, v207, v184
	v_add_f32_e32 v184, v208, v184
	v_add_f32_e32 v184, v209, v184
	v_pk_fma_f32 v[212:213], v[210:211], s[70:71], v[200:201] op_sel_hi:[1,0,0]
	v_pk_fma_f32 v[212:213], v[210:211], v[212:213], s[74:75] op_sel_hi:[1,1,0]
	v_pk_fma_f32 v[212:213], v[210:211], v[212:213], s[76:77] op_sel_hi:[1,1,0]
	s_nop 0
	v_pk_fma_f32 v[212:213], v[210:211], v[212:213], s[78:79] op_sel_hi:[1,1,0]
	s_nop 0
	v_pk_mul_f32 v[210:211], v[210:211], v[212:213]
	v_pk_mul_f32 v[212:213], v[154:155], v[154:155]
	v_pk_mul_f32 v[210:211], v[214:215], v[210:211]
	v_pk_mul_f32 v[212:213], v[212:213], s[80:81] op_sel_hi:[1,0]
	v_pk_mul_f32 v[214:215], v[152:153], v[210:211]
	v_pk_fma_f32 v[210:211], v[152:153], v[210:211], v[152:153] neg_lo:[1,0,0] neg_hi:[1,0,0]
	v_exp_f32_e32 v212, v212
	v_cndmask_b32_e32 v210, v210, v214, vcc
	v_cmp_gt_f32_e32 vcc, 0, v153
	v_and_b32_e32 v214, 0x7fffffff, v154
	v_exp_f32_e32 v213, v213
	v_cndmask_b32_e32 v211, v211, v215, vcc
	v_and_b32_e32 v215, 0x7fffffff, v155
	v_pk_fma_f32 v[214:215], v[214:215], s[68:69], 1.0 op_sel_hi:[1,0,0]
	v_cmp_gt_f32_e32 vcc, 0, v154
	v_rcp_f32_e32 v214, v214
	v_rcp_f32_e32 v215, v215
	v_add_f32_e32 v184, v210, v184
	v_add_f32_e32 v184, v211, v184
	v_pk_fma_f32 v[216:217], v[214:215], s[70:71], v[200:201] op_sel_hi:[1,0,0]
	s_nop 0
	v_pk_fma_f32 v[216:217], v[214:215], v[216:217], s[74:75] op_sel_hi:[1,1,0]
	s_nop 0
	v_pk_fma_f32 v[216:217], v[214:215], v[216:217], s[76:77] op_sel_hi:[1,1,0]
	s_nop 0
	v_pk_fma_f32 v[216:217], v[214:215], v[216:217], s[78:79] op_sel_hi:[1,1,0]
	s_nop 0
	v_pk_mul_f32 v[214:215], v[214:215], v[216:217]
	s_nop 0
	v_pk_mul_f32 v[212:213], v[212:213], v[214:215]
	s_nop 0
	v_pk_mul_f32 v[214:215], v[154:155], v[212:213]
	v_pk_fma_f32 v[212:213], v[154:155], v[212:213], v[154:155] neg_lo:[1,0,0] neg_hi:[1,0,0]
	s_nop 0
	v_cndmask_b32_e32 v212, v212, v214, vcc
	v_cmp_gt_f32_e32 vcc, 0, v155
	v_and_b32_e32 v214, 0x7fffffff, v148
	v_add_f32_e32 v184, v212, v184
	v_cndmask_b32_e32 v213, v213, v215, vcc
	v_and_b32_e32 v215, 0x7fffffff, v149
	v_pk_fma_f32 v[214:215], v[214:215], s[68:69], 1.0 op_sel_hi:[1,0,0]
	v_cmp_gt_f32_e32 vcc, 0, v148
	v_rcp_f32_e32 v214, v214
	v_rcp_f32_e32 v215, v215
	v_add_f32_e32 v184, v213, v184
	v_pk_fma_f32 v[216:217], v[214:215], s[70:71], v[200:201] op_sel_hi:[1,0,0]
	s_nop 0
	v_pk_fma_f32 v[216:217], v[214:215], v[216:217], s[74:75] op_sel_hi:[1,1,0]
	s_nop 0
	v_pk_fma_f32 v[216:217], v[214:215], v[216:217], s[76:77] op_sel_hi:[1,1,0]
	s_nop 0
	v_pk_fma_f32 v[216:217], v[214:215], v[216:217], s[78:79] op_sel_hi:[1,1,0]
	s_nop 0
	v_pk_mul_f32 v[214:215], v[214:215], v[216:217]
	v_pk_mul_f32 v[216:217], v[150:151], v[150:151]
	v_pk_mul_f32 v[214:215], v[218:219], v[214:215]
	v_pk_mul_f32 v[216:217], v[216:217], s[80:81] op_sel_hi:[1,0]
	v_pk_mul_f32 v[218:219], v[148:149], v[214:215]
	v_pk_fma_f32 v[214:215], v[148:149], v[214:215], v[148:149] neg_lo:[1,0,0] neg_hi:[1,0,0]
	v_exp_f32_e32 v216, v216
	v_cndmask_b32_e32 v214, v214, v218, vcc
	v_cmp_gt_f32_e32 vcc, 0, v149
	v_and_b32_e32 v218, 0x7fffffff, v150
	v_exp_f32_e32 v217, v217
	v_cndmask_b32_e32 v215, v215, v219, vcc
	v_and_b32_e32 v219, 0x7fffffff, v151
	v_pk_fma_f32 v[218:219], v[218:219], s[68:69], 1.0 op_sel_hi:[1,0,0]
	v_cmp_gt_f32_e32 vcc, 0, v150
	v_rcp_f32_e32 v218, v218
	v_rcp_f32_e32 v219, v219
	v_add_f32_e32 v184, v214, v184
	v_add_f32_e32 v184, v215, v184
	v_pk_fma_f32 v[220:221], v[218:219], s[70:71], v[200:201] op_sel_hi:[1,0,0]
	s_nop 0
	v_pk_fma_f32 v[220:221], v[218:219], v[220:221], s[74:75] op_sel_hi:[1,1,0]
	s_nop 0
	v_pk_fma_f32 v[220:221], v[218:219], v[220:221], s[76:77] op_sel_hi:[1,1,0]
	s_nop 0
	v_pk_fma_f32 v[220:221], v[218:219], v[220:221], s[78:79] op_sel_hi:[1,1,0]
	s_nop 0
	v_pk_mul_f32 v[218:219], v[218:219], v[220:221]
	s_nop 0
	v_pk_mul_f32 v[216:217], v[216:217], v[218:219]
	s_nop 0
	v_pk_mul_f32 v[218:219], v[150:151], v[216:217]
	v_pk_fma_f32 v[216:217], v[150:151], v[216:217], v[150:151] neg_lo:[1,0,0] neg_hi:[1,0,0]
	s_nop 0
	v_cndmask_b32_e32 v216, v216, v218, vcc
	v_cmp_gt_f32_e32 vcc, 0, v151
	v_and_b32_e32 v218, 0x7fffffff, v144
	v_add_f32_e32 v184, v216, v184
	v_cndmask_b32_e32 v217, v217, v219, vcc
	v_and_b32_e32 v219, 0x7fffffff, v145
	v_pk_fma_f32 v[218:219], v[218:219], s[68:69], 1.0 op_sel_hi:[1,0,0]
	v_cmp_gt_f32_e32 vcc, 0, v144
	v_rcp_f32_e32 v218, v218
	v_rcp_f32_e32 v219, v219
	v_add_f32_e32 v184, v217, v184
	v_pk_fma_f32 v[220:221], v[218:219], s[70:71], v[200:201] op_sel_hi:[1,0,0]
	s_nop 0
	v_pk_fma_f32 v[220:221], v[218:219], v[220:221], s[74:75] op_sel_hi:[1,1,0]
	s_nop 0
	v_pk_fma_f32 v[220:221], v[218:219], v[220:221], s[76:77] op_sel_hi:[1,1,0]
	s_nop 0
	v_pk_fma_f32 v[220:221], v[218:219], v[220:221], s[78:79] op_sel_hi:[1,1,0]
	s_nop 0
	v_pk_mul_f32 v[218:219], v[218:219], v[220:221]
	v_pk_mul_f32 v[220:221], v[146:147], v[146:147]
	v_pk_mul_f32 v[218:219], v[240:241], v[218:219]
	v_pk_mul_f32 v[220:221], v[220:221], s[80:81] op_sel_hi:[1,0]
	v_pk_mul_f32 v[240:241], v[144:145], v[218:219]
	v_pk_fma_f32 v[218:219], v[144:145], v[218:219], v[144:145] neg_lo:[1,0,0] neg_hi:[1,0,0]
	v_exp_f32_e32 v220, v220
	v_cndmask_b32_e32 v218, v218, v240, vcc
	v_cmp_gt_f32_e32 vcc, 0, v145
	v_and_b32_e32 v240, 0x7fffffff, v146
	v_exp_f32_e32 v221, v221
	v_cndmask_b32_e32 v219, v219, v241, vcc
	v_and_b32_e32 v241, 0x7fffffff, v147
	v_pk_fma_f32 v[240:241], v[240:241], s[68:69], 1.0 op_sel_hi:[1,0,0]
	v_cmp_gt_f32_e32 vcc, 0, v146
	v_rcp_f32_e32 v240, v240
	v_rcp_f32_e32 v241, v241
	v_add_f32_e32 v184, v218, v184
	v_add_f32_e32 v184, v219, v184
	v_pk_fma_f32 v[200:201], v[240:241], s[70:71], v[200:201] op_sel_hi:[1,0,0]
	s_nop 0
	v_pk_fma_f32 v[200:201], v[240:241], v[200:201], s[74:75] op_sel_hi:[1,1,0]
	s_nop 0
	v_pk_fma_f32 v[200:201], v[240:241], v[200:201], s[76:77] op_sel_hi:[1,1,0]
	s_nop 0
	v_pk_fma_f32 v[200:201], v[240:241], v[200:201], s[78:79] op_sel_hi:[1,1,0]
	s_nop 0
	v_pk_mul_f32 v[200:201], v[240:241], v[200:201]
	s_nop 0
	v_pk_mul_f32 v[200:201], v[220:221], v[200:201]
	s_nop 0
	v_pk_mul_f32 v[220:221], v[146:147], v[200:201]
	v_pk_fma_f32 v[200:201], v[146:147], v[200:201], v[146:147] neg_lo:[1,0,0] neg_hi:[1,0,0]
	s_nop 0
	v_cndmask_b32_e32 v220, v200, v220, vcc
	v_cmp_gt_f32_e32 vcc, 0, v147
	v_add_f32_e32 v184, v220, v184
	v_cndmask_b32_e32 v221, v201, v221, vcc
	v_mul_f32_e32 v201, v207, v207
	v_fmac_f32_e32 v201, v206, v206
	v_fmac_f32_e32 v201, v208, v208
	v_fmac_f32_e32 v201, v209, v209
	v_fmac_f32_e32 v201, v210, v210
	v_fmac_f32_e32 v201, v211, v211
	v_fmac_f32_e32 v201, v212, v212
	v_fmac_f32_e32 v201, v213, v213
	v_fmac_f32_e32 v201, v214, v214
	v_fmac_f32_e32 v201, v215, v215
	v_fmac_f32_e32 v201, v216, v216
	v_fmac_f32_e32 v201, v217, v217
	v_fmac_f32_e32 v201, v218, v218
	v_add_f32_e32 v184, v221, v184
	v_fmac_f32_e32 v201, v219, v219
	v_mov_b32_e32 v200, v184
	s_nop 1
	v_permlane16_swap_b32_e32 v184, v200
	s_nop 1
	v_fmac_f32_e32 v201, v220, v220
	v_fmac_f32_e32 v201, v221, v221
	v_mov_b32_e32 v205, v201
	s_nop 1
	v_permlane16_swap_b32_e32 v201, v205
	s_nop 1
	s_waitcnt lgkmcnt(1)
	v_add_f32_e32 v184, v184, v200
	s_waitcnt lgkmcnt(0)
	v_add_f32_e32 v201, v201, v205
	v_mov_b32_e32 v200, v184
	s_nop 1
	v_permlane32_swap_b32_e32 v184, v200
	s_nop 1
	v_mov_b32_e32 v203, v201
	s_nop 1
	v_permlane32_swap_b32_e32 v201, v203
	s_nop 1
	s_and_saveexec_b64 s[94:95], s[4:5]
	s_cbranch_execz .LBB0_571
	v_lshlrev_b64 v[240:241], 2, v[198:199]
	v_lshl_add_u64 v[242:243], s[14:15], 0, v[240:241]
	v_lshl_add_u64 v[240:241], s[52:53], 0, v[240:241]
	s_waitcnt lgkmcnt(1)
	v_add_f32_e32 v184, v184, v200
	s_waitcnt lgkmcnt(0)
	v_add_f32_e32 v200, v201, v203
	global_atomic_add_f32 v[240:241], v184, off
	global_atomic_add_f32 v[242:243], v200, off

.LBB0_575:
	s_add_u32 s0, s28, s12
	s_addc_u32 s10, s29, s13
	s_cmp_eq_u32 s83, 3
	s_cselect_b32 s11, s27, s10
	s_cselect_b32 s10, s26, s0
	v_lshlrev_b32_e32 v184, 1, v202
	s_waitcnt lgkmcnt(0)
	v_lshl_add_u64 v[202:203], s[10:11], 0, v[184:185]
	v_lshlrev_b64 v[146:147], 11, v[198:199]
	v_lshl_add_u64 v[150:151], v[202:203], 0, v[146:147]
	v_cvt_pk_bf16_f32 v146, v206, v207
	v_cvt_pk_bf16_f32 v147, v208, v209
	v_cvt_pk_bf16_f32 v148, v210, v211
	v_cvt_pk_bf16_f32 v149, v212, v213
	global_store_dwordx4 v[150:151], v[146:149], off
	v_or_b32_e32 v144, 16, v198
	v_ashrrev_i32_e32 v145, 31, v144
	v_fmamk_f32 v148, v231, 0x3a800000, v228
	v_rsq_f32_e32 v152, v148
	v_cvt_pk_bf16_f32 v146, v214, v215
	v_cvt_pk_bf16_f32 v147, v216, v217
	v_cvt_pk_bf16_f32 v148, v218, v219
	v_cvt_pk_bf16_f32 v149, v220, v221
	global_store_dwordx4 v[150:151], v[146:149], off offset:256
	v_pk_fma_f32 v[110:111], v[110:111], v[152:153], v[46:47] op_sel_hi:[1,0,1]
	v_pk_fma_f32 v[108:109], v[108:109], v[152:153], v[44:45] op_sel_hi:[1,0,1]
	v_cndmask_b32_e64 v146, 0, 1, s[92:93]
	v_pk_fma_f32 v[106:107], v[106:107], v[152:153], v[42:43] op_sel_hi:[1,0,1]
	v_pk_fma_f32 v[104:105], v[104:105], v[152:153], v[40:41] op_sel_hi:[1,0,1]
	v_pk_fma_f32 v[102:103], v[102:103], v[152:153], v[38:39] op_sel_hi:[1,0,1]
	v_pk_fma_f32 v[100:101], v[100:101], v[152:153], v[36:37] op_sel_hi:[1,0,1]
	v_pk_fma_f32 v[98:99], v[98:99], v[152:153], v[34:35] op_sel_hi:[1,0,1]
	v_pk_fma_f32 v[96:97], v[96:97], v[152:153], v[32:33] op_sel_hi:[1,0,1]
	v_cmp_ne_u32_e64 s[10:11], 1, v146
	s_andn2_b64 vcc, exec, s[92:93]
	s_mov_b64 s[12:13], -1
	s_cbranch_vccnz .LBB0_581
	s_and_b64 vcc, exec, s[8:9]
	v_mov_b32_e32 v149, v111
	v_mov_b32_e32 v148, v110
	v_mov_b32_e32 v147, v109
	v_mov_b32_e32 v146, v108
	v_mov_b32_e32 v153, v107
	v_mov_b32_e32 v152, v106
	v_mov_b32_e32 v151, v105
	v_mov_b32_e32 v150, v104
	v_mov_b32_e32 v157, v103
	v_mov_b32_e32 v156, v102
	v_mov_b32_e32 v155, v101
	v_mov_b32_e32 v154, v100
	v_mov_b32_e32 v207, v99
	v_mov_b32_e32 v206, v98
	v_mov_b32_e32 v159, v97
	v_mov_b32_e32 v158, v96
	s_cbranch_vccnz .LBB0_580
	v_and_b32_e32 v147, 0x7fffffff, v109
	v_and_b32_e32 v146, 0x7fffffff, v108
	v_pk_fma_f32 v[146:147], v[146:147], s[68:69], 1.0 op_sel_hi:[1,0,0]
	v_mov_b64_e32 v[206:207], s[72:73]
	v_rcp_f32_e32 v146, v146
	v_rcp_f32_e32 v147, v147
	v_pk_mul_f32 v[150:151], v[108:109], v[108:109]
	v_and_b32_e32 v153, 0x7fffffff, v111
	v_pk_mul_f32 v[150:151], v[150:151], s[80:81] op_sel_hi:[1,0]
	v_pk_fma_f32 v[148:149], v[146:147], s[70:71], v[206:207] op_sel_hi:[1,0,0]
	v_exp_f32_e32 v150, v150
	v_pk_fma_f32 v[148:149], v[146:147], v[148:149], s[74:75] op_sel_hi:[1,1,0]
	v_exp_f32_e32 v151, v151
	v_pk_fma_f32 v[148:149], v[146:147], v[148:149], s[76:77] op_sel_hi:[1,1,0]
	v_and_b32_e32 v152, 0x7fffffff, v110
	v_pk_fma_f32 v[148:149], v[146:147], v[148:149], s[78:79] op_sel_hi:[1,1,0]
	v_pk_fma_f32 v[152:153], v[152:153], s[68:69], 1.0 op_sel_hi:[1,0,0]
	v_pk_mul_f32 v[146:147], v[146:147], v[148:149]
	v_rcp_f32_e32 v152, v152
	v_rcp_f32_e32 v153, v153
	v_pk_mul_f32 v[146:147], v[150:151], v[146:147]
	v_cmp_gt_f32_e32 vcc, 0, v108
	v_pk_mul_f32 v[150:151], v[108:109], v[146:147]
	v_pk_fma_f32 v[146:147], v[108:109], v[146:147], v[108:109] neg_lo:[1,0,0] neg_hi:[1,0,0]
	v_pk_mul_f32 v[148:149], v[110:111], v[110:111]
	v_cndmask_b32_e32 v146, v146, v150, vcc
	v_cmp_gt_f32_e32 vcc, 0, v109
	v_pk_mul_f32 v[148:149], v[148:149], s[80:81] op_sel_hi:[1,0]
	v_pk_mul_f32 v[154:155], v[104:105], v[104:105]
	v_cndmask_b32_e32 v147, v147, v151, vcc
	v_pk_fma_f32 v[150:151], v[152:153], s[70:71], v[206:207] op_sel_hi:[1,0,0]
	v_exp_f32_e32 v148, v148
	v_pk_fma_f32 v[150:151], v[152:153], v[150:151], s[74:75] op_sel_hi:[1,1,0]
	v_exp_f32_e32 v149, v149
	v_pk_fma_f32 v[150:151], v[152:153], v[150:151], s[76:77] op_sel_hi:[1,1,0]
	v_cmp_gt_f32_e32 vcc, 0, v110
	v_pk_fma_f32 v[150:151], v[152:153], v[150:151], s[78:79] op_sel_hi:[1,1,0]
	v_pk_mul_f32 v[154:155], v[154:155], s[80:81] op_sel_hi:[1,0]
	v_pk_mul_f32 v[150:151], v[152:153], v[150:151]
	v_and_b32_e32 v153, 0x7fffffff, v105
	v_and_b32_e32 v152, 0x7fffffff, v104
	v_pk_fma_f32 v[152:153], v[152:153], s[68:69], 1.0 op_sel_hi:[1,0,0]
	v_pk_mul_f32 v[148:149], v[148:149], v[150:151]
	v_rcp_f32_e32 v152, v152
	v_rcp_f32_e32 v153, v153
	v_pk_mul_f32 v[150:151], v[110:111], v[148:149]
	v_pk_fma_f32 v[148:149], v[110:111], v[148:149], v[110:111] neg_lo:[1,0,0] neg_hi:[1,0,0]
	v_exp_f32_e32 v154, v154
	v_cndmask_b32_e32 v148, v148, v150, vcc
	v_cmp_gt_f32_e32 vcc, 0, v111
	v_exp_f32_e32 v155, v155
	v_and_b32_e32 v157, 0x7fffffff, v107
	v_cndmask_b32_e32 v149, v149, v151, vcc
	v_pk_fma_f32 v[150:151], v[152:153], s[70:71], v[206:207] op_sel_hi:[1,0,0]
	v_and_b32_e32 v156, 0x7fffffff, v106
	v_pk_fma_f32 v[150:151], v[152:153], v[150:151], s[74:75] op_sel_hi:[1,1,0]
	v_pk_fma_f32 v[156:157], v[156:157], s[68:69], 1.0 op_sel_hi:[1,0,0]
	v_pk_fma_f32 v[150:151], v[152:153], v[150:151], s[76:77] op_sel_hi:[1,1,0]
	v_rcp_f32_e32 v156, v156
	v_pk_fma_f32 v[150:151], v[152:153], v[150:151], s[78:79] op_sel_hi:[1,1,0]
	v_rcp_f32_e32 v157, v157
	v_pk_mul_f32 v[150:151], v[152:153], v[150:151]
	v_cmp_gt_f32_e32 vcc, 0, v104
	v_pk_mul_f32 v[150:151], v[154:155], v[150:151]
	v_pk_mul_f32 v[152:153], v[106:107], v[106:107]
	v_pk_mul_f32 v[154:155], v[104:105], v[150:151]
	v_pk_fma_f32 v[150:151], v[104:105], v[150:151], v[104:105] neg_lo:[1,0,0] neg_hi:[1,0,0]
	v_pk_mul_f32 v[152:153], v[152:153], s[80:81] op_sel_hi:[1,0]
	v_cndmask_b32_e32 v150, v150, v154, vcc
	v_cmp_gt_f32_e32 vcc, 0, v105
	v_exp_f32_e32 v152, v152
	v_exp_f32_e32 v153, v153
	v_cndmask_b32_e32 v151, v151, v155, vcc
	v_pk_fma_f32 v[154:155], v[156:157], s[70:71], v[206:207] op_sel_hi:[1,0,0]
	v_cmp_gt_f32_e32 vcc, 0, v106
	v_pk_fma_f32 v[154:155], v[156:157], v[154:155], s[74:75] op_sel_hi:[1,1,0]
	v_pk_mul_f32 v[158:159], v[100:101], v[100:101]
	v_pk_fma_f32 v[154:155], v[156:157], v[154:155], s[76:77] op_sel_hi:[1,1,0]
	v_pk_mul_f32 v[158:159], v[158:159], s[80:81] op_sel_hi:[1,0]
	v_pk_fma_f32 v[154:155], v[156:157], v[154:155], s[78:79] op_sel_hi:[1,1,0]
	v_exp_f32_e32 v158, v158
	v_pk_mul_f32 v[154:155], v[156:157], v[154:155]
	v_and_b32_e32 v157, 0x7fffffff, v101
	v_and_b32_e32 v156, 0x7fffffff, v100
	v_pk_fma_f32 v[156:157], v[156:157], s[68:69], 1.0 op_sel_hi:[1,0,0]
	v_pk_mul_f32 v[152:153], v[152:153], v[154:155]
	v_rcp_f32_e32 v156, v156
	v_rcp_f32_e32 v157, v157
	v_pk_mul_f32 v[154:155], v[106:107], v[152:153]
	v_pk_fma_f32 v[152:153], v[106:107], v[152:153], v[106:107] neg_lo:[1,0,0] neg_hi:[1,0,0]
	v_exp_f32_e32 v159, v159
	v_cndmask_b32_e32 v152, v152, v154, vcc
	v_cmp_gt_f32_e32 vcc, 0, v107
	v_and_b32_e32 v209, 0x7fffffff, v103
	v_and_b32_e32 v208, 0x7fffffff, v102
	v_cndmask_b32_e32 v153, v153, v155, vcc
	v_pk_fma_f32 v[154:155], v[156:157], s[70:71], v[206:207] op_sel_hi:[1,0,0]
	v_pk_fma_f32 v[208:209], v[208:209], s[68:69], 1.0 op_sel_hi:[1,0,0]
	v_pk_fma_f32 v[154:155], v[156:157], v[154:155], s[74:75] op_sel_hi:[1,1,0]
	v_rcp_f32_e32 v208, v208
	v_pk_fma_f32 v[154:155], v[156:157], v[154:155], s[76:77] op_sel_hi:[1,1,0]
	v_rcp_f32_e32 v209, v209
	v_pk_fma_f32 v[154:155], v[156:157], v[154:155], s[78:79] op_sel_hi:[1,1,0]
	v_cmp_gt_f32_e32 vcc, 0, v100
	v_pk_mul_f32 v[154:155], v[156:157], v[154:155]
	v_pk_mul_f32 v[156:157], v[102:103], v[102:103]
	v_pk_mul_f32 v[154:155], v[158:159], v[154:155]
	v_pk_mul_f32 v[156:157], v[156:157], s[80:81] op_sel_hi:[1,0]
	v_pk_mul_f32 v[158:159], v[100:101], v[154:155]
	v_pk_fma_f32 v[154:155], v[100:101], v[154:155], v[100:101] neg_lo:[1,0,0] neg_hi:[1,0,0]
	v_exp_f32_e32 v156, v156
	v_cndmask_b32_e32 v154, v154, v158, vcc
	v_cmp_gt_f32_e32 vcc, 0, v101
	v_exp_f32_e32 v157, v157
	v_and_b32_e32 v213, 0x7fffffff, v99
	v_cndmask_b32_e32 v155, v155, v159, vcc
	v_pk_fma_f32 v[158:159], v[208:209], s[70:71], v[206:207] op_sel_hi:[1,0,0]
	v_cmp_gt_f32_e32 vcc, 0, v102
	v_pk_fma_f32 v[158:159], v[208:209], v[158:159], s[74:75] op_sel_hi:[1,1,0]
	v_and_b32_e32 v212, 0x7fffffff, v98
	v_pk_fma_f32 v[158:159], v[208:209], v[158:159], s[76:77] op_sel_hi:[1,1,0]
	v_pk_fma_f32 v[212:213], v[212:213], s[68:69], 1.0 op_sel_hi:[1,0,0]
	v_pk_fma_f32 v[158:159], v[208:209], v[158:159], s[78:79] op_sel_hi:[1,1,0]
	v_rcp_f32_e32 v212, v212
	v_pk_mul_f32 v[158:159], v[208:209], v[158:159]
	v_and_b32_e32 v209, 0x7fffffff, v97
	v_and_b32_e32 v208, 0x7fffffff, v96
	v_pk_fma_f32 v[208:209], v[208:209], s[68:69], 1.0 op_sel_hi:[1,0,0]
	v_pk_mul_f32 v[156:157], v[156:157], v[158:159]
	v_rcp_f32_e32 v208, v208
	v_rcp_f32_e32 v209, v209
	v_pk_mul_f32 v[158:159], v[102:103], v[156:157]
	v_pk_fma_f32 v[156:157], v[102:103], v[156:157], v[102:103] neg_lo:[1,0,0] neg_hi:[1,0,0]
	v_rcp_f32_e32 v213, v213
	v_cndmask_b32_e32 v156, v156, v158, vcc
	v_cmp_gt_f32_e32 vcc, 0, v103
	v_add_f32_e32 v184, 0, v146
	v_pk_mul_f32 v[210:211], v[96:97], v[96:97]
	v_cndmask_b32_e32 v157, v157, v159, vcc
	v_pk_fma_f32 v[158:159], v[208:209], s[70:71], v[206:207] op_sel_hi:[1,0,0]
	v_add_f32_e32 v184, v147, v184
	v_pk_fma_f32 v[158:159], v[208:209], v[158:159], s[74:75] op_sel_hi:[1,1,0]
	v_pk_mul_f32 v[210:211], v[210:211], s[80:81] op_sel_hi:[1,0]
	v_pk_fma_f32 v[158:159], v[208:209], v[158:159], s[76:77] op_sel_hi:[1,1,0]
	v_add_f32_e32 v184, v148, v184
	v_pk_fma_f32 v[158:159], v[208:209], v[158:159], s[78:79] op_sel_hi:[1,1,0]
	v_exp_f32_e32 v210, v210
	v_exp_f32_e32 v211, v211
	v_pk_mul_f32 v[158:159], v[208:209], v[158:159]
	v_pk_mul_f32 v[208:209], v[98:99], v[98:99]
	v_mul_f32_e32 v205, v147, v147
	v_add_f32_e32 v184, v149, v184
	v_pk_fma_f32 v[206:207], v[212:213], s[70:71], v[206:207] op_sel_hi:[1,0,0]
	v_pk_mul_f32 v[208:209], v[208:209], s[80:81] op_sel_hi:[1,0]
	v_fmac_f32_e32 v205, v146, v146
	v_add_f32_e32 v184, v150, v184
	v_pk_fma_f32 v[206:207], v[212:213], v[206:207], s[74:75] op_sel_hi:[1,1,0]
	v_exp_f32_e32 v208, v208
	v_exp_f32_e32 v209, v209
	v_fmac_f32_e32 v205, v148, v148
	v_add_f32_e32 v184, v151, v184
	v_pk_fma_f32 v[206:207], v[212:213], v[206:207], s[76:77] op_sel_hi:[1,1,0]
	v_fmac_f32_e32 v205, v149, v149
	v_add_f32_e32 v184, v152, v184
	v_pk_mul_f32 v[158:159], v[210:211], v[158:159]
	v_pk_fma_f32 v[206:207], v[212:213], v[206:207], s[78:79] op_sel_hi:[1,1,0]
	v_fmac_f32_e32 v205, v150, v150
	v_add_f32_e32 v184, v153, v184
	v_pk_mul_f32 v[210:211], v[96:97], v[158:159]
	v_pk_fma_f32 v[158:159], v[96:97], v[158:159], v[96:97] neg_lo:[1,0,0] neg_hi:[1,0,0]
	v_cmp_gt_f32_e32 vcc, 0, v96
	v_pk_mul_f32 v[206:207], v[212:213], v[206:207]
	v_fmac_f32_e32 v205, v151, v151
	v_add_f32_e32 v184, v154, v184
	v_cndmask_b32_e32 v158, v158, v210, vcc
	v_cmp_gt_f32_e32 vcc, 0, v97
	v_pk_mul_f32 v[206:207], v[208:209], v[206:207]
	v_fmac_f32_e32 v205, v152, v152
	v_add_f32_e32 v184, v155, v184
	v_cndmask_b32_e32 v159, v159, v211, vcc
	v_pk_mul_f32 v[208:209], v[98:99], v[206:207]
	v_pk_fma_f32 v[206:207], v[98:99], v[206:207], v[98:99] neg_lo:[1,0,0] neg_hi:[1,0,0]
	v_cmp_gt_f32_e32 vcc, 0, v98
	v_fmac_f32_e32 v205, v153, v153
	v_add_f32_e32 v184, v156, v184
	v_cndmask_b32_e32 v206, v206, v208, vcc
	v_fmac_f32_e32 v205, v154, v154
	v_add_f32_e32 v184, v157, v184
	v_cmp_gt_f32_e32 vcc, 0, v99
	v_fmac_f32_e32 v205, v155, v155
	v_add_f32_e32 v184, v158, v184
	v_cndmask_b32_e32 v207, v207, v209, vcc
	v_fmac_f32_e32 v205, v156, v156
	v_add_f32_e32 v184, v159, v184
	v_fmac_f32_e32 v205, v157, v157
	v_add_f32_e32 v184, v206, v184
	v_add_f32_e32 v184, v207, v184
	v_fmac_f32_e32 v205, v158, v158
	v_mov_b32_e32 v209, v184
	s_nop 1
	v_permlane16_swap_b32_e32 v184, v209
	s_nop 1
	v_fmac_f32_e32 v205, v159, v159
	v_fmac_f32_e32 v205, v206, v206
	v_fmac_f32_e32 v205, v207, v207
	v_mov_b32_e32 v210, v205
	s_nop 1
	v_permlane16_swap_b32_e32 v205, v210
	s_nop 1
	s_waitcnt lgkmcnt(1)
	v_add_f32_e32 v184, v184, v209
	v_xor_b32_e32 v209, 32, v229
	s_waitcnt lgkmcnt(0)
	v_add_f32_e32 v205, v205, v210
	v_mov_b32_e32 v199, v184
	s_nop 1
	v_permlane32_swap_b32_e32 v184, v199
	s_nop 1
	v_mov_b32_e32 v208, v205
	s_nop 1
	v_permlane32_swap_b32_e32 v205, v208
	s_nop 1
	s_and_saveexec_b64 s[12:13], s[4:5]
	s_cbranch_execz .LBB0_579
	v_lshlrev_b64 v[210:211], 2, v[144:145]
	v_lshl_add_u64 v[212:213], s[14:15], 0, v[210:211]
	v_lshl_add_u64 v[210:211], s[52:53], 0, v[210:211]
	s_waitcnt lgkmcnt(1)
	v_add_f32_e32 v184, v184, v199
	s_waitcnt lgkmcnt(0)
	v_add_f32_e32 v199, v205, v208
	global_atomic_add_f32 v[210:211], v184, off
	global_atomic_add_f32 v[212:213], v199, off

.LBB0_585:
	v_fmamk_f32 v184, v239, 0x3a800000, v228
	v_rsq_f32_e32 v184, v184
	v_or_b32_e32 v204, 32, v198
	v_ashrrev_i32_e32 v205, 31, v204
	s_and_b64 vcc, exec, s[10:11]
	v_pk_fma_f32 v[174:175], v[174:175], v[184:185], v[46:47] op_sel_hi:[1,0,1]
	v_pk_fma_f32 v[172:173], v[172:173], v[184:185], v[44:45] op_sel_hi:[1,0,1]
	v_pk_fma_f32 v[170:171], v[170:171], v[184:185], v[42:43] op_sel_hi:[1,0,1]
	v_pk_fma_f32 v[168:169], v[168:169], v[184:185], v[40:41] op_sel_hi:[1,0,1]
	v_pk_fma_f32 v[166:167], v[166:167], v[184:185], v[38:39] op_sel_hi:[1,0,1]
	v_pk_fma_f32 v[164:165], v[164:165], v[184:185], v[36:37] op_sel_hi:[1,0,1]
	v_pk_fma_f32 v[162:163], v[162:163], v[184:185], v[34:35] op_sel_hi:[1,0,1]
	v_pk_fma_f32 v[160:161], v[160:161], v[184:185], v[32:33] op_sel_hi:[1,0,1]
	s_mov_b64 s[90:91], -1
	s_cbranch_vccnz .LBB0_591
	s_and_b64 vcc, exec, s[8:9]
	v_mov_b32_e32 v209, v175
	s_waitcnt lgkmcnt(0)
	v_mov_b32_e32 v208, v174
	v_mov_b32_e32 v207, v173
	v_mov_b32_e32 v206, v172
	v_mov_b32_e32 v213, v171
	v_mov_b32_e32 v212, v170
	v_mov_b32_e32 v211, v169
	v_mov_b32_e32 v210, v168
	v_mov_b32_e32 v217, v167
	v_mov_b32_e32 v216, v166
	v_mov_b32_e32 v215, v165
	v_mov_b32_e32 v214, v164
	v_mov_b32_e32 v221, v163
	v_mov_b32_e32 v220, v162
	v_mov_b32_e32 v219, v161
	v_mov_b32_e32 v218, v160
	s_cbranch_vccnz .LBB0_590
	v_and_b32_e32 v207, 0x7fffffff, v173
	v_and_b32_e32 v206, 0x7fffffff, v172
	v_pk_fma_f32 v[206:207], v[206:207], s[68:69], 1.0 op_sel_hi:[1,0,0]
	v_mov_b64_e32 v[220:221], s[72:73]
	v_rcp_f32_e32 v206, v206
	v_rcp_f32_e32 v207, v207
	v_pk_mul_f32 v[210:211], v[172:173], v[172:173]
	v_and_b32_e32 v213, 0x7fffffff, v175
	v_pk_mul_f32 v[210:211], v[210:211], s[80:81] op_sel_hi:[1,0]
	v_pk_fma_f32 v[208:209], v[206:207], s[70:71], v[220:221] op_sel_hi:[1,0,0]
	v_exp_f32_e32 v210, v210
	v_pk_fma_f32 v[208:209], v[206:207], v[208:209], s[74:75] op_sel_hi:[1,1,0]
	v_exp_f32_e32 v211, v211
	v_pk_fma_f32 v[208:209], v[206:207], v[208:209], s[76:77] op_sel_hi:[1,1,0]
	v_and_b32_e32 v212, 0x7fffffff, v174
	v_pk_fma_f32 v[208:209], v[206:207], v[208:209], s[78:79] op_sel_hi:[1,1,0]
	v_pk_fma_f32 v[212:213], v[212:213], s[68:69], 1.0 op_sel_hi:[1,0,0]
	v_pk_mul_f32 v[206:207], v[206:207], v[208:209]
	v_rcp_f32_e32 v212, v212
	v_rcp_f32_e32 v213, v213
	v_pk_mul_f32 v[206:207], v[210:211], v[206:207]
	v_cmp_gt_f32_e32 vcc, 0, v172
	v_pk_mul_f32 v[210:211], v[172:173], v[206:207]
	v_pk_fma_f32 v[206:207], v[172:173], v[206:207], v[172:173] neg_lo:[1,0,0] neg_hi:[1,0,0]
	v_pk_mul_f32 v[208:209], v[174:175], v[174:175]
	v_cndmask_b32_e32 v206, v206, v210, vcc
	v_cmp_gt_f32_e32 vcc, 0, v173
	v_pk_mul_f32 v[208:209], v[208:209], s[80:81] op_sel_hi:[1,0]
	v_pk_mul_f32 v[214:215], v[168:169], v[168:169]
	v_cndmask_b32_e32 v207, v207, v211, vcc
	v_pk_fma_f32 v[210:211], v[212:213], s[70:71], v[220:221] op_sel_hi:[1,0,0]
	v_exp_f32_e32 v208, v208
	v_pk_fma_f32 v[210:211], v[212:213], v[210:211], s[74:75] op_sel_hi:[1,1,0]
	v_exp_f32_e32 v209, v209
	v_pk_fma_f32 v[210:211], v[212:213], v[210:211], s[76:77] op_sel_hi:[1,1,0]
	v_cmp_gt_f32_e32 vcc, 0, v174
	v_pk_fma_f32 v[210:211], v[212:213], v[210:211], s[78:79] op_sel_hi:[1,1,0]
	v_pk_mul_f32 v[214:215], v[214:215], s[80:81] op_sel_hi:[1,0]
	v_pk_mul_f32 v[210:211], v[212:213], v[210:211]
	v_and_b32_e32 v213, 0x7fffffff, v169
	v_and_b32_e32 v212, 0x7fffffff, v168
	v_pk_fma_f32 v[212:213], v[212:213], s[68:69], 1.0 op_sel_hi:[1,0,0]
	v_pk_mul_f32 v[208:209], v[208:209], v[210:211]
	v_rcp_f32_e32 v212, v212
	v_rcp_f32_e32 v213, v213
	v_pk_mul_f32 v[210:211], v[174:175], v[208:209]
	v_pk_fma_f32 v[208:209], v[174:175], v[208:209], v[174:175] neg_lo:[1,0,0] neg_hi:[1,0,0]
	v_exp_f32_e32 v214, v214
	v_cndmask_b32_e32 v208, v208, v210, vcc
	v_cmp_gt_f32_e32 vcc, 0, v175
	v_exp_f32_e32 v215, v215
	v_and_b32_e32 v217, 0x7fffffff, v171
	v_cndmask_b32_e32 v209, v209, v211, vcc
	v_pk_fma_f32 v[210:211], v[212:213], s[70:71], v[220:221] op_sel_hi:[1,0,0]
	v_and_b32_e32 v216, 0x7fffffff, v170
	v_pk_fma_f32 v[210:211], v[212:213], v[210:211], s[74:75] op_sel_hi:[1,1,0]
	v_pk_fma_f32 v[216:217], v[216:217], s[68:69], 1.0 op_sel_hi:[1,0,0]
	v_pk_fma_f32 v[210:211], v[212:213], v[210:211], s[76:77] op_sel_hi:[1,1,0]
	v_rcp_f32_e32 v216, v216
	v_pk_fma_f32 v[210:211], v[212:213], v[210:211], s[78:79] op_sel_hi:[1,1,0]
	v_rcp_f32_e32 v217, v217
	v_pk_mul_f32 v[210:211], v[212:213], v[210:211]
	v_cmp_gt_f32_e32 vcc, 0, v168
	v_pk_mul_f32 v[210:211], v[214:215], v[210:211]
	v_pk_mul_f32 v[212:213], v[170:171], v[170:171]
	v_pk_mul_f32 v[214:215], v[168:169], v[210:211]
	v_pk_fma_f32 v[210:211], v[168:169], v[210:211], v[168:169] neg_lo:[1,0,0] neg_hi:[1,0,0]
	v_pk_mul_f32 v[212:213], v[212:213], s[80:81] op_sel_hi:[1,0]
	v_cndmask_b32_e32 v210, v210, v214, vcc
	v_cmp_gt_f32_e32 vcc, 0, v169
	v_exp_f32_e32 v212, v212
	v_exp_f32_e32 v213, v213
	v_cndmask_b32_e32 v211, v211, v215, vcc
	v_pk_fma_f32 v[214:215], v[216:217], s[70:71], v[220:221] op_sel_hi:[1,0,0]
	v_cmp_gt_f32_e32 vcc, 0, v170
	v_pk_fma_f32 v[214:215], v[216:217], v[214:215], s[74:75] op_sel_hi:[1,1,0]
	v_pk_mul_f32 v[218:219], v[164:165], v[164:165]
	v_pk_fma_f32 v[214:215], v[216:217], v[214:215], s[76:77] op_sel_hi:[1,1,0]
	v_pk_mul_f32 v[218:219], v[218:219], s[80:81] op_sel_hi:[1,0]
	v_pk_fma_f32 v[214:215], v[216:217], v[214:215], s[78:79] op_sel_hi:[1,1,0]
	v_exp_f32_e32 v218, v218
	v_pk_mul_f32 v[214:215], v[216:217], v[214:215]
	v_and_b32_e32 v217, 0x7fffffff, v165
	v_and_b32_e32 v216, 0x7fffffff, v164
	v_pk_fma_f32 v[216:217], v[216:217], s[68:69], 1.0 op_sel_hi:[1,0,0]
	v_pk_mul_f32 v[212:213], v[212:213], v[214:215]
	v_rcp_f32_e32 v216, v216
	v_rcp_f32_e32 v217, v217
	v_pk_mul_f32 v[214:215], v[170:171], v[212:213]
	v_pk_fma_f32 v[212:213], v[170:171], v[212:213], v[170:171] neg_lo:[1,0,0] neg_hi:[1,0,0]
	v_exp_f32_e32 v219, v219
	v_cndmask_b32_e32 v212, v212, v214, vcc
	v_cmp_gt_f32_e32 vcc, 0, v171
	v_and_b32_e32 v241, 0x7fffffff, v167
	v_and_b32_e32 v240, 0x7fffffff, v166
	v_cndmask_b32_e32 v213, v213, v215, vcc
	v_pk_fma_f32 v[214:215], v[216:217], s[70:71], v[220:221] op_sel_hi:[1,0,0]
	v_pk_fma_f32 v[240:241], v[240:241], s[68:69], 1.0 op_sel_hi:[1,0,0]
	v_pk_fma_f32 v[214:215], v[216:217], v[214:215], s[74:75] op_sel_hi:[1,1,0]
	v_rcp_f32_e32 v240, v240
	v_pk_fma_f32 v[214:215], v[216:217], v[214:215], s[76:77] op_sel_hi:[1,1,0]
	v_rcp_f32_e32 v241, v241
	v_pk_fma_f32 v[214:215], v[216:217], v[214:215], s[78:79] op_sel_hi:[1,1,0]
	v_cmp_gt_f32_e32 vcc, 0, v164
	v_pk_mul_f32 v[214:215], v[216:217], v[214:215]
	v_pk_mul_f32 v[216:217], v[166:167], v[166:167]
	v_pk_mul_f32 v[214:215], v[218:219], v[214:215]
	v_pk_mul_f32 v[216:217], v[216:217], s[80:81] op_sel_hi:[1,0]
	v_pk_mul_f32 v[218:219], v[164:165], v[214:215]
	v_pk_fma_f32 v[214:215], v[164:165], v[214:215], v[164:165] neg_lo:[1,0,0] neg_hi:[1,0,0]
	v_exp_f32_e32 v216, v216
	v_cndmask_b32_e32 v214, v214, v218, vcc
	v_cmp_gt_f32_e32 vcc, 0, v165
	v_exp_f32_e32 v217, v217
	v_and_b32_e32 v245, 0x7fffffff, v163
	v_cndmask_b32_e32 v215, v215, v219, vcc
	v_pk_fma_f32 v[218:219], v[240:241], s[70:71], v[220:221] op_sel_hi:[1,0,0]
	v_cmp_gt_f32_e32 vcc, 0, v166
	v_pk_fma_f32 v[218:219], v[240:241], v[218:219], s[74:75] op_sel_hi:[1,1,0]
	v_and_b32_e32 v244, 0x7fffffff, v162
	v_pk_fma_f32 v[218:219], v[240:241], v[218:219], s[76:77] op_sel_hi:[1,1,0]
	v_pk_fma_f32 v[244:245], v[244:245], s[68:69], 1.0 op_sel_hi:[1,0,0]
	v_pk_fma_f32 v[218:219], v[240:241], v[218:219], s[78:79] op_sel_hi:[1,1,0]
	v_add_f32_e32 v184, 0, v206
	v_pk_mul_f32 v[218:219], v[240:241], v[218:219]
	v_and_b32_e32 v241, 0x7fffffff, v161
	v_and_b32_e32 v240, 0x7fffffff, v160
	v_pk_fma_f32 v[240:241], v[240:241], s[68:69], 1.0 op_sel_hi:[1,0,0]
	v_pk_mul_f32 v[216:217], v[216:217], v[218:219]
	v_rcp_f32_e32 v240, v240
	v_rcp_f32_e32 v241, v241
	v_pk_mul_f32 v[218:219], v[166:167], v[216:217]
	v_pk_fma_f32 v[216:217], v[166:167], v[216:217], v[166:167] neg_lo:[1,0,0] neg_hi:[1,0,0]
	v_rcp_f32_e32 v244, v244
	v_cndmask_b32_e32 v216, v216, v218, vcc
	v_cmp_gt_f32_e32 vcc, 0, v167
	v_rcp_f32_e32 v245, v245
	v_add_f32_e32 v184, v207, v184
	v_cndmask_b32_e32 v217, v217, v219, vcc
	v_pk_fma_f32 v[218:219], v[240:241], s[70:71], v[220:221] op_sel_hi:[1,0,0]
	v_pk_mul_f32 v[242:243], v[160:161], v[160:161]
	v_pk_fma_f32 v[218:219], v[240:241], v[218:219], s[74:75] op_sel_hi:[1,1,0]
	v_add_f32_e32 v184, v208, v184
	v_pk_fma_f32 v[218:219], v[240:241], v[218:219], s[76:77] op_sel_hi:[1,1,0]
	v_pk_mul_f32 v[242:243], v[242:243], s[80:81] op_sel_hi:[1,0]
	v_pk_fma_f32 v[218:219], v[240:241], v[218:219], s[78:79] op_sel_hi:[1,1,0]
	v_mul_f32_e32 v231, v207, v207
	v_add_f32_e32 v184, v209, v184
	v_exp_f32_e32 v242, v242
	v_exp_f32_e32 v243, v243
	v_pk_mul_f32 v[218:219], v[240:241], v[218:219]
	v_pk_mul_f32 v[240:241], v[162:163], v[162:163]
	v_fmac_f32_e32 v231, v206, v206
	v_add_f32_e32 v184, v210, v184
	v_pk_fma_f32 v[220:221], v[244:245], s[70:71], v[220:221] op_sel_hi:[1,0,0]
	v_pk_mul_f32 v[240:241], v[240:241], s[80:81] op_sel_hi:[1,0]
	v_fmac_f32_e32 v231, v208, v208
	v_add_f32_e32 v184, v211, v184
	v_pk_fma_f32 v[220:221], v[244:245], v[220:221], s[74:75] op_sel_hi:[1,1,0]
	v_exp_f32_e32 v240, v240
	v_exp_f32_e32 v241, v241
	v_fmac_f32_e32 v231, v209, v209
	v_add_f32_e32 v184, v212, v184
	v_pk_fma_f32 v[220:221], v[244:245], v[220:221], s[76:77] op_sel_hi:[1,1,0]
	v_fmac_f32_e32 v231, v210, v210
	v_add_f32_e32 v184, v213, v184
	v_pk_mul_f32 v[218:219], v[242:243], v[218:219]
	v_pk_fma_f32 v[220:221], v[244:245], v[220:221], s[78:79] op_sel_hi:[1,1,0]
	v_fmac_f32_e32 v231, v211, v211
	v_add_f32_e32 v184, v214, v184
	v_pk_mul_f32 v[242:243], v[160:161], v[218:219]
	v_pk_fma_f32 v[218:219], v[160:161], v[218:219], v[160:161] neg_lo:[1,0,0] neg_hi:[1,0,0]
	v_cmp_gt_f32_e32 vcc, 0, v160
	v_pk_mul_f32 v[220:221], v[244:245], v[220:221]
	v_fmac_f32_e32 v231, v212, v212
	v_add_f32_e32 v184, v215, v184
	v_cndmask_b32_e32 v218, v218, v242, vcc
	v_cmp_gt_f32_e32 vcc, 0, v161
	v_pk_mul_f32 v[220:221], v[240:241], v[220:221]
	v_fmac_f32_e32 v231, v213, v213
	v_add_f32_e32 v184, v216, v184
	v_cndmask_b32_e32 v219, v219, v243, vcc
	v_pk_mul_f32 v[240:241], v[162:163], v[220:221]
	v_pk_fma_f32 v[220:221], v[162:163], v[220:221], v[162:163] neg_lo:[1,0,0] neg_hi:[1,0,0]
	v_cmp_gt_f32_e32 vcc, 0, v162
	v_fmac_f32_e32 v231, v214, v214
	v_add_f32_e32 v184, v217, v184
	v_cndmask_b32_e32 v220, v220, v240, vcc
	v_cmp_gt_f32_e32 vcc, 0, v163
	v_fmac_f32_e32 v231, v215, v215
	v_add_f32_e32 v184, v218, v184
	v_cndmask_b32_e32 v221, v221, v241, vcc
	v_fmac_f32_e32 v231, v216, v216
	v_add_f32_e32 v184, v219, v184
	v_fmac_f32_e32 v231, v217, v217
	v_add_f32_e32 v184, v220, v184
	v_add_f32_e32 v184, v221, v184
	v_fmac_f32_e32 v231, v218, v218
	v_mov_b32_e32 v240, v184
	s_nop 1
	v_permlane16_swap_b32_e32 v184, v240
	s_nop 1
	v_fmac_f32_e32 v231, v219, v219
	v_fmac_f32_e32 v231, v220, v220
	v_fmac_f32_e32 v231, v221, v221
	v_mov_b32_e32 v241, v231
	s_nop 1
	v_permlane16_swap_b32_e32 v231, v241
	s_nop 1
	s_waitcnt lgkmcnt(1)
	v_add_f32_e32 v184, v184, v240
	v_xor_b32_e32 v240, 32, v229
	s_waitcnt lgkmcnt(0)
	v_add_f32_e32 v231, v231, v241
	v_mov_b32_e32 v199, v184
	s_nop 1
	v_permlane32_swap_b32_e32 v184, v199
	s_nop 1
	v_mov_b32_e32 v239, v231
	s_nop 1
	v_permlane32_swap_b32_e32 v231, v239
	s_nop 1
	s_and_saveexec_b64 s[90:91], s[4:5]
	s_cbranch_execz .LBB0_589
	v_lshlrev_b64 v[240:241], 2, v[204:205]
	v_lshl_add_u64 v[242:243], s[14:15], 0, v[240:241]
	v_lshl_add_u64 v[240:241], s[52:53], 0, v[240:241]
	s_waitcnt lgkmcnt(1)
	v_add_f32_e32 v184, v184, v199
	s_waitcnt lgkmcnt(0)
	v_add_f32_e32 v199, v231, v239
	global_atomic_add_f32 v[240:241], v184, off
	global_atomic_add_f32 v[242:243], v199, off

.LBB0_593:
	v_lshlrev_b64 v[162:163], 11, v[204:205]
	v_lshl_add_u64 v[166:167], v[202:203], 0, v[162:163]
	v_cvt_pk_bf16_f32 v162, v206, v207
	s_waitcnt lgkmcnt(0)
	v_cvt_pk_bf16_f32 v163, v208, v209
	v_cvt_pk_bf16_f32 v164, v210, v211
	v_cvt_pk_bf16_f32 v165, v212, v213
	global_store_dwordx4 v[166:167], v[162:165], off
	v_or_b32_e32 v160, 48, v198
	v_ashrrev_i32_e32 v161, 31, v160
	v_fmamk_f32 v164, v238, 0x3a800000, v228
	v_rsq_f32_e32 v168, v164
	v_cvt_pk_bf16_f32 v162, v214, v215
	v_cvt_pk_bf16_f32 v163, v216, v217
	v_cvt_pk_bf16_f32 v164, v218, v219
	v_cvt_pk_bf16_f32 v165, v220, v221
	s_and_b64 vcc, exec, s[10:11]
	v_pk_fma_f32 v[142:143], v[142:143], v[168:169], v[46:47] op_sel_hi:[1,0,1]
	v_pk_fma_f32 v[140:141], v[140:141], v[168:169], v[44:45] op_sel_hi:[1,0,1]
	v_pk_fma_f32 v[138:139], v[138:139], v[168:169], v[42:43] op_sel_hi:[1,0,1]
	v_pk_fma_f32 v[136:137], v[136:137], v[168:169], v[40:41] op_sel_hi:[1,0,1]
	v_pk_fma_f32 v[134:135], v[134:135], v[168:169], v[38:39] op_sel_hi:[1,0,1]
	v_pk_fma_f32 v[132:133], v[132:133], v[168:169], v[36:37] op_sel_hi:[1,0,1]
	v_pk_fma_f32 v[130:131], v[130:131], v[168:169], v[34:35] op_sel_hi:[1,0,1]
	v_pk_fma_f32 v[128:129], v[128:129], v[168:169], v[32:33] op_sel_hi:[1,0,1]
	s_mov_b64 s[90:91], -1
	global_store_dwordx4 v[166:167], v[162:165], off offset:256
	s_cbranch_vccnz .LBB0_599
	s_and_b64 vcc, exec, s[8:9]
	v_mov_b32_e32 v165, v143
	v_mov_b32_e32 v164, v142
	v_mov_b32_e32 v163, v141
	v_mov_b32_e32 v162, v140
	v_mov_b32_e32 v169, v139
	v_mov_b32_e32 v168, v138
	v_mov_b32_e32 v167, v137
	v_mov_b32_e32 v166, v136
	v_mov_b32_e32 v173, v135
	v_mov_b32_e32 v172, v134
	v_mov_b32_e32 v171, v133
	v_mov_b32_e32 v170, v132
	v_mov_b32_e32 v205, v131
	v_mov_b32_e32 v204, v130
	v_mov_b32_e32 v175, v129
	v_mov_b32_e32 v174, v128
	s_cbranch_vccnz .LBB0_598
	v_and_b32_e32 v163, 0x7fffffff, v141
	v_and_b32_e32 v162, 0x7fffffff, v140
	v_pk_fma_f32 v[162:163], v[162:163], s[68:69], 1.0 op_sel_hi:[1,0,0]
	v_mov_b64_e32 v[204:205], s[72:73]
	v_rcp_f32_e32 v162, v162
	v_rcp_f32_e32 v163, v163
	v_pk_mul_f32 v[166:167], v[140:141], v[140:141]
	v_and_b32_e32 v169, 0x7fffffff, v143
	v_pk_mul_f32 v[166:167], v[166:167], s[80:81] op_sel_hi:[1,0]
	v_pk_fma_f32 v[164:165], v[162:163], s[70:71], v[204:205] op_sel_hi:[1,0,0]
	v_exp_f32_e32 v166, v166
	v_pk_fma_f32 v[164:165], v[162:163], v[164:165], s[74:75] op_sel_hi:[1,1,0]
	v_exp_f32_e32 v167, v167
	v_pk_fma_f32 v[164:165], v[162:163], v[164:165], s[76:77] op_sel_hi:[1,1,0]
	v_and_b32_e32 v168, 0x7fffffff, v142
	v_pk_fma_f32 v[164:165], v[162:163], v[164:165], s[78:79] op_sel_hi:[1,1,0]
	v_pk_fma_f32 v[168:169], v[168:169], s[68:69], 1.0 op_sel_hi:[1,0,0]
	v_pk_mul_f32 v[162:163], v[162:163], v[164:165]
	v_rcp_f32_e32 v168, v168
	v_rcp_f32_e32 v169, v169
	v_pk_mul_f32 v[162:163], v[166:167], v[162:163]
	v_cmp_gt_f32_e32 vcc, 0, v140
	v_pk_mul_f32 v[166:167], v[140:141], v[162:163]
	v_pk_fma_f32 v[162:163], v[140:141], v[162:163], v[140:141] neg_lo:[1,0,0] neg_hi:[1,0,0]
	v_pk_mul_f32 v[164:165], v[142:143], v[142:143]
	v_cndmask_b32_e32 v162, v162, v166, vcc
	v_cmp_gt_f32_e32 vcc, 0, v141
	v_pk_mul_f32 v[164:165], v[164:165], s[80:81] op_sel_hi:[1,0]
	v_pk_mul_f32 v[170:171], v[136:137], v[136:137]
	v_cndmask_b32_e32 v163, v163, v167, vcc
	v_pk_fma_f32 v[166:167], v[168:169], s[70:71], v[204:205] op_sel_hi:[1,0,0]
	v_exp_f32_e32 v164, v164
	v_pk_fma_f32 v[166:167], v[168:169], v[166:167], s[74:75] op_sel_hi:[1,1,0]
	v_exp_f32_e32 v165, v165
	v_pk_fma_f32 v[166:167], v[168:169], v[166:167], s[76:77] op_sel_hi:[1,1,0]
	v_cmp_gt_f32_e32 vcc, 0, v142
	v_pk_fma_f32 v[166:167], v[168:169], v[166:167], s[78:79] op_sel_hi:[1,1,0]
	v_pk_mul_f32 v[170:171], v[170:171], s[80:81] op_sel_hi:[1,0]
	v_pk_mul_f32 v[166:167], v[168:169], v[166:167]
	v_and_b32_e32 v169, 0x7fffffff, v137
	v_and_b32_e32 v168, 0x7fffffff, v136
	v_pk_fma_f32 v[168:169], v[168:169], s[68:69], 1.0 op_sel_hi:[1,0,0]
	v_pk_mul_f32 v[164:165], v[164:165], v[166:167]
	v_rcp_f32_e32 v168, v168
	v_rcp_f32_e32 v169, v169
	v_pk_mul_f32 v[166:167], v[142:143], v[164:165]
	v_pk_fma_f32 v[164:165], v[142:143], v[164:165], v[142:143] neg_lo:[1,0,0] neg_hi:[1,0,0]
	v_exp_f32_e32 v170, v170
	v_cndmask_b32_e32 v164, v164, v166, vcc
	v_cmp_gt_f32_e32 vcc, 0, v143
	v_exp_f32_e32 v171, v171
	v_and_b32_e32 v173, 0x7fffffff, v139
	v_cndmask_b32_e32 v165, v165, v167, vcc
	v_pk_fma_f32 v[166:167], v[168:169], s[70:71], v[204:205] op_sel_hi:[1,0,0]
	v_and_b32_e32 v172, 0x7fffffff, v138
	v_pk_fma_f32 v[166:167], v[168:169], v[166:167], s[74:75] op_sel_hi:[1,1,0]
	v_pk_fma_f32 v[172:173], v[172:173], s[68:69], 1.0 op_sel_hi:[1,0,0]
	v_pk_fma_f32 v[166:167], v[168:169], v[166:167], s[76:77] op_sel_hi:[1,1,0]
	v_rcp_f32_e32 v172, v172
	v_pk_fma_f32 v[166:167], v[168:169], v[166:167], s[78:79] op_sel_hi:[1,1,0]
	v_rcp_f32_e32 v173, v173
	v_pk_mul_f32 v[166:167], v[168:169], v[166:167]
	v_cmp_gt_f32_e32 vcc, 0, v136
	v_pk_mul_f32 v[166:167], v[170:171], v[166:167]
	v_pk_mul_f32 v[168:169], v[138:139], v[138:139]
	v_pk_mul_f32 v[170:171], v[136:137], v[166:167]
	v_pk_fma_f32 v[166:167], v[136:137], v[166:167], v[136:137] neg_lo:[1,0,0] neg_hi:[1,0,0]
	v_pk_mul_f32 v[168:169], v[168:169], s[80:81] op_sel_hi:[1,0]
	v_cndmask_b32_e32 v166, v166, v170, vcc
	v_cmp_gt_f32_e32 vcc, 0, v137
	v_exp_f32_e32 v168, v168
	v_exp_f32_e32 v169, v169
	v_cndmask_b32_e32 v167, v167, v171, vcc
	v_pk_fma_f32 v[170:171], v[172:173], s[70:71], v[204:205] op_sel_hi:[1,0,0]
	v_cmp_gt_f32_e32 vcc, 0, v138
	v_pk_fma_f32 v[170:171], v[172:173], v[170:171], s[74:75] op_sel_hi:[1,1,0]
	v_pk_mul_f32 v[174:175], v[132:133], v[132:133]
	v_pk_fma_f32 v[170:171], v[172:173], v[170:171], s[76:77] op_sel_hi:[1,1,0]
	v_pk_mul_f32 v[174:175], v[174:175], s[80:81] op_sel_hi:[1,0]
	v_pk_fma_f32 v[170:171], v[172:173], v[170:171], s[78:79] op_sel_hi:[1,1,0]
	v_exp_f32_e32 v174, v174
	v_pk_mul_f32 v[170:171], v[172:173], v[170:171]
	v_and_b32_e32 v173, 0x7fffffff, v133
	v_and_b32_e32 v172, 0x7fffffff, v132
	v_pk_fma_f32 v[172:173], v[172:173], s[68:69], 1.0 op_sel_hi:[1,0,0]
	v_pk_mul_f32 v[168:169], v[168:169], v[170:171]
	v_rcp_f32_e32 v172, v172
	v_rcp_f32_e32 v173, v173
	v_pk_mul_f32 v[170:171], v[138:139], v[168:169]
	v_pk_fma_f32 v[168:169], v[138:139], v[168:169], v[138:139] neg_lo:[1,0,0] neg_hi:[1,0,0]
	v_exp_f32_e32 v175, v175
	v_cndmask_b32_e32 v168, v168, v170, vcc
	v_cmp_gt_f32_e32 vcc, 0, v139
	v_and_b32_e32 v207, 0x7fffffff, v135
	v_and_b32_e32 v206, 0x7fffffff, v134
	v_cndmask_b32_e32 v169, v169, v171, vcc
	v_pk_fma_f32 v[170:171], v[172:173], s[70:71], v[204:205] op_sel_hi:[1,0,0]
	v_pk_fma_f32 v[206:207], v[206:207], s[68:69], 1.0 op_sel_hi:[1,0,0]
	v_pk_fma_f32 v[170:171], v[172:173], v[170:171], s[74:75] op_sel_hi:[1,1,0]
	v_rcp_f32_e32 v206, v206
	v_pk_fma_f32 v[170:171], v[172:173], v[170:171], s[76:77] op_sel_hi:[1,1,0]
	v_rcp_f32_e32 v207, v207
	v_pk_fma_f32 v[170:171], v[172:173], v[170:171], s[78:79] op_sel_hi:[1,1,0]
	v_cmp_gt_f32_e32 vcc, 0, v132
	v_pk_mul_f32 v[170:171], v[172:173], v[170:171]
	v_pk_mul_f32 v[172:173], v[134:135], v[134:135]
	v_pk_mul_f32 v[170:171], v[174:175], v[170:171]
	v_pk_mul_f32 v[172:173], v[172:173], s[80:81] op_sel_hi:[1,0]
	v_pk_mul_f32 v[174:175], v[132:133], v[170:171]
	v_pk_fma_f32 v[170:171], v[132:133], v[170:171], v[132:133] neg_lo:[1,0,0] neg_hi:[1,0,0]
	v_exp_f32_e32 v172, v172
	v_cndmask_b32_e32 v170, v170, v174, vcc
	v_cmp_gt_f32_e32 vcc, 0, v133
	v_exp_f32_e32 v173, v173
	v_and_b32_e32 v211, 0x7fffffff, v131
	v_cndmask_b32_e32 v171, v171, v175, vcc
	v_pk_fma_f32 v[174:175], v[206:207], s[70:71], v[204:205] op_sel_hi:[1,0,0]
	v_cmp_gt_f32_e32 vcc, 0, v134
	v_pk_fma_f32 v[174:175], v[206:207], v[174:175], s[74:75] op_sel_hi:[1,1,0]
	v_and_b32_e32 v210, 0x7fffffff, v130
	v_pk_fma_f32 v[174:175], v[206:207], v[174:175], s[76:77] op_sel_hi:[1,1,0]
	v_pk_fma_f32 v[210:211], v[210:211], s[68:69], 1.0 op_sel_hi:[1,0,0]
	v_pk_fma_f32 v[174:175], v[206:207], v[174:175], s[78:79] op_sel_hi:[1,1,0]
	v_rcp_f32_e32 v210, v210
	v_pk_mul_f32 v[174:175], v[206:207], v[174:175]
	v_and_b32_e32 v207, 0x7fffffff, v129
	v_and_b32_e32 v206, 0x7fffffff, v128
	v_pk_fma_f32 v[206:207], v[206:207], s[68:69], 1.0 op_sel_hi:[1,0,0]
	v_pk_mul_f32 v[172:173], v[172:173], v[174:175]
	v_rcp_f32_e32 v206, v206
	v_rcp_f32_e32 v207, v207
	v_pk_mul_f32 v[174:175], v[134:135], v[172:173]
	v_pk_fma_f32 v[172:173], v[134:135], v[172:173], v[134:135] neg_lo:[1,0,0] neg_hi:[1,0,0]
	v_rcp_f32_e32 v211, v211
	v_cndmask_b32_e32 v172, v172, v174, vcc
	v_cmp_gt_f32_e32 vcc, 0, v135
	v_pk_mul_f32 v[208:209], v[128:129], v[128:129]
	v_add_f32_e32 v184, 0, v162
	v_cndmask_b32_e32 v173, v173, v175, vcc
	v_pk_fma_f32 v[174:175], v[206:207], s[70:71], v[204:205] op_sel_hi:[1,0,0]
	v_pk_mul_f32 v[208:209], v[208:209], s[80:81] op_sel_hi:[1,0]
	v_pk_fma_f32 v[174:175], v[206:207], v[174:175], s[74:75] op_sel_hi:[1,1,0]
	v_exp_f32_e32 v208, v208
	v_pk_fma_f32 v[174:175], v[206:207], v[174:175], s[76:77] op_sel_hi:[1,1,0]
	v_exp_f32_e32 v209, v209
	v_pk_fma_f32 v[174:175], v[206:207], v[174:175], s[78:79] op_sel_hi:[1,1,0]
	v_pk_fma_f32 v[204:205], v[210:211], s[70:71], v[204:205] op_sel_hi:[1,0,0]
	v_pk_mul_f32 v[174:175], v[206:207], v[174:175]
	v_pk_mul_f32 v[206:207], v[130:131], v[130:131]
	v_pk_fma_f32 v[204:205], v[210:211], v[204:205], s[74:75] op_sel_hi:[1,1,0]
	v_pk_mul_f32 v[206:207], v[206:207], s[80:81] op_sel_hi:[1,0]
	v_pk_fma_f32 v[204:205], v[210:211], v[204:205], s[76:77] op_sel_hi:[1,1,0]
	v_exp_f32_e32 v206, v206
	v_exp_f32_e32 v207, v207
	v_pk_mul_f32 v[174:175], v[208:209], v[174:175]
	v_pk_fma_f32 v[204:205], v[210:211], v[204:205], s[78:79] op_sel_hi:[1,1,0]
	v_pk_mul_f32 v[208:209], v[128:129], v[174:175]
	v_pk_fma_f32 v[174:175], v[128:129], v[174:175], v[128:129] neg_lo:[1,0,0] neg_hi:[1,0,0]
	v_cmp_gt_f32_e32 vcc, 0, v128
	v_pk_mul_f32 v[204:205], v[210:211], v[204:205]
	v_add_f32_e32 v184, v163, v184
	v_cndmask_b32_e32 v174, v174, v208, vcc
	v_cmp_gt_f32_e32 vcc, 0, v129
	v_pk_mul_f32 v[204:205], v[206:207], v[204:205]
	v_add_f32_e32 v184, v164, v184
	v_cndmask_b32_e32 v175, v175, v209, vcc
	v_pk_mul_f32 v[206:207], v[130:131], v[204:205]
	v_pk_fma_f32 v[204:205], v[130:131], v[204:205], v[130:131] neg_lo:[1,0,0] neg_hi:[1,0,0]
	v_cmp_gt_f32_e32 vcc, 0, v130
	v_add_f32_e32 v184, v165, v184
	v_add_f32_e32 v184, v166, v184
	v_cndmask_b32_e32 v204, v204, v206, vcc
	v_mul_f32_e32 v206, v163, v163
	v_fmac_f32_e32 v206, v162, v162
	v_fmac_f32_e32 v206, v164, v164
	v_add_f32_e32 v184, v167, v184
	v_fmac_f32_e32 v206, v165, v165
	v_add_f32_e32 v184, v168, v184
	v_fmac_f32_e32 v206, v166, v166
	v_add_f32_e32 v184, v169, v184
	v_fmac_f32_e32 v206, v167, v167
	v_add_f32_e32 v184, v170, v184
	v_fmac_f32_e32 v206, v168, v168
	v_add_f32_e32 v184, v171, v184
	v_cmp_gt_f32_e32 vcc, 0, v131
	v_fmac_f32_e32 v206, v169, v169
	v_add_f32_e32 v184, v172, v184
	v_cndmask_b32_e32 v205, v205, v207, vcc
	v_fmac_f32_e32 v206, v170, v170
	v_add_f32_e32 v184, v173, v184
	v_fmac_f32_e32 v206, v171, v171
	v_add_f32_e32 v184, v174, v184
	v_fmac_f32_e32 v206, v172, v172
	v_add_f32_e32 v184, v175, v184
	v_fmac_f32_e32 v206, v173, v173
	v_add_f32_e32 v184, v204, v184
	v_add_f32_e32 v184, v205, v184
	v_fmac_f32_e32 v206, v174, v174
	v_mov_b32_e32 v208, v184
	s_nop 1
	v_permlane16_swap_b32_e32 v184, v208
	s_nop 1
	v_fmac_f32_e32 v206, v175, v175
	v_fmac_f32_e32 v206, v204, v204
	v_fmac_f32_e32 v206, v205, v205
	v_mov_b32_e32 v209, v206
	s_nop 1
	v_permlane16_swap_b32_e32 v206, v209
	s_nop 1
	s_waitcnt lgkmcnt(1)
	v_add_f32_e32 v184, v184, v208
	v_xor_b32_e32 v208, 32, v229
	s_waitcnt lgkmcnt(0)
	v_add_f32_e32 v206, v206, v209
	v_mov_b32_e32 v199, v184
	s_nop 1
	v_permlane32_swap_b32_e32 v184, v199
	s_nop 1
	v_mov_b32_e32 v207, v206
	s_nop 1
	v_permlane32_swap_b32_e32 v206, v207
	s_nop 1
	s_and_saveexec_b64 s[90:91], s[4:5]
	s_cbranch_execz .LBB0_597
	v_lshlrev_b64 v[208:209], 2, v[160:161]
	v_lshl_add_u64 v[210:211], s[14:15], 0, v[208:209]
	v_lshl_add_u64 v[208:209], s[52:53], 0, v[208:209]
	s_waitcnt lgkmcnt(1)
	v_add_f32_e32 v184, v184, v199
	s_waitcnt lgkmcnt(0)
	v_add_f32_e32 v199, v206, v207
	global_atomic_add_f32 v[208:209], v184, off
	global_atomic_add_f32 v[210:211], v199, off

.LBB0_603:
	s_nop 0
	v_fmamk_f32 v128, v237, 0x3a800000, v228
	v_rsq_f32_e32 v130, v128
	v_add_u32_e32 v128, 0x80, v198
	v_ashrrev_i32_e32 v129, 31, v128
	s_and_b64 vcc, exec, s[10:11]
	v_pk_fma_f32 v[94:95], v[94:95], v[130:131], v[46:47] op_sel_hi:[1,0,1]
	v_pk_fma_f32 v[92:93], v[92:93], v[130:131], v[44:45] op_sel_hi:[1,0,1]
	v_pk_fma_f32 v[90:91], v[90:91], v[130:131], v[42:43] op_sel_hi:[1,0,1]
	v_pk_fma_f32 v[88:89], v[88:89], v[130:131], v[40:41] op_sel_hi:[1,0,1]
	v_pk_fma_f32 v[74:75], v[74:75], v[130:131], v[38:39] op_sel_hi:[1,0,1]
	v_pk_fma_f32 v[72:73], v[72:73], v[130:131], v[36:37] op_sel_hi:[1,0,1]
	v_pk_fma_f32 v[70:71], v[70:71], v[130:131], v[34:35] op_sel_hi:[1,0,1]
	v_pk_fma_f32 v[68:69], v[68:69], v[130:131], v[32:33] op_sel_hi:[1,0,1]
	s_mov_b64 s[90:91], -1
	s_cbranch_vccnz .LBB0_609
	s_and_b64 vcc, exec, s[8:9]
	v_mov_b32_e32 v133, v95
	v_mov_b32_e32 v132, v94
	v_mov_b32_e32 v131, v93
	v_mov_b32_e32 v130, v92
	v_mov_b32_e32 v137, v91
	v_mov_b32_e32 v136, v90
	v_mov_b32_e32 v135, v89
	v_mov_b32_e32 v134, v88
	v_mov_b32_e32 v141, v75
	v_mov_b32_e32 v140, v74
	v_mov_b32_e32 v139, v73
	v_mov_b32_e32 v138, v72
	v_mov_b32_e32 v161, v71
	v_mov_b32_e32 v160, v70
	v_mov_b32_e32 v143, v69
	v_mov_b32_e32 v142, v68
	s_cbranch_vccnz .LBB0_608
	v_and_b32_e32 v131, 0x7fffffff, v93
	v_and_b32_e32 v130, 0x7fffffff, v92
	v_pk_fma_f32 v[130:131], v[130:131], s[68:69], 1.0 op_sel_hi:[1,0,0]
	v_mov_b64_e32 v[160:161], s[72:73]
	v_rcp_f32_e32 v130, v130
	v_rcp_f32_e32 v131, v131
	v_pk_mul_f32 v[134:135], v[92:93], v[92:93]
	v_and_b32_e32 v137, 0x7fffffff, v95
	v_pk_mul_f32 v[134:135], v[134:135], s[80:81] op_sel_hi:[1,0]
	v_pk_fma_f32 v[132:133], v[130:131], s[70:71], v[160:161] op_sel_hi:[1,0,0]
	v_exp_f32_e32 v134, v134
	v_pk_fma_f32 v[132:133], v[130:131], v[132:133], s[74:75] op_sel_hi:[1,1,0]
	v_exp_f32_e32 v135, v135
	v_pk_fma_f32 v[132:133], v[130:131], v[132:133], s[76:77] op_sel_hi:[1,1,0]
	v_and_b32_e32 v136, 0x7fffffff, v94
	v_pk_fma_f32 v[132:133], v[130:131], v[132:133], s[78:79] op_sel_hi:[1,1,0]
	v_pk_fma_f32 v[136:137], v[136:137], s[68:69], 1.0 op_sel_hi:[1,0,0]
	v_pk_mul_f32 v[130:131], v[130:131], v[132:133]
	v_rcp_f32_e32 v136, v136
	v_rcp_f32_e32 v137, v137
	v_pk_mul_f32 v[130:131], v[134:135], v[130:131]
	v_cmp_gt_f32_e32 vcc, 0, v92
	v_pk_mul_f32 v[134:135], v[92:93], v[130:131]
	v_pk_fma_f32 v[130:131], v[92:93], v[130:131], v[92:93] neg_lo:[1,0,0] neg_hi:[1,0,0]
	v_pk_mul_f32 v[132:133], v[94:95], v[94:95]
	v_cndmask_b32_e32 v130, v130, v134, vcc
	v_cmp_gt_f32_e32 vcc, 0, v93
	v_pk_mul_f32 v[132:133], v[132:133], s[80:81] op_sel_hi:[1,0]
	v_pk_mul_f32 v[138:139], v[88:89], v[88:89]
	v_cndmask_b32_e32 v131, v131, v135, vcc
	v_pk_fma_f32 v[134:135], v[136:137], s[70:71], v[160:161] op_sel_hi:[1,0,0]
	v_exp_f32_e32 v132, v132
	v_pk_fma_f32 v[134:135], v[136:137], v[134:135], s[74:75] op_sel_hi:[1,1,0]
	v_exp_f32_e32 v133, v133
	v_pk_fma_f32 v[134:135], v[136:137], v[134:135], s[76:77] op_sel_hi:[1,1,0]
	v_cmp_gt_f32_e32 vcc, 0, v94
	v_pk_fma_f32 v[134:135], v[136:137], v[134:135], s[78:79] op_sel_hi:[1,1,0]
	v_pk_mul_f32 v[138:139], v[138:139], s[80:81] op_sel_hi:[1,0]
	v_pk_mul_f32 v[134:135], v[136:137], v[134:135]
	v_and_b32_e32 v137, 0x7fffffff, v89
	v_and_b32_e32 v136, 0x7fffffff, v88
	v_pk_fma_f32 v[136:137], v[136:137], s[68:69], 1.0 op_sel_hi:[1,0,0]
	v_pk_mul_f32 v[132:133], v[132:133], v[134:135]
	v_rcp_f32_e32 v136, v136
	v_rcp_f32_e32 v137, v137
	v_pk_mul_f32 v[134:135], v[94:95], v[132:133]
	v_pk_fma_f32 v[132:133], v[94:95], v[132:133], v[94:95] neg_lo:[1,0,0] neg_hi:[1,0,0]
	v_exp_f32_e32 v138, v138
	v_cndmask_b32_e32 v132, v132, v134, vcc
	v_cmp_gt_f32_e32 vcc, 0, v95
	v_exp_f32_e32 v139, v139
	v_and_b32_e32 v141, 0x7fffffff, v91
	v_cndmask_b32_e32 v133, v133, v135, vcc
	v_pk_fma_f32 v[134:135], v[136:137], s[70:71], v[160:161] op_sel_hi:[1,0,0]
	v_and_b32_e32 v140, 0x7fffffff, v90
	v_pk_fma_f32 v[134:135], v[136:137], v[134:135], s[74:75] op_sel_hi:[1,1,0]
	v_pk_fma_f32 v[140:141], v[140:141], s[68:69], 1.0 op_sel_hi:[1,0,0]
	v_pk_fma_f32 v[134:135], v[136:137], v[134:135], s[76:77] op_sel_hi:[1,1,0]
	v_rcp_f32_e32 v140, v140
	v_pk_fma_f32 v[134:135], v[136:137], v[134:135], s[78:79] op_sel_hi:[1,1,0]
	v_rcp_f32_e32 v141, v141
	v_pk_mul_f32 v[134:135], v[136:137], v[134:135]
	v_cmp_gt_f32_e32 vcc, 0, v88
	v_pk_mul_f32 v[134:135], v[138:139], v[134:135]
	v_pk_mul_f32 v[136:137], v[90:91], v[90:91]
	v_pk_mul_f32 v[138:139], v[88:89], v[134:135]
	v_pk_fma_f32 v[134:135], v[88:89], v[134:135], v[88:89] neg_lo:[1,0,0] neg_hi:[1,0,0]
	v_pk_mul_f32 v[136:137], v[136:137], s[80:81] op_sel_hi:[1,0]
	v_cndmask_b32_e32 v134, v134, v138, vcc
	v_cmp_gt_f32_e32 vcc, 0, v89
	v_exp_f32_e32 v136, v136
	v_exp_f32_e32 v137, v137
	v_cndmask_b32_e32 v135, v135, v139, vcc
	v_pk_fma_f32 v[138:139], v[140:141], s[70:71], v[160:161] op_sel_hi:[1,0,0]
	v_cmp_gt_f32_e32 vcc, 0, v90
	v_pk_fma_f32 v[138:139], v[140:141], v[138:139], s[74:75] op_sel_hi:[1,1,0]
	v_pk_mul_f32 v[142:143], v[72:73], v[72:73]
	v_pk_fma_f32 v[138:139], v[140:141], v[138:139], s[76:77] op_sel_hi:[1,1,0]
	v_pk_mul_f32 v[142:143], v[142:143], s[80:81] op_sel_hi:[1,0]
	v_pk_fma_f32 v[138:139], v[140:141], v[138:139], s[78:79] op_sel_hi:[1,1,0]
	v_exp_f32_e32 v142, v142
	v_pk_mul_f32 v[138:139], v[140:141], v[138:139]
	v_and_b32_e32 v141, 0x7fffffff, v73
	v_and_b32_e32 v140, 0x7fffffff, v72
	v_pk_fma_f32 v[140:141], v[140:141], s[68:69], 1.0 op_sel_hi:[1,0,0]
	v_pk_mul_f32 v[136:137], v[136:137], v[138:139]
	v_rcp_f32_e32 v140, v140
	v_rcp_f32_e32 v141, v141
	v_pk_mul_f32 v[138:139], v[90:91], v[136:137]
	v_pk_fma_f32 v[136:137], v[90:91], v[136:137], v[90:91] neg_lo:[1,0,0] neg_hi:[1,0,0]
	v_exp_f32_e32 v143, v143
	v_cndmask_b32_e32 v136, v136, v138, vcc
	v_cmp_gt_f32_e32 vcc, 0, v91
	v_and_b32_e32 v163, 0x7fffffff, v75
	v_and_b32_e32 v162, 0x7fffffff, v74
	v_cndmask_b32_e32 v137, v137, v139, vcc
	v_pk_fma_f32 v[138:139], v[140:141], s[70:71], v[160:161] op_sel_hi:[1,0,0]
	v_pk_fma_f32 v[162:163], v[162:163], s[68:69], 1.0 op_sel_hi:[1,0,0]
	v_pk_fma_f32 v[138:139], v[140:141], v[138:139], s[74:75] op_sel_hi:[1,1,0]
	v_rcp_f32_e32 v162, v162
	v_pk_fma_f32 v[138:139], v[140:141], v[138:139], s[76:77] op_sel_hi:[1,1,0]
	v_rcp_f32_e32 v163, v163
	v_pk_fma_f32 v[138:139], v[140:141], v[138:139], s[78:79] op_sel_hi:[1,1,0]
	v_cmp_gt_f32_e32 vcc, 0, v72
	v_pk_mul_f32 v[138:139], v[140:141], v[138:139]
	v_pk_mul_f32 v[140:141], v[74:75], v[74:75]
	v_pk_mul_f32 v[138:139], v[142:143], v[138:139]
	v_pk_mul_f32 v[140:141], v[140:141], s[80:81] op_sel_hi:[1,0]
	v_pk_mul_f32 v[142:143], v[72:73], v[138:139]
	v_pk_fma_f32 v[138:139], v[72:73], v[138:139], v[72:73] neg_lo:[1,0,0] neg_hi:[1,0,0]
	v_exp_f32_e32 v140, v140
	v_cndmask_b32_e32 v138, v138, v142, vcc
	v_cmp_gt_f32_e32 vcc, 0, v73
	v_exp_f32_e32 v141, v141
	v_and_b32_e32 v167, 0x7fffffff, v71
	v_cndmask_b32_e32 v139, v139, v143, vcc
	v_pk_fma_f32 v[142:143], v[162:163], s[70:71], v[160:161] op_sel_hi:[1,0,0]
	v_cmp_gt_f32_e32 vcc, 0, v74
	v_pk_fma_f32 v[142:143], v[162:163], v[142:143], s[74:75] op_sel_hi:[1,1,0]
	v_and_b32_e32 v166, 0x7fffffff, v70
	v_pk_fma_f32 v[142:143], v[162:163], v[142:143], s[76:77] op_sel_hi:[1,1,0]
	v_pk_fma_f32 v[166:167], v[166:167], s[68:69], 1.0 op_sel_hi:[1,0,0]
	v_pk_fma_f32 v[142:143], v[162:163], v[142:143], s[78:79] op_sel_hi:[1,1,0]
	v_rcp_f32_e32 v166, v166
	v_pk_mul_f32 v[142:143], v[162:163], v[142:143]
	v_and_b32_e32 v163, 0x7fffffff, v69
	v_and_b32_e32 v162, 0x7fffffff, v68
	v_pk_fma_f32 v[162:163], v[162:163], s[68:69], 1.0 op_sel_hi:[1,0,0]
	v_pk_mul_f32 v[140:141], v[140:141], v[142:143]
	v_rcp_f32_e32 v162, v162
	v_rcp_f32_e32 v163, v163
	v_pk_mul_f32 v[142:143], v[74:75], v[140:141]
	v_pk_fma_f32 v[140:141], v[74:75], v[140:141], v[74:75] neg_lo:[1,0,0] neg_hi:[1,0,0]
	v_rcp_f32_e32 v167, v167
	v_cndmask_b32_e32 v140, v140, v142, vcc
	v_cmp_gt_f32_e32 vcc, 0, v75
	v_pk_mul_f32 v[164:165], v[68:69], v[68:69]
	s_nop 0
	v_cndmask_b32_e32 v141, v141, v143, vcc
	v_pk_fma_f32 v[142:143], v[162:163], s[70:71], v[160:161] op_sel_hi:[1,0,0]
	v_pk_mul_f32 v[164:165], v[164:165], s[80:81] op_sel_hi:[1,0]
	v_pk_fma_f32 v[142:143], v[162:163], v[142:143], s[74:75] op_sel_hi:[1,1,0]
	v_exp_f32_e32 v164, v164
	v_pk_fma_f32 v[142:143], v[162:163], v[142:143], s[76:77] op_sel_hi:[1,1,0]
	v_exp_f32_e32 v165, v165
	v_pk_fma_f32 v[142:143], v[162:163], v[142:143], s[78:79] op_sel_hi:[1,1,0]
	v_pk_fma_f32 v[160:161], v[166:167], s[70:71], v[160:161] op_sel_hi:[1,0,0]
	v_pk_mul_f32 v[142:143], v[162:163], v[142:143]
	v_pk_mul_f32 v[162:163], v[70:71], v[70:71]
	v_pk_fma_f32 v[160:161], v[166:167], v[160:161], s[74:75] op_sel_hi:[1,1,0]
	v_pk_mul_f32 v[162:163], v[162:163], s[80:81] op_sel_hi:[1,0]
	v_pk_fma_f32 v[160:161], v[166:167], v[160:161], s[76:77] op_sel_hi:[1,1,0]
	v_exp_f32_e32 v162, v162
	v_exp_f32_e32 v163, v163
	v_pk_mul_f32 v[142:143], v[164:165], v[142:143]
	v_pk_fma_f32 v[160:161], v[166:167], v[160:161], s[78:79] op_sel_hi:[1,1,0]
	v_pk_mul_f32 v[164:165], v[68:69], v[142:143]
	v_pk_fma_f32 v[142:143], v[68:69], v[142:143], v[68:69] neg_lo:[1,0,0] neg_hi:[1,0,0]
	v_cmp_gt_f32_e32 vcc, 0, v68
	v_pk_mul_f32 v[160:161], v[166:167], v[160:161]
	s_nop 0
	v_cndmask_b32_e32 v142, v142, v164, vcc
	v_cmp_gt_f32_e32 vcc, 0, v69
	v_pk_mul_f32 v[160:161], v[162:163], v[160:161]
	v_mul_f32_e32 v164, v131, v131
	v_cndmask_b32_e32 v143, v143, v165, vcc
	v_pk_mul_f32 v[162:163], v[70:71], v[160:161]
	v_pk_fma_f32 v[160:161], v[70:71], v[160:161], v[70:71] neg_lo:[1,0,0] neg_hi:[1,0,0]
	v_cmp_gt_f32_e32 vcc, 0, v70
	v_fmac_f32_e32 v164, v130, v130
	v_fmac_f32_e32 v164, v132, v132
	v_cndmask_b32_e32 v160, v160, v162, vcc
	v_add_f32_e32 v162, 0, v130
	v_add_f32_e32 v162, v131, v162
	v_add_f32_e32 v162, v132, v162
	v_add_f32_e32 v162, v133, v162
	v_add_f32_e32 v162, v134, v162
	v_add_f32_e32 v162, v135, v162
	v_fmac_f32_e32 v164, v133, v133
	v_add_f32_e32 v162, v136, v162
	v_fmac_f32_e32 v164, v134, v134
	v_add_f32_e32 v162, v137, v162
	v_fmac_f32_e32 v164, v135, v135
	v_add_f32_e32 v162, v138, v162
	v_fmac_f32_e32 v164, v136, v136
	v_add_f32_e32 v162, v139, v162
	v_fmac_f32_e32 v164, v137, v137
	v_add_f32_e32 v162, v140, v162
	v_cmp_gt_f32_e32 vcc, 0, v71
	v_fmac_f32_e32 v164, v138, v138
	v_add_f32_e32 v162, v141, v162
	v_cndmask_b32_e32 v161, v161, v163, vcc
	v_fmac_f32_e32 v164, v139, v139
	v_add_f32_e32 v162, v142, v162
	v_fmac_f32_e32 v164, v140, v140
	v_add_f32_e32 v162, v143, v162
	v_fmac_f32_e32 v164, v141, v141
	v_add_f32_e32 v162, v160, v162
	v_add_f32_e32 v162, v161, v162
	v_fmac_f32_e32 v164, v142, v142
	v_mov_b32_e32 v166, v162
	s_nop 1
	v_permlane16_swap_b32_e32 v162, v166
	s_nop 1
	v_fmac_f32_e32 v164, v143, v143
	v_fmac_f32_e32 v164, v160, v160
	v_fmac_f32_e32 v164, v161, v161
	v_mov_b32_e32 v167, v164
	s_nop 1
	v_permlane16_swap_b32_e32 v164, v167
	s_nop 1
	s_waitcnt lgkmcnt(1)
	v_add_f32_e32 v162, v162, v166
	v_xor_b32_e32 v166, 32, v229
	s_waitcnt lgkmcnt(0)
	v_add_f32_e32 v164, v164, v167
	v_mov_b32_e32 v163, v162
	s_nop 1
	v_permlane32_swap_b32_e32 v162, v163
	s_nop 1
	v_mov_b32_e32 v165, v164
	s_nop 1
	v_permlane32_swap_b32_e32 v164, v165
	s_nop 1
	s_and_saveexec_b64 s[90:91], s[4:5]
	s_cbranch_execz .LBB0_607
	v_lshlrev_b64 v[166:167], 2, v[128:129]
	v_lshl_add_u64 v[168:169], s[14:15], 0, v[166:167]
	v_lshl_add_u64 v[166:167], s[52:53], 0, v[166:167]
	s_waitcnt lgkmcnt(1)
	v_add_f32_e32 v162, v162, v163
	s_waitcnt lgkmcnt(0)
	v_add_f32_e32 v163, v164, v165
	global_atomic_add_f32 v[166:167], v162, off
	global_atomic_add_f32 v[168:169], v163, off

.LBB0_611:
	v_lshlrev_b64 v[70:71], 11, v[128:129]
	v_lshl_add_u64 v[74:75], v[202:203], 0, v[70:71]
	v_cvt_pk_bf16_f32 v70, v130, v131
	v_cvt_pk_bf16_f32 v71, v132, v133
	v_cvt_pk_bf16_f32 v72, v134, v135
	v_cvt_pk_bf16_f32 v73, v136, v137
	global_store_dwordx4 v[74:75], v[70:73], off
	v_add_u32_e32 v68, 0x90, v198
	v_ashrrev_i32_e32 v69, 31, v68
	v_fmamk_f32 v72, v236, 0x3a800000, v228
	v_rsq_f32_e32 v88, v72
	v_cvt_pk_bf16_f32 v70, v138, v139
	v_cvt_pk_bf16_f32 v71, v140, v141
	v_cvt_pk_bf16_f32 v72, v142, v143
	v_cvt_pk_bf16_f32 v73, v160, v161
	s_and_b64 vcc, exec, s[10:11]
	v_pk_fma_f32 v[62:63], v[62:63], v[88:89], v[46:47] op_sel_hi:[1,0,1]
	v_pk_fma_f32 v[60:61], v[60:61], v[88:89], v[44:45] op_sel_hi:[1,0,1]
	v_pk_fma_f32 v[58:59], v[58:59], v[88:89], v[42:43] op_sel_hi:[1,0,1]
	v_pk_fma_f32 v[56:57], v[56:57], v[88:89], v[40:41] op_sel_hi:[1,0,1]
	v_pk_fma_f32 v[54:55], v[54:55], v[88:89], v[38:39] op_sel_hi:[1,0,1]
	v_pk_fma_f32 v[52:53], v[52:53], v[88:89], v[36:37] op_sel_hi:[1,0,1]
	v_pk_fma_f32 v[50:51], v[50:51], v[88:89], v[34:35] op_sel_hi:[1,0,1]
	v_pk_fma_f32 v[48:49], v[48:49], v[88:89], v[32:33] op_sel_hi:[1,0,1]
	s_mov_b64 s[90:91], -1
	global_store_dwordx4 v[74:75], v[70:73], off offset:256
	s_cbranch_vccnz .LBB0_617
	s_and_b64 vcc, exec, s[8:9]
	v_mov_b32_e32 v73, v63
	v_mov_b32_e32 v72, v62
	v_mov_b32_e32 v71, v61
	v_mov_b32_e32 v70, v60
	v_mov_b32_e32 v89, v59
	v_mov_b32_e32 v88, v58
	v_mov_b32_e32 v75, v57
	v_mov_b32_e32 v74, v56
	v_mov_b32_e32 v93, v55
	v_mov_b32_e32 v92, v54
	v_mov_b32_e32 v91, v53
	v_mov_b32_e32 v90, v52
	s_waitcnt vmcnt(9)
	v_mov_b32_e32 v113, v51
	v_mov_b32_e32 v112, v50
	v_mov_b32_e32 v95, v49
	v_mov_b32_e32 v94, v48
	s_cbranch_vccnz .LBB0_616
	v_and_b32_e32 v71, 0x7fffffff, v61
	v_and_b32_e32 v70, 0x7fffffff, v60
	v_pk_fma_f32 v[70:71], v[70:71], s[68:69], 1.0 op_sel_hi:[1,0,0]
	v_mov_b64_e32 v[112:113], s[72:73]
	v_rcp_f32_e32 v70, v70
	v_rcp_f32_e32 v71, v71
	v_pk_mul_f32 v[74:75], v[60:61], v[60:61]
	v_and_b32_e32 v89, 0x7fffffff, v63
	v_pk_mul_f32 v[74:75], v[74:75], s[80:81] op_sel_hi:[1,0]
	v_pk_fma_f32 v[72:73], v[70:71], s[70:71], v[112:113] op_sel_hi:[1,0,0]
	v_exp_f32_e32 v74, v74
	v_pk_fma_f32 v[72:73], v[70:71], v[72:73], s[74:75] op_sel_hi:[1,1,0]
	v_exp_f32_e32 v75, v75
	v_pk_fma_f32 v[72:73], v[70:71], v[72:73], s[76:77] op_sel_hi:[1,1,0]
	v_and_b32_e32 v88, 0x7fffffff, v62
	v_pk_fma_f32 v[72:73], v[70:71], v[72:73], s[78:79] op_sel_hi:[1,1,0]
	v_pk_fma_f32 v[88:89], v[88:89], s[68:69], 1.0 op_sel_hi:[1,0,0]
	v_pk_mul_f32 v[70:71], v[70:71], v[72:73]
	v_rcp_f32_e32 v88, v88
	v_rcp_f32_e32 v89, v89
	v_pk_mul_f32 v[70:71], v[74:75], v[70:71]
	v_cmp_gt_f32_e32 vcc, 0, v60
	v_pk_mul_f32 v[74:75], v[60:61], v[70:71]
	v_pk_fma_f32 v[70:71], v[60:61], v[70:71], v[60:61] neg_lo:[1,0,0] neg_hi:[1,0,0]
	v_pk_mul_f32 v[72:73], v[62:63], v[62:63]
	v_cndmask_b32_e32 v70, v70, v74, vcc
	v_cmp_gt_f32_e32 vcc, 0, v61
	v_pk_mul_f32 v[72:73], v[72:73], s[80:81] op_sel_hi:[1,0]
	v_pk_mul_f32 v[90:91], v[56:57], v[56:57]
	v_cndmask_b32_e32 v71, v71, v75, vcc
	v_pk_fma_f32 v[74:75], v[88:89], s[70:71], v[112:113] op_sel_hi:[1,0,0]
	v_exp_f32_e32 v72, v72
	v_pk_fma_f32 v[74:75], v[88:89], v[74:75], s[74:75] op_sel_hi:[1,1,0]
	v_exp_f32_e32 v73, v73
	v_pk_fma_f32 v[74:75], v[88:89], v[74:75], s[76:77] op_sel_hi:[1,1,0]
	v_cmp_gt_f32_e32 vcc, 0, v62
	v_pk_fma_f32 v[74:75], v[88:89], v[74:75], s[78:79] op_sel_hi:[1,1,0]
	v_pk_mul_f32 v[90:91], v[90:91], s[80:81] op_sel_hi:[1,0]
	v_pk_mul_f32 v[74:75], v[88:89], v[74:75]
	v_and_b32_e32 v89, 0x7fffffff, v57
	v_and_b32_e32 v88, 0x7fffffff, v56
	v_pk_fma_f32 v[88:89], v[88:89], s[68:69], 1.0 op_sel_hi:[1,0,0]
	v_pk_mul_f32 v[72:73], v[72:73], v[74:75]
	v_rcp_f32_e32 v88, v88
	v_rcp_f32_e32 v89, v89
	v_pk_mul_f32 v[74:75], v[62:63], v[72:73]
	v_pk_fma_f32 v[72:73], v[62:63], v[72:73], v[62:63] neg_lo:[1,0,0] neg_hi:[1,0,0]
	v_exp_f32_e32 v90, v90
	v_cndmask_b32_e32 v72, v72, v74, vcc
	v_cmp_gt_f32_e32 vcc, 0, v63
	v_exp_f32_e32 v91, v91
	v_and_b32_e32 v93, 0x7fffffff, v59
	v_cndmask_b32_e32 v73, v73, v75, vcc
	v_pk_fma_f32 v[74:75], v[88:89], s[70:71], v[112:113] op_sel_hi:[1,0,0]
	v_and_b32_e32 v92, 0x7fffffff, v58
	v_pk_fma_f32 v[74:75], v[88:89], v[74:75], s[74:75] op_sel_hi:[1,1,0]
	v_pk_fma_f32 v[92:93], v[92:93], s[68:69], 1.0 op_sel_hi:[1,0,0]
	v_pk_fma_f32 v[74:75], v[88:89], v[74:75], s[76:77] op_sel_hi:[1,1,0]
	v_rcp_f32_e32 v92, v92
	v_pk_fma_f32 v[74:75], v[88:89], v[74:75], s[78:79] op_sel_hi:[1,1,0]
	v_rcp_f32_e32 v93, v93
	v_pk_mul_f32 v[74:75], v[88:89], v[74:75]
	v_cmp_gt_f32_e32 vcc, 0, v56
	v_pk_mul_f32 v[74:75], v[90:91], v[74:75]
	v_pk_mul_f32 v[88:89], v[58:59], v[58:59]
	v_pk_mul_f32 v[90:91], v[56:57], v[74:75]
	v_pk_fma_f32 v[74:75], v[56:57], v[74:75], v[56:57] neg_lo:[1,0,0] neg_hi:[1,0,0]
	v_pk_mul_f32 v[88:89], v[88:89], s[80:81] op_sel_hi:[1,0]
	v_cndmask_b32_e32 v74, v74, v90, vcc
	v_cmp_gt_f32_e32 vcc, 0, v57
	v_exp_f32_e32 v88, v88
	v_exp_f32_e32 v89, v89
	v_cndmask_b32_e32 v75, v75, v91, vcc
	v_pk_fma_f32 v[90:91], v[92:93], s[70:71], v[112:113] op_sel_hi:[1,0,0]
	v_cmp_gt_f32_e32 vcc, 0, v58
	v_pk_fma_f32 v[90:91], v[92:93], v[90:91], s[74:75] op_sel_hi:[1,1,0]
	v_pk_mul_f32 v[94:95], v[52:53], v[52:53]
	v_pk_fma_f32 v[90:91], v[92:93], v[90:91], s[76:77] op_sel_hi:[1,1,0]
	v_pk_mul_f32 v[94:95], v[94:95], s[80:81] op_sel_hi:[1,0]
	v_pk_fma_f32 v[90:91], v[92:93], v[90:91], s[78:79] op_sel_hi:[1,1,0]
	v_exp_f32_e32 v94, v94
	v_pk_mul_f32 v[90:91], v[92:93], v[90:91]
	v_and_b32_e32 v93, 0x7fffffff, v53
	v_and_b32_e32 v92, 0x7fffffff, v52
	v_pk_fma_f32 v[92:93], v[92:93], s[68:69], 1.0 op_sel_hi:[1,0,0]
	v_pk_mul_f32 v[88:89], v[88:89], v[90:91]
	v_rcp_f32_e32 v92, v92
	v_rcp_f32_e32 v93, v93
	v_pk_mul_f32 v[90:91], v[58:59], v[88:89]
	v_pk_fma_f32 v[88:89], v[58:59], v[88:89], v[58:59] neg_lo:[1,0,0] neg_hi:[1,0,0]
	v_exp_f32_e32 v95, v95
	v_cndmask_b32_e32 v88, v88, v90, vcc
	v_cmp_gt_f32_e32 vcc, 0, v59
	v_and_b32_e32 v115, 0x7fffffff, v55
	v_and_b32_e32 v114, 0x7fffffff, v54
	v_cndmask_b32_e32 v89, v89, v91, vcc
	v_pk_fma_f32 v[90:91], v[92:93], s[70:71], v[112:113] op_sel_hi:[1,0,0]
	v_pk_fma_f32 v[114:115], v[114:115], s[68:69], 1.0 op_sel_hi:[1,0,0]
	v_pk_fma_f32 v[90:91], v[92:93], v[90:91], s[74:75] op_sel_hi:[1,1,0]
	v_rcp_f32_e32 v114, v114
	v_pk_fma_f32 v[90:91], v[92:93], v[90:91], s[76:77] op_sel_hi:[1,1,0]
	v_rcp_f32_e32 v115, v115
	v_pk_fma_f32 v[90:91], v[92:93], v[90:91], s[78:79] op_sel_hi:[1,1,0]
	v_cmp_gt_f32_e32 vcc, 0, v52
	v_pk_mul_f32 v[90:91], v[92:93], v[90:91]
	v_pk_mul_f32 v[92:93], v[54:55], v[54:55]
	v_pk_mul_f32 v[90:91], v[94:95], v[90:91]
	v_pk_mul_f32 v[92:93], v[92:93], s[80:81] op_sel_hi:[1,0]
	v_pk_mul_f32 v[94:95], v[52:53], v[90:91]
	v_pk_fma_f32 v[90:91], v[52:53], v[90:91], v[52:53] neg_lo:[1,0,0] neg_hi:[1,0,0]
	v_exp_f32_e32 v92, v92
	v_cndmask_b32_e32 v90, v90, v94, vcc
	v_cmp_gt_f32_e32 vcc, 0, v53
	v_exp_f32_e32 v93, v93
	s_waitcnt vmcnt(8)
	v_and_b32_e32 v119, 0x7fffffff, v51
	v_cndmask_b32_e32 v91, v91, v95, vcc
	v_pk_fma_f32 v[94:95], v[114:115], s[70:71], v[112:113] op_sel_hi:[1,0,0]
	v_cmp_gt_f32_e32 vcc, 0, v54
	v_pk_fma_f32 v[94:95], v[114:115], v[94:95], s[74:75] op_sel_hi:[1,1,0]
	v_and_b32_e32 v118, 0x7fffffff, v50
	v_pk_fma_f32 v[94:95], v[114:115], v[94:95], s[76:77] op_sel_hi:[1,1,0]
	v_pk_fma_f32 v[118:119], v[118:119], s[68:69], 1.0 op_sel_hi:[1,0,0]
	v_pk_fma_f32 v[94:95], v[114:115], v[94:95], s[78:79] op_sel_hi:[1,1,0]
	v_rcp_f32_e32 v118, v118
	v_pk_mul_f32 v[94:95], v[114:115], v[94:95]
	v_and_b32_e32 v115, 0x7fffffff, v49
	v_and_b32_e32 v114, 0x7fffffff, v48
	v_pk_fma_f32 v[114:115], v[114:115], s[68:69], 1.0 op_sel_hi:[1,0,0]
	v_pk_mul_f32 v[92:93], v[92:93], v[94:95]
	v_rcp_f32_e32 v114, v114
	v_rcp_f32_e32 v115, v115
	v_pk_mul_f32 v[94:95], v[54:55], v[92:93]
	v_pk_fma_f32 v[92:93], v[54:55], v[92:93], v[54:55] neg_lo:[1,0,0] neg_hi:[1,0,0]
	v_rcp_f32_e32 v119, v119
	v_cndmask_b32_e32 v92, v92, v94, vcc
	v_cmp_gt_f32_e32 vcc, 0, v55
	v_pk_mul_f32 v[116:117], v[48:49], v[48:49]
	s_nop 0
	v_cndmask_b32_e32 v93, v93, v95, vcc
	v_pk_fma_f32 v[94:95], v[114:115], s[70:71], v[112:113] op_sel_hi:[1,0,0]
	v_pk_mul_f32 v[116:117], v[116:117], s[80:81] op_sel_hi:[1,0]
	v_pk_fma_f32 v[94:95], v[114:115], v[94:95], s[74:75] op_sel_hi:[1,1,0]
	v_exp_f32_e32 v116, v116
	v_pk_fma_f32 v[94:95], v[114:115], v[94:95], s[76:77] op_sel_hi:[1,1,0]
	v_exp_f32_e32 v117, v117
	v_pk_fma_f32 v[94:95], v[114:115], v[94:95], s[78:79] op_sel_hi:[1,1,0]
	v_pk_fma_f32 v[112:113], v[118:119], s[70:71], v[112:113] op_sel_hi:[1,0,0]
	v_pk_mul_f32 v[94:95], v[114:115], v[94:95]
	v_pk_mul_f32 v[114:115], v[50:51], v[50:51]
	v_pk_fma_f32 v[112:113], v[118:119], v[112:113], s[74:75] op_sel_hi:[1,1,0]
	v_pk_mul_f32 v[114:115], v[114:115], s[80:81] op_sel_hi:[1,0]
	v_pk_fma_f32 v[112:113], v[118:119], v[112:113], s[76:77] op_sel_hi:[1,1,0]
	v_exp_f32_e32 v114, v114
	v_exp_f32_e32 v115, v115
	v_pk_mul_f32 v[94:95], v[116:117], v[94:95]
	v_pk_fma_f32 v[112:113], v[118:119], v[112:113], s[78:79] op_sel_hi:[1,1,0]
	v_pk_mul_f32 v[116:117], v[48:49], v[94:95]
	v_pk_fma_f32 v[94:95], v[48:49], v[94:95], v[48:49] neg_lo:[1,0,0] neg_hi:[1,0,0]
	v_cmp_gt_f32_e32 vcc, 0, v48
	v_pk_mul_f32 v[112:113], v[118:119], v[112:113]
	s_nop 0
	v_cndmask_b32_e32 v94, v94, v116, vcc
	v_cmp_gt_f32_e32 vcc, 0, v49
	v_pk_mul_f32 v[112:113], v[114:115], v[112:113]
	v_mul_f32_e32 v116, v71, v71
	v_cndmask_b32_e32 v95, v95, v117, vcc
	v_pk_mul_f32 v[114:115], v[50:51], v[112:113]
	v_pk_fma_f32 v[112:113], v[50:51], v[112:113], v[50:51] neg_lo:[1,0,0] neg_hi:[1,0,0]
	v_cmp_gt_f32_e32 vcc, 0, v50
	v_fmac_f32_e32 v116, v70, v70
	v_fmac_f32_e32 v116, v72, v72
	v_cndmask_b32_e32 v112, v112, v114, vcc
	v_add_f32_e32 v114, 0, v70
	v_add_f32_e32 v114, v71, v114
	v_add_f32_e32 v114, v72, v114
	v_add_f32_e32 v114, v73, v114
	v_add_f32_e32 v114, v74, v114
	v_add_f32_e32 v114, v75, v114
	v_fmac_f32_e32 v116, v73, v73
	v_add_f32_e32 v114, v88, v114
	v_fmac_f32_e32 v116, v74, v74
	v_add_f32_e32 v114, v89, v114
	v_fmac_f32_e32 v116, v75, v75
	v_add_f32_e32 v114, v90, v114
	v_fmac_f32_e32 v116, v88, v88
	v_add_f32_e32 v114, v91, v114
	v_fmac_f32_e32 v116, v89, v89
	v_add_f32_e32 v114, v92, v114
	v_cmp_gt_f32_e32 vcc, 0, v51
	v_fmac_f32_e32 v116, v90, v90
	v_add_f32_e32 v114, v93, v114
	v_cndmask_b32_e32 v113, v113, v115, vcc
	v_fmac_f32_e32 v116, v91, v91
	v_add_f32_e32 v114, v94, v114
	v_fmac_f32_e32 v116, v92, v92
	v_add_f32_e32 v114, v95, v114
	v_fmac_f32_e32 v116, v93, v93
	v_add_f32_e32 v114, v112, v114
	v_add_f32_e32 v114, v113, v114
	v_fmac_f32_e32 v116, v94, v94
	v_mov_b32_e32 v118, v114
	s_nop 1
	v_permlane16_swap_b32_e32 v114, v118
	s_nop 1
	v_fmac_f32_e32 v116, v95, v95
	v_fmac_f32_e32 v116, v112, v112
	v_fmac_f32_e32 v116, v113, v113
	v_mov_b32_e32 v119, v116
	s_nop 1
	v_permlane16_swap_b32_e32 v116, v119
	s_nop 1
	s_waitcnt lgkmcnt(1)
	v_add_f32_e32 v114, v114, v118
	v_xor_b32_e32 v118, 32, v229
	s_waitcnt lgkmcnt(0)
	v_add_f32_e32 v116, v116, v119
	v_mov_b32_e32 v115, v114
	s_nop 1
	v_permlane32_swap_b32_e32 v114, v115
	s_nop 1
	v_mov_b32_e32 v117, v116
	s_nop 1
	v_permlane32_swap_b32_e32 v116, v117
	s_nop 1
	s_and_saveexec_b64 s[90:91], s[4:5]
	s_cbranch_execz .LBB0_615
	v_lshlrev_b64 v[118:119], 2, v[68:69]
	s_waitcnt vmcnt(7)
	v_lshl_add_u64 v[120:121], s[14:15], 0, v[118:119]
	v_lshl_add_u64 v[118:119], s[52:53], 0, v[118:119]
	s_waitcnt lgkmcnt(1)
	v_add_f32_e32 v114, v114, v115
	s_waitcnt lgkmcnt(0)
	v_add_f32_e32 v115, v116, v117
	global_atomic_add_f32 v[118:119], v114, off
	global_atomic_add_f32 v[120:121], v115, off

.LBB0_621:
	s_nop 0
	v_fmamk_f32 v48, v234, 0x3a800000, v228
	v_rsq_f32_e32 v50, v48
	v_add_u32_e32 v48, 0xa0, v198
	v_ashrrev_i32_e32 v49, 31, v48
	s_and_b64 vcc, exec, s[10:11]
	v_pk_fma_f32 v[30:31], v[30:31], v[50:51], v[46:47] op_sel_hi:[1,0,1]
	v_pk_fma_f32 v[28:29], v[28:29], v[50:51], v[44:45] op_sel_hi:[1,0,1]
	v_pk_fma_f32 v[26:27], v[26:27], v[50:51], v[42:43] op_sel_hi:[1,0,1]
	v_pk_fma_f32 v[24:25], v[24:25], v[50:51], v[40:41] op_sel_hi:[1,0,1]
	v_pk_fma_f32 v[22:23], v[22:23], v[50:51], v[38:39] op_sel_hi:[1,0,1]
	v_pk_fma_f32 v[20:21], v[20:21], v[50:51], v[36:37] op_sel_hi:[1,0,1]
	v_pk_fma_f32 v[18:19], v[18:19], v[50:51], v[34:35] op_sel_hi:[1,0,1]
	v_pk_fma_f32 v[16:17], v[16:17], v[50:51], v[32:33] op_sel_hi:[1,0,1]
	s_mov_b64 s[12:13], -1
	s_cbranch_vccnz .LBB0_627
	s_and_b64 vcc, exec, s[8:9]
	v_mov_b32_e32 v53, v31
	v_mov_b32_e32 v52, v30
	v_mov_b32_e32 v51, v29
	v_mov_b32_e32 v50, v28
	v_mov_b32_e32 v57, v27
	v_mov_b32_e32 v56, v26
	v_mov_b32_e32 v55, v25
	v_mov_b32_e32 v54, v24
	v_mov_b32_e32 v61, v23
	v_mov_b32_e32 v60, v22
	v_mov_b32_e32 v59, v21
	v_mov_b32_e32 v58, v20
	s_waitcnt vmcnt(7)
	v_mov_b32_e32 v65, v19
	v_mov_b32_e32 v64, v18
	v_mov_b32_e32 v63, v17
	v_mov_b32_e32 v62, v16
	s_cbranch_vccnz .LBB0_626
	v_and_b32_e32 v51, 0x7fffffff, v29
	v_and_b32_e32 v50, 0x7fffffff, v28
	v_pk_fma_f32 v[50:51], v[50:51], s[68:69], 1.0 op_sel_hi:[1,0,0]
	v_mov_b64_e32 v[64:65], s[72:73]
	v_rcp_f32_e32 v50, v50
	v_rcp_f32_e32 v51, v51
	v_pk_mul_f32 v[54:55], v[28:29], v[28:29]
	v_and_b32_e32 v57, 0x7fffffff, v31
	v_pk_mul_f32 v[54:55], v[54:55], s[80:81] op_sel_hi:[1,0]
	v_pk_fma_f32 v[52:53], v[50:51], s[70:71], v[64:65] op_sel_hi:[1,0,0]
	v_exp_f32_e32 v54, v54
	v_pk_fma_f32 v[52:53], v[50:51], v[52:53], s[74:75] op_sel_hi:[1,1,0]
	v_exp_f32_e32 v55, v55
	v_pk_fma_f32 v[52:53], v[50:51], v[52:53], s[76:77] op_sel_hi:[1,1,0]
	v_and_b32_e32 v56, 0x7fffffff, v30
	v_pk_fma_f32 v[52:53], v[50:51], v[52:53], s[78:79] op_sel_hi:[1,1,0]
	v_pk_fma_f32 v[56:57], v[56:57], s[68:69], 1.0 op_sel_hi:[1,0,0]
	v_pk_mul_f32 v[50:51], v[50:51], v[52:53]
	v_rcp_f32_e32 v56, v56
	v_rcp_f32_e32 v57, v57
	v_pk_mul_f32 v[50:51], v[54:55], v[50:51]
	v_cmp_gt_f32_e32 vcc, 0, v28
	v_pk_mul_f32 v[54:55], v[28:29], v[50:51]
	v_pk_fma_f32 v[50:51], v[28:29], v[50:51], v[28:29] neg_lo:[1,0,0] neg_hi:[1,0,0]
	v_pk_mul_f32 v[52:53], v[30:31], v[30:31]
	v_cndmask_b32_e32 v50, v50, v54, vcc
	v_cmp_gt_f32_e32 vcc, 0, v29
	v_pk_mul_f32 v[52:53], v[52:53], s[80:81] op_sel_hi:[1,0]
	v_pk_mul_f32 v[58:59], v[24:25], v[24:25]
	v_cndmask_b32_e32 v51, v51, v55, vcc
	v_pk_fma_f32 v[54:55], v[56:57], s[70:71], v[64:65] op_sel_hi:[1,0,0]
	v_exp_f32_e32 v52, v52
	v_pk_fma_f32 v[54:55], v[56:57], v[54:55], s[74:75] op_sel_hi:[1,1,0]
	v_exp_f32_e32 v53, v53
	v_pk_fma_f32 v[54:55], v[56:57], v[54:55], s[76:77] op_sel_hi:[1,1,0]
	v_cmp_gt_f32_e32 vcc, 0, v30
	v_pk_fma_f32 v[54:55], v[56:57], v[54:55], s[78:79] op_sel_hi:[1,1,0]
	v_pk_mul_f32 v[58:59], v[58:59], s[80:81] op_sel_hi:[1,0]
	v_pk_mul_f32 v[54:55], v[56:57], v[54:55]
	v_and_b32_e32 v57, 0x7fffffff, v25
	v_and_b32_e32 v56, 0x7fffffff, v24
	v_pk_fma_f32 v[56:57], v[56:57], s[68:69], 1.0 op_sel_hi:[1,0,0]
	v_pk_mul_f32 v[52:53], v[52:53], v[54:55]
	v_rcp_f32_e32 v56, v56
	v_rcp_f32_e32 v57, v57
	v_pk_mul_f32 v[54:55], v[30:31], v[52:53]
	v_pk_fma_f32 v[52:53], v[30:31], v[52:53], v[30:31] neg_lo:[1,0,0] neg_hi:[1,0,0]
	v_exp_f32_e32 v58, v58
	v_cndmask_b32_e32 v52, v52, v54, vcc
	v_cmp_gt_f32_e32 vcc, 0, v31
	v_exp_f32_e32 v59, v59
	v_and_b32_e32 v61, 0x7fffffff, v27
	v_cndmask_b32_e32 v53, v53, v55, vcc
	v_pk_fma_f32 v[54:55], v[56:57], s[70:71], v[64:65] op_sel_hi:[1,0,0]
	v_and_b32_e32 v60, 0x7fffffff, v26
	v_pk_fma_f32 v[54:55], v[56:57], v[54:55], s[74:75] op_sel_hi:[1,1,0]
	v_pk_fma_f32 v[60:61], v[60:61], s[68:69], 1.0 op_sel_hi:[1,0,0]
	v_pk_fma_f32 v[54:55], v[56:57], v[54:55], s[76:77] op_sel_hi:[1,1,0]
	v_rcp_f32_e32 v60, v60
	v_pk_fma_f32 v[54:55], v[56:57], v[54:55], s[78:79] op_sel_hi:[1,1,0]
	v_rcp_f32_e32 v61, v61
	v_pk_mul_f32 v[54:55], v[56:57], v[54:55]
	v_cmp_gt_f32_e32 vcc, 0, v24
	v_pk_mul_f32 v[54:55], v[58:59], v[54:55]
	v_pk_mul_f32 v[56:57], v[26:27], v[26:27]
	v_pk_mul_f32 v[58:59], v[24:25], v[54:55]
	v_pk_fma_f32 v[54:55], v[24:25], v[54:55], v[24:25] neg_lo:[1,0,0] neg_hi:[1,0,0]
	v_pk_mul_f32 v[56:57], v[56:57], s[80:81] op_sel_hi:[1,0]
	v_cndmask_b32_e32 v54, v54, v58, vcc
	v_cmp_gt_f32_e32 vcc, 0, v25
	v_exp_f32_e32 v56, v56
	v_exp_f32_e32 v57, v57
	v_cndmask_b32_e32 v55, v55, v59, vcc
	v_pk_fma_f32 v[58:59], v[60:61], s[70:71], v[64:65] op_sel_hi:[1,0,0]
	v_cmp_gt_f32_e32 vcc, 0, v26
	v_pk_fma_f32 v[58:59], v[60:61], v[58:59], s[74:75] op_sel_hi:[1,1,0]
	v_pk_mul_f32 v[62:63], v[20:21], v[20:21]
	v_pk_fma_f32 v[58:59], v[60:61], v[58:59], s[76:77] op_sel_hi:[1,1,0]
	v_pk_mul_f32 v[62:63], v[62:63], s[80:81] op_sel_hi:[1,0]
	v_pk_fma_f32 v[58:59], v[60:61], v[58:59], s[78:79] op_sel_hi:[1,1,0]
	v_exp_f32_e32 v62, v62
	v_pk_mul_f32 v[58:59], v[60:61], v[58:59]
	v_and_b32_e32 v61, 0x7fffffff, v21
	v_and_b32_e32 v60, 0x7fffffff, v20
	v_pk_fma_f32 v[60:61], v[60:61], s[68:69], 1.0 op_sel_hi:[1,0,0]
	v_pk_mul_f32 v[56:57], v[56:57], v[58:59]
	v_rcp_f32_e32 v60, v60
	v_rcp_f32_e32 v61, v61
	v_pk_mul_f32 v[58:59], v[26:27], v[56:57]
	v_pk_fma_f32 v[56:57], v[26:27], v[56:57], v[26:27] neg_lo:[1,0,0] neg_hi:[1,0,0]
	v_exp_f32_e32 v63, v63
	v_cndmask_b32_e32 v56, v56, v58, vcc
	v_cmp_gt_f32_e32 vcc, 0, v27
	v_and_b32_e32 v67, 0x7fffffff, v23
	v_and_b32_e32 v66, 0x7fffffff, v22
	v_cndmask_b32_e32 v57, v57, v59, vcc
	v_pk_fma_f32 v[58:59], v[60:61], s[70:71], v[64:65] op_sel_hi:[1,0,0]
	v_pk_fma_f32 v[66:67], v[66:67], s[68:69], 1.0 op_sel_hi:[1,0,0]
	v_pk_fma_f32 v[58:59], v[60:61], v[58:59], s[74:75] op_sel_hi:[1,1,0]
	v_rcp_f32_e32 v66, v66
	v_pk_fma_f32 v[58:59], v[60:61], v[58:59], s[76:77] op_sel_hi:[1,1,0]
	v_rcp_f32_e32 v67, v67
	v_pk_fma_f32 v[58:59], v[60:61], v[58:59], s[78:79] op_sel_hi:[1,1,0]
	v_cmp_gt_f32_e32 vcc, 0, v20
	v_pk_mul_f32 v[58:59], v[60:61], v[58:59]
	v_pk_mul_f32 v[60:61], v[22:23], v[22:23]
	v_pk_mul_f32 v[58:59], v[62:63], v[58:59]
	v_pk_mul_f32 v[60:61], v[60:61], s[80:81] op_sel_hi:[1,0]
	v_pk_mul_f32 v[62:63], v[20:21], v[58:59]
	v_pk_fma_f32 v[58:59], v[20:21], v[58:59], v[20:21] neg_lo:[1,0,0] neg_hi:[1,0,0]
	v_exp_f32_e32 v60, v60
	v_cndmask_b32_e32 v58, v58, v62, vcc
	v_cmp_gt_f32_e32 vcc, 0, v21
	v_exp_f32_e32 v61, v61
	v_and_b32_e32 v71, 0x7fffffff, v19
	v_cndmask_b32_e32 v59, v59, v63, vcc
	v_pk_fma_f32 v[62:63], v[66:67], s[70:71], v[64:65] op_sel_hi:[1,0,0]
	v_cmp_gt_f32_e32 vcc, 0, v22
	v_pk_fma_f32 v[62:63], v[66:67], v[62:63], s[74:75] op_sel_hi:[1,1,0]
	v_and_b32_e32 v70, 0x7fffffff, v18
	v_pk_fma_f32 v[62:63], v[66:67], v[62:63], s[76:77] op_sel_hi:[1,1,0]
	v_pk_fma_f32 v[70:71], v[70:71], s[68:69], 1.0 op_sel_hi:[1,0,0]
	v_pk_fma_f32 v[62:63], v[66:67], v[62:63], s[78:79] op_sel_hi:[1,1,0]
	v_rcp_f32_e32 v70, v70
	v_pk_mul_f32 v[62:63], v[66:67], v[62:63]
	v_and_b32_e32 v67, 0x7fffffff, v17
	v_and_b32_e32 v66, 0x7fffffff, v16
	v_pk_fma_f32 v[66:67], v[66:67], s[68:69], 1.0 op_sel_hi:[1,0,0]
	v_pk_mul_f32 v[60:61], v[60:61], v[62:63]
	v_rcp_f32_e32 v66, v66
	v_rcp_f32_e32 v67, v67
	v_pk_mul_f32 v[62:63], v[22:23], v[60:61]
	v_pk_fma_f32 v[60:61], v[22:23], v[60:61], v[22:23] neg_lo:[1,0,0] neg_hi:[1,0,0]
	v_rcp_f32_e32 v71, v71
	v_cndmask_b32_e32 v60, v60, v62, vcc
	v_cmp_gt_f32_e32 vcc, 0, v23
	v_pk_mul_f32 v[68:69], v[16:17], v[16:17]
	s_nop 0
	v_cndmask_b32_e32 v61, v61, v63, vcc
	v_pk_fma_f32 v[62:63], v[66:67], s[70:71], v[64:65] op_sel_hi:[1,0,0]
	v_pk_mul_f32 v[68:69], v[68:69], s[80:81] op_sel_hi:[1,0]
	v_pk_fma_f32 v[62:63], v[66:67], v[62:63], s[74:75] op_sel_hi:[1,1,0]
	v_exp_f32_e32 v68, v68
	v_pk_fma_f32 v[62:63], v[66:67], v[62:63], s[76:77] op_sel_hi:[1,1,0]
	v_exp_f32_e32 v69, v69
	v_pk_fma_f32 v[62:63], v[66:67], v[62:63], s[78:79] op_sel_hi:[1,1,0]
	v_pk_fma_f32 v[64:65], v[70:71], s[70:71], v[64:65] op_sel_hi:[1,0,0]
	v_pk_mul_f32 v[62:63], v[66:67], v[62:63]
	v_pk_mul_f32 v[66:67], v[18:19], v[18:19]
	v_pk_fma_f32 v[64:65], v[70:71], v[64:65], s[74:75] op_sel_hi:[1,1,0]
	v_pk_mul_f32 v[66:67], v[66:67], s[80:81] op_sel_hi:[1,0]
	v_pk_fma_f32 v[64:65], v[70:71], v[64:65], s[76:77] op_sel_hi:[1,1,0]
	v_exp_f32_e32 v66, v66
	v_exp_f32_e32 v67, v67
	v_pk_mul_f32 v[62:63], v[68:69], v[62:63]
	v_pk_fma_f32 v[64:65], v[70:71], v[64:65], s[78:79] op_sel_hi:[1,1,0]
	v_pk_mul_f32 v[68:69], v[16:17], v[62:63]
	v_pk_fma_f32 v[62:63], v[16:17], v[62:63], v[16:17] neg_lo:[1,0,0] neg_hi:[1,0,0]
	v_cmp_gt_f32_e32 vcc, 0, v16
	v_pk_mul_f32 v[64:65], v[70:71], v[64:65]
	s_nop 0
	v_cndmask_b32_e32 v62, v62, v68, vcc
	v_cmp_gt_f32_e32 vcc, 0, v17
	v_pk_mul_f32 v[64:65], v[66:67], v[64:65]
	v_mul_f32_e32 v68, v51, v51
	v_cndmask_b32_e32 v63, v63, v69, vcc
	v_pk_mul_f32 v[66:67], v[18:19], v[64:65]
	v_pk_fma_f32 v[64:65], v[18:19], v[64:65], v[18:19] neg_lo:[1,0,0] neg_hi:[1,0,0]
	v_cmp_gt_f32_e32 vcc, 0, v18
	v_fmac_f32_e32 v68, v50, v50
	v_fmac_f32_e32 v68, v52, v52
	v_cndmask_b32_e32 v64, v64, v66, vcc
	v_add_f32_e32 v66, 0, v50
	v_add_f32_e32 v66, v51, v66
	v_add_f32_e32 v66, v52, v66
	v_add_f32_e32 v66, v53, v66
	v_add_f32_e32 v66, v54, v66
	v_add_f32_e32 v66, v55, v66
	v_fmac_f32_e32 v68, v53, v53
	v_add_f32_e32 v66, v56, v66
	v_fmac_f32_e32 v68, v54, v54
	v_add_f32_e32 v66, v57, v66
	v_fmac_f32_e32 v68, v55, v55
	v_add_f32_e32 v66, v58, v66
	v_fmac_f32_e32 v68, v56, v56
	v_add_f32_e32 v66, v59, v66
	v_fmac_f32_e32 v68, v57, v57
	v_add_f32_e32 v66, v60, v66
	v_cmp_gt_f32_e32 vcc, 0, v19
	v_fmac_f32_e32 v68, v58, v58
	v_add_f32_e32 v66, v61, v66
	v_cndmask_b32_e32 v65, v65, v67, vcc
	v_fmac_f32_e32 v68, v59, v59
	v_add_f32_e32 v66, v62, v66
	v_fmac_f32_e32 v68, v60, v60
	v_add_f32_e32 v66, v63, v66
	v_fmac_f32_e32 v68, v61, v61
	v_add_f32_e32 v66, v64, v66
	v_add_f32_e32 v66, v65, v66
	v_fmac_f32_e32 v68, v62, v62
	v_mov_b32_e32 v70, v66
	s_nop 1
	v_permlane16_swap_b32_e32 v66, v70
	s_nop 1
	v_fmac_f32_e32 v68, v63, v63
	v_fmac_f32_e32 v68, v64, v64
	v_fmac_f32_e32 v68, v65, v65
	v_mov_b32_e32 v71, v68
	s_nop 1
	v_permlane16_swap_b32_e32 v68, v71
	s_nop 1
	s_waitcnt lgkmcnt(1)
	v_add_f32_e32 v66, v66, v70
	v_xor_b32_e32 v70, 32, v229
	s_waitcnt lgkmcnt(0)
	v_add_f32_e32 v68, v68, v71
	v_mov_b32_e32 v67, v66
	s_nop 1
	v_permlane32_swap_b32_e32 v66, v67
	s_nop 1
	v_mov_b32_e32 v69, v68
	s_nop 1
	v_permlane32_swap_b32_e32 v68, v69
	s_nop 1
	s_and_saveexec_b64 s[12:13], s[4:5]
	s_cbranch_execz .LBB0_625
	v_lshlrev_b64 v[70:71], 2, v[48:49]
	v_lshl_add_u64 v[72:73], s[14:15], 0, v[70:71]
	v_lshl_add_u64 v[70:71], s[52:53], 0, v[70:71]
	s_waitcnt lgkmcnt(1)
	v_add_f32_e32 v66, v66, v67
	s_waitcnt lgkmcnt(0)
	v_add_f32_e32 v67, v68, v69
	global_atomic_add_f32 v[70:71], v66, off
	global_atomic_add_f32 v[72:73], v67, off

.LBB0_629:
	v_lshlrev_b64 v[18:19], 11, v[48:49]
	v_lshl_add_u64 v[22:23], v[202:203], 0, v[18:19]
	v_cvt_pk_bf16_f32 v18, v50, v51
	v_cvt_pk_bf16_f32 v19, v52, v53
	v_cvt_pk_bf16_f32 v20, v54, v55
	v_cvt_pk_bf16_f32 v21, v56, v57
	global_store_dwordx4 v[22:23], v[18:21], off
	v_add_u32_e32 v16, 0xb0, v198
	v_ashrrev_i32_e32 v17, 31, v16
	v_fmamk_f32 v20, v233, 0x3a800000, v228
	v_rsq_f32_e32 v24, v20
	v_cvt_pk_bf16_f32 v18, v58, v59
	v_cvt_pk_bf16_f32 v19, v60, v61
	v_cvt_pk_bf16_f32 v20, v62, v63
	s_waitcnt vmcnt(8)
	v_cvt_pk_bf16_f32 v21, v64, v65
	s_and_b64 vcc, exec, s[10:11]
	v_pk_fma_f32 v[14:15], v[14:15], v[24:25], v[46:47] op_sel_hi:[1,0,1]
	v_pk_fma_f32 v[12:13], v[12:13], v[24:25], v[44:45] op_sel_hi:[1,0,1]
	v_pk_fma_f32 v[10:11], v[10:11], v[24:25], v[42:43] op_sel_hi:[1,0,1]
	v_pk_fma_f32 v[8:9], v[8:9], v[24:25], v[40:41] op_sel_hi:[1,0,1]
	v_pk_fma_f32 v[6:7], v[6:7], v[24:25], v[38:39] op_sel_hi:[1,0,1]
	v_pk_fma_f32 v[4:5], v[4:5], v[24:25], v[36:37] op_sel_hi:[1,0,1]
	v_pk_fma_f32 v[2:3], v[2:3], v[24:25], v[34:35] op_sel_hi:[1,0,1]
	v_pk_fma_f32 v[0:1], v[0:1], v[24:25], v[32:33] op_sel_hi:[1,0,1]
	s_mov_b64 s[10:11], -1
	global_store_dwordx4 v[22:23], v[18:21], off offset:256
	s_cbranch_vccnz .LBB0_635
	s_and_b64 vcc, exec, s[8:9]
	v_mov_b32_e32 v21, v15
	v_mov_b32_e32 v20, v14
	v_mov_b32_e32 v19, v13
	v_mov_b32_e32 v18, v12
	v_mov_b32_e32 v25, v11
	v_mov_b32_e32 v24, v10
	v_mov_b32_e32 v23, v9
	v_mov_b32_e32 v22, v8
	v_mov_b32_e32 v29, v7
	v_mov_b32_e32 v28, v6
	v_mov_b32_e32 v27, v5
	v_mov_b32_e32 v26, v4
	v_mov_b32_e32 v33, v3
	v_mov_b32_e32 v32, v2
	v_mov_b32_e32 v31, v1
	v_mov_b32_e32 v30, v0
	s_cbranch_vccnz .LBB0_634
	v_and_b32_e32 v19, 0x7fffffff, v13
	v_and_b32_e32 v18, 0x7fffffff, v12
	v_pk_fma_f32 v[18:19], v[18:19], s[68:69], 1.0 op_sel_hi:[1,0,0]
	v_mov_b64_e32 v[32:33], s[72:73]
	v_rcp_f32_e32 v18, v18
	v_rcp_f32_e32 v19, v19
	v_pk_mul_f32 v[22:23], v[12:13], v[12:13]
	v_and_b32_e32 v25, 0x7fffffff, v15
	v_pk_mul_f32 v[22:23], v[22:23], s[80:81] op_sel_hi:[1,0]
	v_pk_fma_f32 v[20:21], v[18:19], s[70:71], v[32:33] op_sel_hi:[1,0,0]
	v_exp_f32_e32 v22, v22
	v_pk_fma_f32 v[20:21], v[18:19], v[20:21], s[74:75] op_sel_hi:[1,1,0]
	v_exp_f32_e32 v23, v23
	v_pk_fma_f32 v[20:21], v[18:19], v[20:21], s[76:77] op_sel_hi:[1,1,0]
	v_and_b32_e32 v24, 0x7fffffff, v14
	v_pk_fma_f32 v[20:21], v[18:19], v[20:21], s[78:79] op_sel_hi:[1,1,0]
	v_pk_fma_f32 v[24:25], v[24:25], s[68:69], 1.0 op_sel_hi:[1,0,0]
	v_pk_mul_f32 v[18:19], v[18:19], v[20:21]
	v_rcp_f32_e32 v24, v24
	v_rcp_f32_e32 v25, v25
	v_pk_mul_f32 v[18:19], v[22:23], v[18:19]
	v_cmp_gt_f32_e32 vcc, 0, v12
	v_pk_mul_f32 v[22:23], v[12:13], v[18:19]
	v_pk_fma_f32 v[18:19], v[12:13], v[18:19], v[12:13] neg_lo:[1,0,0] neg_hi:[1,0,0]
	v_pk_mul_f32 v[20:21], v[14:15], v[14:15]
	v_cndmask_b32_e32 v18, v18, v22, vcc
	v_cmp_gt_f32_e32 vcc, 0, v13
	v_pk_mul_f32 v[20:21], v[20:21], s[80:81] op_sel_hi:[1,0]
	v_pk_mul_f32 v[26:27], v[8:9], v[8:9]
	v_cndmask_b32_e32 v19, v19, v23, vcc
	v_pk_fma_f32 v[22:23], v[24:25], s[70:71], v[32:33] op_sel_hi:[1,0,0]
	v_exp_f32_e32 v20, v20
	v_pk_fma_f32 v[22:23], v[24:25], v[22:23], s[74:75] op_sel_hi:[1,1,0]
	v_exp_f32_e32 v21, v21
	v_pk_fma_f32 v[22:23], v[24:25], v[22:23], s[76:77] op_sel_hi:[1,1,0]
	v_cmp_gt_f32_e32 vcc, 0, v14
	v_pk_fma_f32 v[22:23], v[24:25], v[22:23], s[78:79] op_sel_hi:[1,1,0]
	v_pk_mul_f32 v[26:27], v[26:27], s[80:81] op_sel_hi:[1,0]
	v_pk_mul_f32 v[22:23], v[24:25], v[22:23]
	v_and_b32_e32 v25, 0x7fffffff, v9
	v_and_b32_e32 v24, 0x7fffffff, v8
	v_pk_fma_f32 v[24:25], v[24:25], s[68:69], 1.0 op_sel_hi:[1,0,0]
	v_pk_mul_f32 v[20:21], v[20:21], v[22:23]
	v_rcp_f32_e32 v24, v24
	v_rcp_f32_e32 v25, v25
	v_pk_mul_f32 v[22:23], v[14:15], v[20:21]
	v_pk_fma_f32 v[20:21], v[14:15], v[20:21], v[14:15] neg_lo:[1,0,0] neg_hi:[1,0,0]
	v_exp_f32_e32 v26, v26
	v_cndmask_b32_e32 v20, v20, v22, vcc
	v_cmp_gt_f32_e32 vcc, 0, v15
	v_exp_f32_e32 v27, v27
	v_and_b32_e32 v29, 0x7fffffff, v11
	v_cndmask_b32_e32 v21, v21, v23, vcc
	v_pk_fma_f32 v[22:23], v[24:25], s[70:71], v[32:33] op_sel_hi:[1,0,0]
	v_and_b32_e32 v28, 0x7fffffff, v10
	v_pk_fma_f32 v[22:23], v[24:25], v[22:23], s[74:75] op_sel_hi:[1,1,0]
	v_pk_fma_f32 v[28:29], v[28:29], s[68:69], 1.0 op_sel_hi:[1,0,0]
	v_pk_fma_f32 v[22:23], v[24:25], v[22:23], s[76:77] op_sel_hi:[1,1,0]
	v_rcp_f32_e32 v28, v28
	v_pk_fma_f32 v[22:23], v[24:25], v[22:23], s[78:79] op_sel_hi:[1,1,0]
	v_rcp_f32_e32 v29, v29
	v_pk_mul_f32 v[22:23], v[24:25], v[22:23]
	v_cmp_gt_f32_e32 vcc, 0, v8
	v_pk_mul_f32 v[22:23], v[26:27], v[22:23]
	v_pk_mul_f32 v[24:25], v[10:11], v[10:11]
	v_pk_mul_f32 v[26:27], v[8:9], v[22:23]
	v_pk_fma_f32 v[22:23], v[8:9], v[22:23], v[8:9] neg_lo:[1,0,0] neg_hi:[1,0,0]
	v_pk_mul_f32 v[24:25], v[24:25], s[80:81] op_sel_hi:[1,0]
	v_cndmask_b32_e32 v22, v22, v26, vcc
	v_cmp_gt_f32_e32 vcc, 0, v9
	v_exp_f32_e32 v24, v24
	v_exp_f32_e32 v25, v25
	v_cndmask_b32_e32 v23, v23, v27, vcc
	v_pk_fma_f32 v[26:27], v[28:29], s[70:71], v[32:33] op_sel_hi:[1,0,0]
	v_cmp_gt_f32_e32 vcc, 0, v10
	v_pk_fma_f32 v[26:27], v[28:29], v[26:27], s[74:75] op_sel_hi:[1,1,0]
	v_pk_mul_f32 v[30:31], v[4:5], v[4:5]
	v_pk_fma_f32 v[26:27], v[28:29], v[26:27], s[76:77] op_sel_hi:[1,1,0]
	v_pk_mul_f32 v[30:31], v[30:31], s[80:81] op_sel_hi:[1,0]
	v_pk_fma_f32 v[26:27], v[28:29], v[26:27], s[78:79] op_sel_hi:[1,1,0]
	v_exp_f32_e32 v30, v30
	v_pk_mul_f32 v[26:27], v[28:29], v[26:27]
	v_and_b32_e32 v29, 0x7fffffff, v5
	v_and_b32_e32 v28, 0x7fffffff, v4
	v_pk_fma_f32 v[28:29], v[28:29], s[68:69], 1.0 op_sel_hi:[1,0,0]
	v_pk_mul_f32 v[24:25], v[24:25], v[26:27]
	v_rcp_f32_e32 v28, v28
	v_rcp_f32_e32 v29, v29
	v_pk_mul_f32 v[26:27], v[10:11], v[24:25]
	v_pk_fma_f32 v[24:25], v[10:11], v[24:25], v[10:11] neg_lo:[1,0,0] neg_hi:[1,0,0]
	v_exp_f32_e32 v31, v31
	v_cndmask_b32_e32 v24, v24, v26, vcc
	v_cmp_gt_f32_e32 vcc, 0, v11
	v_and_b32_e32 v35, 0x7fffffff, v7
	v_and_b32_e32 v34, 0x7fffffff, v6
	v_cndmask_b32_e32 v25, v25, v27, vcc
	v_pk_fma_f32 v[26:27], v[28:29], s[70:71], v[32:33] op_sel_hi:[1,0,0]
	v_pk_fma_f32 v[34:35], v[34:35], s[68:69], 1.0 op_sel_hi:[1,0,0]
	v_pk_fma_f32 v[26:27], v[28:29], v[26:27], s[74:75] op_sel_hi:[1,1,0]
	v_rcp_f32_e32 v34, v34
	v_pk_fma_f32 v[26:27], v[28:29], v[26:27], s[76:77] op_sel_hi:[1,1,0]
	v_rcp_f32_e32 v35, v35
	v_pk_fma_f32 v[26:27], v[28:29], v[26:27], s[78:79] op_sel_hi:[1,1,0]
	v_cmp_gt_f32_e32 vcc, 0, v4
	v_pk_mul_f32 v[26:27], v[28:29], v[26:27]
	v_pk_mul_f32 v[28:29], v[6:7], v[6:7]
	v_pk_mul_f32 v[26:27], v[30:31], v[26:27]
	v_pk_mul_f32 v[28:29], v[28:29], s[80:81] op_sel_hi:[1,0]
	v_pk_mul_f32 v[30:31], v[4:5], v[26:27]
	v_pk_fma_f32 v[26:27], v[4:5], v[26:27], v[4:5] neg_lo:[1,0,0] neg_hi:[1,0,0]
	v_exp_f32_e32 v28, v28
	v_cndmask_b32_e32 v26, v26, v30, vcc
	v_cmp_gt_f32_e32 vcc, 0, v5
	v_exp_f32_e32 v29, v29
	v_and_b32_e32 v39, 0x7fffffff, v3
	v_cndmask_b32_e32 v27, v27, v31, vcc
	v_pk_fma_f32 v[30:31], v[34:35], s[70:71], v[32:33] op_sel_hi:[1,0,0]
	v_cmp_gt_f32_e32 vcc, 0, v6
	v_pk_fma_f32 v[30:31], v[34:35], v[30:31], s[74:75] op_sel_hi:[1,1,0]
	v_and_b32_e32 v38, 0x7fffffff, v2
	v_pk_fma_f32 v[30:31], v[34:35], v[30:31], s[76:77] op_sel_hi:[1,1,0]
	v_pk_fma_f32 v[38:39], v[38:39], s[68:69], 1.0 op_sel_hi:[1,0,0]
	v_pk_fma_f32 v[30:31], v[34:35], v[30:31], s[78:79] op_sel_hi:[1,1,0]
	v_rcp_f32_e32 v38, v38
	v_pk_mul_f32 v[30:31], v[34:35], v[30:31]
	v_and_b32_e32 v35, 0x7fffffff, v1
	v_and_b32_e32 v34, 0x7fffffff, v0
	v_pk_fma_f32 v[34:35], v[34:35], s[68:69], 1.0 op_sel_hi:[1,0,0]
	v_pk_mul_f32 v[28:29], v[28:29], v[30:31]
	v_rcp_f32_e32 v34, v34
	v_rcp_f32_e32 v35, v35
	v_pk_mul_f32 v[30:31], v[6:7], v[28:29]
	v_pk_fma_f32 v[28:29], v[6:7], v[28:29], v[6:7] neg_lo:[1,0,0] neg_hi:[1,0,0]
	v_rcp_f32_e32 v39, v39
	v_cndmask_b32_e32 v28, v28, v30, vcc
	v_cmp_gt_f32_e32 vcc, 0, v7
	v_pk_mul_f32 v[36:37], v[0:1], v[0:1]
	s_nop 0
	v_cndmask_b32_e32 v29, v29, v31, vcc
	v_pk_fma_f32 v[30:31], v[34:35], s[70:71], v[32:33] op_sel_hi:[1,0,0]
	v_pk_mul_f32 v[36:37], v[36:37], s[80:81] op_sel_hi:[1,0]
	v_pk_fma_f32 v[30:31], v[34:35], v[30:31], s[74:75] op_sel_hi:[1,1,0]
	v_exp_f32_e32 v36, v36
	v_pk_fma_f32 v[30:31], v[34:35], v[30:31], s[76:77] op_sel_hi:[1,1,0]
	v_exp_f32_e32 v37, v37
	v_pk_fma_f32 v[30:31], v[34:35], v[30:31], s[78:79] op_sel_hi:[1,1,0]
	v_pk_fma_f32 v[32:33], v[38:39], s[70:71], v[32:33] op_sel_hi:[1,0,0]
	v_pk_mul_f32 v[30:31], v[34:35], v[30:31]
	v_pk_mul_f32 v[34:35], v[2:3], v[2:3]
	v_pk_fma_f32 v[32:33], v[38:39], v[32:33], s[74:75] op_sel_hi:[1,1,0]
	v_pk_mul_f32 v[34:35], v[34:35], s[80:81] op_sel_hi:[1,0]
	v_pk_fma_f32 v[32:33], v[38:39], v[32:33], s[76:77] op_sel_hi:[1,1,0]
	v_exp_f32_e32 v34, v34
	v_exp_f32_e32 v35, v35
	v_pk_mul_f32 v[30:31], v[36:37], v[30:31]
	v_pk_fma_f32 v[32:33], v[38:39], v[32:33], s[78:79] op_sel_hi:[1,1,0]
	v_pk_mul_f32 v[36:37], v[0:1], v[30:31]
	v_pk_fma_f32 v[30:31], v[0:1], v[30:31], v[0:1] neg_lo:[1,0,0] neg_hi:[1,0,0]
	v_cmp_gt_f32_e32 vcc, 0, v0
	v_pk_mul_f32 v[32:33], v[38:39], v[32:33]
	s_nop 0
	v_cndmask_b32_e32 v30, v30, v36, vcc
	v_cmp_gt_f32_e32 vcc, 0, v1
	v_pk_mul_f32 v[32:33], v[34:35], v[32:33]
	v_mul_f32_e32 v36, v19, v19
	v_cndmask_b32_e32 v31, v31, v37, vcc
	v_pk_mul_f32 v[34:35], v[2:3], v[32:33]
	v_pk_fma_f32 v[32:33], v[2:3], v[32:33], v[2:3] neg_lo:[1,0,0] neg_hi:[1,0,0]
	v_cmp_gt_f32_e32 vcc, 0, v2
	v_fmac_f32_e32 v36, v18, v18
	v_fmac_f32_e32 v36, v20, v20
	v_cndmask_b32_e32 v32, v32, v34, vcc
	v_add_f32_e32 v34, 0, v18
	v_add_f32_e32 v34, v19, v34
	v_add_f32_e32 v34, v20, v34
	v_add_f32_e32 v34, v21, v34
	v_add_f32_e32 v34, v22, v34
	v_add_f32_e32 v34, v23, v34
	v_fmac_f32_e32 v36, v21, v21
	v_add_f32_e32 v34, v24, v34
	v_fmac_f32_e32 v36, v22, v22
	v_add_f32_e32 v34, v25, v34
	v_fmac_f32_e32 v36, v23, v23
	v_add_f32_e32 v34, v26, v34
	v_fmac_f32_e32 v36, v24, v24
	v_add_f32_e32 v34, v27, v34
	v_fmac_f32_e32 v36, v25, v25
	v_add_f32_e32 v34, v28, v34
	v_cmp_gt_f32_e32 vcc, 0, v3
	v_fmac_f32_e32 v36, v26, v26
	v_add_f32_e32 v34, v29, v34
	v_cndmask_b32_e32 v33, v33, v35, vcc
	v_fmac_f32_e32 v36, v27, v27
	v_add_f32_e32 v34, v30, v34
	v_fmac_f32_e32 v36, v28, v28
	v_add_f32_e32 v34, v31, v34
	v_fmac_f32_e32 v36, v29, v29
	v_add_f32_e32 v34, v32, v34
	v_add_f32_e32 v34, v33, v34
	v_fmac_f32_e32 v36, v30, v30
	v_mov_b32_e32 v38, v34
	s_nop 1
	v_permlane16_swap_b32_e32 v34, v38
	s_nop 1
	v_fmac_f32_e32 v36, v31, v31
	v_fmac_f32_e32 v36, v32, v32
	v_fmac_f32_e32 v36, v33, v33
	v_mov_b32_e32 v39, v36
	s_nop 1
	v_permlane16_swap_b32_e32 v36, v39
	s_nop 1
	s_waitcnt lgkmcnt(1)
	v_add_f32_e32 v34, v34, v38
	v_xor_b32_e32 v38, 32, v229
	s_waitcnt lgkmcnt(0)
	v_add_f32_e32 v36, v36, v39
	v_mov_b32_e32 v35, v34
	s_nop 1
	v_permlane32_swap_b32_e32 v34, v35
	s_nop 1
	v_mov_b32_e32 v37, v36
	s_nop 1
	v_permlane32_swap_b32_e32 v36, v37
	s_nop 1
	s_and_saveexec_b64 s[8:9], s[4:5]
	s_cbranch_execz .LBB0_633
	v_lshlrev_b64 v[38:39], 2, v[16:17]
	v_lshl_add_u64 v[40:41], s[14:15], 0, v[38:39]
	v_lshl_add_u64 v[38:39], s[52:53], 0, v[38:39]
	s_waitcnt lgkmcnt(1)
	v_add_f32_e32 v34, v34, v35
	s_waitcnt lgkmcnt(0)
	v_add_f32_e32 v35, v36, v37
	global_atomic_add_f32 v[38:39], v34, off
	global_atomic_add_f32 v[40:41], v35, off

.LBB0_1419:
	v_and_b32_e32 v129, 64, v182
	v_xor_b32_e32 v128, 16, v182
	v_add_u32_e32 v129, 64, v129
	v_cmp_lt_i32_e32 vcc, v128, v129
	v_mul_f32_e32 v131, v31, v31
	v_fmac_f32_e32 v131, v30, v30
	v_cndmask_b32_e32 v128, v182, v128, vcc
	v_lshlrev_b32_e32 v130, 2, v128
	v_mul_f32_e32 v128, v29, v29
	v_fmac_f32_e32 v128, v28, v28
	v_add_f32_e32 v128, v128, v131
	v_mul_f32_e32 v131, v37, v37
	v_fmac_f32_e32 v131, v36, v36
	v_add_f32_e32 v128, v128, v131
	v_mul_f32_e32 v131, v39, v39
	v_fmac_f32_e32 v131, v38, v38
	v_add_f32_e32 v128, v131, v128
	v_mul_f32_e32 v131, v105, v105
	v_mul_f32_e32 v132, v107, v107
	v_fmac_f32_e32 v131, v104, v104
	v_fmac_f32_e32 v132, v106, v106
	v_add_f32_e32 v131, v131, v132
	v_mul_f32_e32 v132, v109, v109
	v_fmac_f32_e32 v132, v108, v108
	v_add_f32_e32 v131, v131, v132
	v_mul_f32_e32 v132, v111, v111
	v_fmac_f32_e32 v132, v110, v110
	v_add_f32_e32 v131, v132, v131
	v_add_f32_e32 v128, v128, v131
	v_mul_f32_e32 v131, 0x3e800000, v128
	ds_bpermute_b32 v132, v130, v131
	v_lshl_add_u32 v160, s78, 8, v178
	v_ashrrev_i32_e32 v161, 31, v160
	s_waitcnt lgkmcnt(0)
	v_fmac_f32_e32 v132, 0x3e800000, v128
	v_mov_b32_e32 v133, v132
	s_nop 1
	v_permlane32_swap_b32_e32 v132, v133
	s_nop 1
	v_lshl_add_u64 v[128:129], v[160:161], 2, s[34:35]
	s_and_saveexec_b64 s[48:49], s[0:1]
	s_cbranch_execz .LBB0_1421
	s_waitcnt lgkmcnt(0)
	v_add_f32_e32 v132, v132, v133
	global_atomic_add_f32 v[128:129], v132, off
